# k20 plus: the 36 redundant adjacent s_setprio 0 / s_setprio 1 pairs between the two MMA halves of each GEMM phase removed (priority stays 1 across the 32-MFMA block)
# speedup vs baseline: 1.0039x; 1.0009x over previous
; #define PG8_STAGE(bufoff, gbase, voff) do { _Pragma("unroll") for (int _i = 0; _i < 2; ++_i) \
;         __builtin_amdgcn_global_load_lds((const unsigned*)((const char*)(gbase) + (voff)[_i]), (LAS unsigned*)(lds + (bufoff) + ldsw + _i * 8192), 16, 0, 0); } while (0)
; #define PG8_LDA(dst, b, h) do { _Pragma("unroll") for (int m = 0; m < 4; ++m) _Pragma("unroll") for (int k = 0; k < 2; ++k) dst[m][k] = *(const LAS bf16x8*)(lds + PG8_SA(b, h) + aoff + m * 2048 + k * 1024); } while (0)
; #define PG8_LDB(dst, b, h) do { _Pragma("unroll") for (int n = 0; n < 2; ++n) _Pragma("unroll") for (int k = 0; k < 2; ++k) dst[n][k] = *(const LAS bf16x8*)(lds + PG8_SB(b, h) + boff + n * 2048 + k * 1024); } while (0)
; #define PG8_MMA(ai, bj, At, Bt) do { __builtin_amdgcn_s_setprio(1); _Pragma("unroll") for (int m = 0; m < 4; ++m) _Pragma("unroll") for (int n = 0; n < 2; ++n) _Pragma("unroll") for (int k = 0; k < 2; ++k) \
;         acc[ai][bj][m][n] = __builtin_amdgcn_mfma_f32_16x16x32_bf16(Bt[n][k], At[m][k], acc[ai][bj][m][n], 0, 0, 0); __builtin_amdgcn_s_setprio(0); } while (0)
; #define PG8_WAIT_V(n) asm volatile("s_waitcnt vmcnt(" #n ")" ::: "memory")
; #define PG8_WAIT_L(n) asm volatile("s_waitcnt lgkmcnt(" #n ")" ::: "memory")
; #define PG8_BAR __builtin_amdgcn_s_barrier()
; #define PG8_SCHED __builtin_amdgcn_sched_barrier(0)
; template <class Epi, class Sched, bool ALIGN_EPI = true, bool SP2 = true>
; __device__ __forceinline__ void gemm_phase(LAS unsigned char* lds, const Gemm g, const Sched& S, const Epi& E) {
;     ...
;             PG8_LDB(B0, 0, 0); PG8_LDB(B1, 0, 1); PG8_SCHED; PG8_LDA(At, 0, 0); PG8_STAGE(PG8_SA(1, 1), a1 + hstepA, voffA);
;             PG8_WAIT_V(8); PG8_WAIT_L(0); PG8_BAR; PG8_MMA(0, 0, At, B0); PG8_MMA(0, 1, At, B1); PG8_BAR; PG8_SCHED;
;             PG8_LDA(At, 0, 1); PG8_STAGE(PG8_SB(0, 0), b2, voffB); PG8_STAGE(PG8_SB(0, 1), b2 + hstepB, voffB); PG8_STAGE(PG8_SA(0, 0), a2, voffA);
;             PG8_WAIT_V(8); PG8_WAIT_L(0); PG8_BAR; PG8_MMA(1, 0, At, B0); PG8_MMA(1, 1, At, B1); PG8_BAR; PG8_SCHED;
.LBB0_205:
	s_add_u32 s35, s36, 0xfffc0080
	s_addc_u32 s42, s37, -1
	s_add_i32 s58, 0, 0x10000
	s_cmp_eq_u32 s27, 12
	s_cselect_b32 s45, s1, s42
	s_cselect_b32 s44, s2, s35
	v_add_u32_e32 v140, s58, v141
	s_cselect_b32 s43, s8, s25
	s_cselect_b32 s42, s9, s15
	s_add_i32 s35, 0, 0x14000
	ds_read_b128 v[142:145], v140
	ds_read_b128 v[148:151], v140 offset:1024
	ds_read_b128 v[152:155], v140 offset:2048
	ds_read_b128 v[156:159], v140 offset:3072
	v_add_u32_e32 v140, s35, v141
	ds_read_b128 v[160:163], v140
	ds_read_b128 v[164:167], v140 offset:1024
	ds_read_b128 v[168:171], v140 offset:2048
	ds_read_b128 v[172:175], v140 offset:3072
	v_lshl_add_u64 v[212:213], s[36:37], 0, v[136:137]
	s_add_i32 m0, s64, 0xc000
	ds_read_b128 v[176:179], v146
	ds_read_b128 v[180:183], v146 offset:1024
	ds_read_b128 v[184:187], v146 offset:2048
	ds_read_b128 v[188:191], v146 offset:3072
	ds_read_b128 v[196:199], v146 offset:4096
	ds_read_b128 v[200:203], v146 offset:5120
	ds_read_b128 v[204:207], v146 offset:6144
	ds_read_b128 v[208:211], v146 offset:7168
	global_load_lds_dwordx4 v[212:213], off
	v_lshl_add_u64 v[212:213], s[36:37], 0, v[138:139]
	s_add_i32 m0, s64, 0xe000
	s_nop 0
	global_load_lds_dwordx4 v[212:213], off
	s_waitcnt vmcnt(8)
	s_waitcnt lgkmcnt(0)
	s_barrier
	s_setprio 1
	s_waitcnt lgkmcnt(0)
	v_mfma_f32_16x16x32_bf16 v[126:129], v[142:145], v[176:179], v[126:129]
	v_mfma_f32_16x16x32_bf16 v[122:125], v[152:155], v[176:179], v[122:125]
	v_mfma_f32_16x16x32_bf16 v[110:113], v[142:145], v[184:187], v[110:113]
	v_mfma_f32_16x16x32_bf16 v[106:109], v[152:155], v[184:187], v[106:109]
	v_mfma_f32_16x16x32_bf16 v[94:97], v[142:145], v[196:199], v[94:97]
	v_mfma_f32_16x16x32_bf16 v[90:93], v[152:155], v[196:199], v[90:93]
	v_mfma_f32_16x16x32_bf16 v[78:81], v[142:145], v[204:207], v[78:81]
	v_mfma_f32_16x16x32_bf16 v[74:77], v[152:155], v[204:207], v[74:77]
	v_mfma_f32_16x16x32_bf16 v[126:129], v[148:151], v[180:183], v[126:129]
	v_mfma_f32_16x16x32_bf16 v[122:125], v[156:159], v[180:183], v[122:125]
	v_mfma_f32_16x16x32_bf16 v[110:113], v[148:151], v[188:191], v[110:113]
	v_mfma_f32_16x16x32_bf16 v[106:109], v[156:159], v[188:191], v[106:109]
	v_mfma_f32_16x16x32_bf16 v[94:97], v[148:151], v[200:203], v[94:97]
	v_mfma_f32_16x16x32_bf16 v[90:93], v[156:159], v[200:203], v[90:93]
	v_mfma_f32_16x16x32_bf16 v[78:81], v[148:151], v[208:211], v[78:81]
	v_mfma_f32_16x16x32_bf16 v[74:77], v[156:159], v[208:211], v[74:77]
	v_mfma_f32_16x16x32_bf16 v[118:121], v[160:163], v[176:179], v[118:121]
	v_mfma_f32_16x16x32_bf16 v[114:117], v[168:171], v[176:179], v[114:117]
	v_mfma_f32_16x16x32_bf16 v[102:105], v[160:163], v[184:187], v[102:105]
	v_mfma_f32_16x16x32_bf16 v[98:101], v[168:171], v[184:187], v[98:101]
	v_mfma_f32_16x16x32_bf16 v[86:89], v[160:163], v[196:199], v[86:89]
	v_mfma_f32_16x16x32_bf16 v[82:85], v[168:171], v[196:199], v[82:85]
	v_mfma_f32_16x16x32_bf16 v[70:73], v[160:163], v[204:207], v[70:73]
	v_mfma_f32_16x16x32_bf16 v[66:69], v[168:171], v[204:207], v[66:69]
	v_mfma_f32_16x16x32_bf16 v[118:121], v[164:167], v[180:183], v[118:121]
	v_mfma_f32_16x16x32_bf16 v[114:117], v[172:175], v[180:183], v[114:117]
	v_mfma_f32_16x16x32_bf16 v[102:105], v[164:167], v[188:191], v[102:105]
	v_mfma_f32_16x16x32_bf16 v[98:101], v[172:175], v[188:191], v[98:101]
	v_mfma_f32_16x16x32_bf16 v[86:89], v[164:167], v[200:203], v[86:89]
	v_mfma_f32_16x16x32_bf16 v[82:85], v[172:175], v[200:203], v[82:85]
	v_mfma_f32_16x16x32_bf16 v[70:73], v[164:167], v[208:211], v[70:73]
	v_mfma_f32_16x16x32_bf16 v[66:69], v[172:175], v[208:211], v[66:69]
	s_setprio 0
	s_barrier
	s_add_i32 s58, s58, s62
	v_lshl_add_u64 v[212:213], s[42:43], 0, v[0:1]
	s_mov_b32 m0, s58
	ds_read_b128 v[176:179], v146 offset:16384
	ds_read_b128 v[180:183], v146 offset:17408
	ds_read_b128 v[184:187], v146 offset:18432
	ds_read_b128 v[188:191], v146 offset:19456
	ds_read_b128 v[196:199], v146 offset:20480
	ds_read_b128 v[200:203], v146 offset:21504
	ds_read_b128 v[204:207], v146 offset:22528
	ds_read_b128 v[208:211], v146 offset:23552
	global_load_lds_dwordx4 v[212:213], off
	s_add_i32 m0, s58, 0x2000
	s_add_u32 s58, s42, 0x40000
	v_lshl_add_u64 v[214:215], s[42:43], 0, v[130:131]
	s_addc_u32 s59, s43, 0
	s_add_i32 s35, s35, s62
	global_load_lds_dwordx4 v[214:215], off
	v_lshl_add_u64 v[220:221], s[58:59], 0, v[0:1]
	s_mov_b32 m0, s35
	v_lshl_add_u64 v[222:223], s[44:45], 0, v[132:133]
	global_load_lds_dwordx4 v[220:221], off
	v_lshl_add_u64 v[220:221], s[58:59], 0, v[130:131]
	s_add_i32 m0, s35, 0x2000
	s_nop 0
	global_load_lds_dwordx4 v[220:221], off
	v_lshl_add_u64 v[220:221], s[44:45], 0, v[134:135]
	s_mov_b32 m0, s64
	s_nop 0
	global_load_lds_dwordx4 v[220:221], off
	s_mov_b32 m0, s65
	s_nop 0
	global_load_lds_dwordx4 v[222:223], off
	s_waitcnt vmcnt(8)
	s_waitcnt lgkmcnt(0)
	s_barrier
; #define PG8_STAGE(bufoff, gbase, voff) do { _Pragma("unroll") for (int _i = 0; _i < 2; ++_i) \
;         __builtin_amdgcn_global_load_lds((const unsigned*)((const char*)(gbase) + (voff)[_i]), (LAS unsigned*)(lds + (bufoff) + ldsw + _i * 8192), 16, 0, 0); } while (0)
; #define PG8_LDA(dst, b, h) do { _Pragma("unroll") for (int m = 0; m < 4; ++m) _Pragma("unroll") for (int k = 0; k < 2; ++k) dst[m][k] = *(const LAS bf16x8*)(lds + PG8_SA(b, h) + aoff + m * 2048 + k * 1024); } while (0)
; #define PG8_LDB(dst, b, h) do { _Pragma("unroll") for (int n = 0; n < 2; ++n) _Pragma("unroll") for (int k = 0; k < 2; ++k) dst[n][k] = *(const LAS bf16x8*)(lds + PG8_SB(b, h) + boff + n * 2048 + k * 1024); } while (0)
; #define PG8_MMA(ai, bj, At, Bt) do { __builtin_amdgcn_s_setprio(1); _Pragma("unroll") for (int m = 0; m < 4; ++m) _Pragma("unroll") for (int n = 0; n < 2; ++n) _Pragma("unroll") for (int k = 0; k < 2; ++k) \
;         acc[ai][bj][m][n] = __builtin_amdgcn_mfma_f32_16x16x32_bf16(Bt[n][k], At[m][k], acc[ai][bj][m][n], 0, 0, 0); __builtin_amdgcn_s_setprio(0); } while (0)
; #define PG8_WAIT_V(n) asm volatile("s_waitcnt vmcnt(" #n ")" ::: "memory")
; #define PG8_WAIT_L(n) asm volatile("s_waitcnt lgkmcnt(" #n ")" ::: "memory")
; #define PG8_BAR __builtin_amdgcn_s_barrier()
; #define PG8_SCHED __builtin_amdgcn_sched_barrier(0)
; template <class Epi, class Sched, bool ALIGN_EPI = true, bool SP2 = true>
; __device__ __forceinline__ void gemm_phase(LAS unsigned char* lds, const Gemm g, const Sched& S, const Epi& E) {
;     ...
;             PG8_WAIT_V(8); PG8_WAIT_L(0); PG8_BAR; PG8_MMA(1, 0, At, B0); PG8_MMA(1, 1, At, B1); PG8_BAR; PG8_SCHED;
;             PG8_LDB(B0, 1, 0); PG8_LDB(B1, 1, 1); PG8_SCHED; PG8_LDA(At, 1, 0); PG8_STAGE(PG8_SA(0, 1), a2 + hstepA, voffA);
;             PG8_WAIT_V(8); PG8_WAIT_L(0); PG8_BAR; PG8_MMA(0, 0, At, B0); PG8_MMA(0, 1, At, B1); PG8_BAR; PG8_SCHED;
	s_setprio 1
	s_waitcnt lgkmcnt(0)
	v_mfma_f32_16x16x32_bf16 v[62:65], v[142:145], v[176:179], v[62:65]
	v_mfma_f32_16x16x32_bf16 v[58:61], v[152:155], v[176:179], v[58:61]
	v_mfma_f32_16x16x32_bf16 v[46:49], v[142:145], v[184:187], v[46:49]
	v_mfma_f32_16x16x32_bf16 v[42:45], v[152:155], v[184:187], v[42:45]
	v_mfma_f32_16x16x32_bf16 v[30:33], v[142:145], v[196:199], v[30:33]
	v_mfma_f32_16x16x32_bf16 v[26:29], v[152:155], v[196:199], v[26:29]
	v_mfma_f32_16x16x32_bf16 v[14:17], v[142:145], v[204:207], v[14:17]
	v_mfma_f32_16x16x32_bf16 v[10:13], v[152:155], v[204:207], v[10:13]
	v_mfma_f32_16x16x32_bf16 v[62:65], v[148:151], v[180:183], v[62:65]
	v_mfma_f32_16x16x32_bf16 v[58:61], v[156:159], v[180:183], v[58:61]
	v_mfma_f32_16x16x32_bf16 v[46:49], v[148:151], v[188:191], v[46:49]
	v_mfma_f32_16x16x32_bf16 v[42:45], v[156:159], v[188:191], v[42:45]
	v_mfma_f32_16x16x32_bf16 v[30:33], v[148:151], v[200:203], v[30:33]
	v_mfma_f32_16x16x32_bf16 v[26:29], v[156:159], v[200:203], v[26:29]
	v_mfma_f32_16x16x32_bf16 v[14:17], v[148:151], v[208:211], v[14:17]
	v_mfma_f32_16x16x32_bf16 v[10:13], v[156:159], v[208:211], v[10:13]
	v_mfma_f32_16x16x32_bf16 v[54:57], v[160:163], v[176:179], v[54:57]
	v_mfma_f32_16x16x32_bf16 v[50:53], v[168:171], v[176:179], v[50:53]
	v_mfma_f32_16x16x32_bf16 v[38:41], v[160:163], v[184:187], v[38:41]
	v_mfma_f32_16x16x32_bf16 v[34:37], v[168:171], v[184:187], v[34:37]
	v_mfma_f32_16x16x32_bf16 v[22:25], v[160:163], v[196:199], v[22:25]
	v_mfma_f32_16x16x32_bf16 v[18:21], v[168:171], v[196:199], v[18:21]
	v_mfma_f32_16x16x32_bf16 v[6:9], v[160:163], v[204:207], v[6:9]
	v_mfma_f32_16x16x32_bf16 v[2:5], v[168:171], v[204:207], v[2:5]
	v_mfma_f32_16x16x32_bf16 v[54:57], v[164:167], v[180:183], v[54:57]
	v_mfma_f32_16x16x32_bf16 v[50:53], v[172:175], v[180:183], v[50:53]
	v_mfma_f32_16x16x32_bf16 v[38:41], v[164:167], v[188:191], v[38:41]
	v_mfma_f32_16x16x32_bf16 v[34:37], v[172:175], v[188:191], v[34:37]
	v_mfma_f32_16x16x32_bf16 v[22:25], v[164:167], v[200:203], v[22:25]
	v_mfma_f32_16x16x32_bf16 v[18:21], v[172:175], v[200:203], v[18:21]
	v_mfma_f32_16x16x32_bf16 v[6:9], v[164:167], v[208:211], v[6:9]
	v_mfma_f32_16x16x32_bf16 v[2:5], v[172:175], v[208:211], v[2:5]
	s_setprio 0
	s_barrier
	s_add_i32 s35, 0, 0x18000
	v_add_u32_e32 v140, s35, v141
	s_add_i32 s58, 0, 0x1c000
	ds_read_b128 v[142:145], v140
	ds_read_b128 v[148:151], v140 offset:1024
	ds_read_b128 v[152:155], v140 offset:2048
	ds_read_b128 v[156:159], v140 offset:3072
	v_add_u32_e32 v140, s58, v141
	ds_read_b128 v[160:163], v140
	ds_read_b128 v[164:167], v140 offset:1024
	ds_read_b128 v[168:171], v140 offset:2048
	ds_read_b128 v[172:175], v140 offset:3072
	s_add_u32 s44, s44, 0x40000
	s_addc_u32 s45, s45, 0
	s_mov_b32 m0, s46
	v_lshl_add_u64 v[224:225], s[44:45], 0, v[134:135]
	ds_read_b128 v[176:179], v146 offset:32768
	ds_read_b128 v[180:183], v146 offset:33792
	ds_read_b128 v[184:187], v146 offset:34816
	ds_read_b128 v[188:191], v146 offset:35840
	ds_read_b128 v[196:199], v146 offset:36864
	ds_read_b128 v[200:203], v146 offset:37888
	ds_read_b128 v[204:207], v146 offset:38912
	ds_read_b128 v[208:211], v146 offset:39936
	global_load_lds_dwordx4 v[224:225], off
	v_lshl_add_u64 v[224:225], s[44:45], 0, v[132:133]
	s_mov_b32 m0, s51
	s_nop 0
	global_load_lds_dwordx4 v[224:225], off
	s_waitcnt vmcnt(8)
	s_waitcnt lgkmcnt(0)
	s_barrier
	s_setprio 1
	s_waitcnt lgkmcnt(0)
	v_mfma_f32_16x16x32_bf16 v[126:129], v[142:145], v[176:179], v[126:129]
	v_mfma_f32_16x16x32_bf16 v[122:125], v[152:155], v[176:179], v[122:125]
	v_mfma_f32_16x16x32_bf16 v[110:113], v[142:145], v[184:187], v[110:113]
	v_mfma_f32_16x16x32_bf16 v[106:109], v[152:155], v[184:187], v[106:109]
	v_mfma_f32_16x16x32_bf16 v[94:97], v[142:145], v[196:199], v[94:97]
	v_mfma_f32_16x16x32_bf16 v[90:93], v[152:155], v[196:199], v[90:93]
	v_mfma_f32_16x16x32_bf16 v[78:81], v[142:145], v[204:207], v[78:81]
	v_mfma_f32_16x16x32_bf16 v[74:77], v[152:155], v[204:207], v[74:77]
	v_mfma_f32_16x16x32_bf16 v[126:129], v[148:151], v[180:183], v[126:129]
	v_mfma_f32_16x16x32_bf16 v[122:125], v[156:159], v[180:183], v[122:125]
	v_mfma_f32_16x16x32_bf16 v[110:113], v[148:151], v[188:191], v[110:113]
	v_mfma_f32_16x16x32_bf16 v[106:109], v[156:159], v[188:191], v[106:109]
	v_mfma_f32_16x16x32_bf16 v[94:97], v[148:151], v[200:203], v[94:97]
	v_mfma_f32_16x16x32_bf16 v[90:93], v[156:159], v[200:203], v[90:93]
	v_mfma_f32_16x16x32_bf16 v[78:81], v[148:151], v[208:211], v[78:81]
	v_mfma_f32_16x16x32_bf16 v[74:77], v[156:159], v[208:211], v[74:77]
	v_mfma_f32_16x16x32_bf16 v[118:121], v[160:163], v[176:179], v[118:121]
	v_mfma_f32_16x16x32_bf16 v[114:117], v[168:171], v[176:179], v[114:117]
	v_mfma_f32_16x16x32_bf16 v[102:105], v[160:163], v[184:187], v[102:105]
	v_mfma_f32_16x16x32_bf16 v[98:101], v[168:171], v[184:187], v[98:101]
	v_mfma_f32_16x16x32_bf16 v[86:89], v[160:163], v[196:199], v[86:89]
	v_mfma_f32_16x16x32_bf16 v[82:85], v[168:171], v[196:199], v[82:85]
	v_mfma_f32_16x16x32_bf16 v[70:73], v[160:163], v[204:207], v[70:73]
	v_mfma_f32_16x16x32_bf16 v[66:69], v[168:171], v[204:207], v[66:69]
	v_mfma_f32_16x16x32_bf16 v[118:121], v[164:167], v[180:183], v[118:121]
	v_mfma_f32_16x16x32_bf16 v[114:117], v[172:175], v[180:183], v[114:117]
	v_mfma_f32_16x16x32_bf16 v[102:105], v[164:167], v[188:191], v[102:105]
	v_mfma_f32_16x16x32_bf16 v[98:101], v[172:175], v[188:191], v[98:101]
	v_mfma_f32_16x16x32_bf16 v[86:89], v[164:167], v[200:203], v[86:89]
	v_mfma_f32_16x16x32_bf16 v[82:85], v[172:175], v[200:203], v[82:85]
	v_mfma_f32_16x16x32_bf16 v[70:73], v[164:167], v[208:211], v[70:73]
	v_mfma_f32_16x16x32_bf16 v[66:69], v[172:175], v[208:211], v[66:69]
	s_setprio 0
	s_barrier
; #define PG8_STAGE(bufoff, gbase, voff) do { _Pragma("unroll") for (int _i = 0; _i < 2; ++_i) \
;         __builtin_amdgcn_global_load_lds((const unsigned*)((const char*)(gbase) + (voff)[_i]), (LAS unsigned*)(lds + (bufoff) + ldsw + _i * 8192), 16, 0, 0); } while (0)
; #define PG8_LDA(dst, b, h) do { _Pragma("unroll") for (int m = 0; m < 4; ++m) _Pragma("unroll") for (int k = 0; k < 2; ++k) dst[m][k] = *(const LAS bf16x8*)(lds + PG8_SA(b, h) + aoff + m * 2048 + k * 1024); } while (0)
; #define PG8_MMA(ai, bj, At, Bt) do { __builtin_amdgcn_s_setprio(1); _Pragma("unroll") for (int m = 0; m < 4; ++m) _Pragma("unroll") for (int n = 0; n < 2; ++n) _Pragma("unroll") for (int k = 0; k < 2; ++k) \
;         acc[ai][bj][m][n] = __builtin_amdgcn_mfma_f32_16x16x32_bf16(Bt[n][k], At[m][k], acc[ai][bj][m][n], 0, 0, 0); __builtin_amdgcn_s_setprio(0); } while (0)
; #define PG8_WAIT_V(n) asm volatile("s_waitcnt vmcnt(" #n ")" ::: "memory")
; #define PG8_WAIT_L(n) asm volatile("s_waitcnt lgkmcnt(" #n ")" ::: "memory")
; #define PG8_BAR __builtin_amdgcn_s_barrier()
; #define PG8_SCHED __builtin_amdgcn_sched_barrier(0)
; template <class Epi, class Sched, bool ALIGN_EPI = true, bool SP2 = true>
; __device__ __forceinline__ void gemm_phase(LAS unsigned char* lds, const Gemm g, const Sched& S, const Epi& E) {
;     ...
;             PG8_LDA(At, 1, 1); PG8_STAGE(PG8_SB(1, 0), b3, voffB); PG8_STAGE(PG8_SB(1, 1), b3 + hstepB, voffB); PG8_STAGE(PG8_SA(1, 0), a3, voffA);
;             PG8_WAIT_V(8); PG8_WAIT_L(0); PG8_BAR; PG8_MMA(1, 0, At, B0); PG8_MMA(1, 1, At, B1); PG8_BAR; PG8_SCHED;
;         }
	s_add_i32 s35, s35, s62
	v_lshl_add_u64 v[212:213], v[212:213], 0, s[12:13]
	s_mov_b32 m0, s35
	ds_read_b128 v[176:179], v146 offset:49152
	ds_read_b128 v[180:183], v146 offset:50176
	ds_read_b128 v[184:187], v146 offset:51200
	ds_read_b128 v[188:191], v146 offset:52224
	ds_read_b128 v[196:199], v146 offset:53248
	ds_read_b128 v[200:203], v146 offset:54272
	ds_read_b128 v[204:207], v146 offset:55296
	ds_read_b128 v[208:211], v146 offset:56320
	global_load_lds_dwordx4 v[212:213], off
	s_add_i32 m0, s35, 0x2000
	s_add_u32 s42, s42, 0x40080
	v_lshl_add_u64 v[212:213], v[214:215], 0, s[12:13]
	s_addc_u32 s43, s43, 0
	s_add_i32 s35, s58, s62
	global_load_lds_dwordx4 v[212:213], off
	v_lshl_add_u64 v[212:213], s[42:43], 0, v[0:1]
	s_mov_b32 m0, s35
	s_nop 0
	global_load_lds_dwordx4 v[212:213], off
	v_lshl_add_u64 v[212:213], s[42:43], 0, v[130:131]
	s_add_i32 m0, s35, 0x2000
	s_nop 0
	global_load_lds_dwordx4 v[212:213], off
	v_lshl_add_u64 v[212:213], v[220:221], 0, s[12:13]
	s_mov_b32 m0, s16
	s_nop 0
	global_load_lds_dwordx4 v[212:213], off
	v_lshl_add_u64 v[212:213], v[222:223], 0, s[12:13]
	s_mov_b32 m0, s17
	s_nop 0
	global_load_lds_dwordx4 v[212:213], off
	s_waitcnt vmcnt(8)
	s_waitcnt lgkmcnt(0)
	s_barrier
	s_setprio 1
	s_waitcnt lgkmcnt(0)
	v_mfma_f32_16x16x32_bf16 v[62:65], v[142:145], v[176:179], v[62:65]
	v_mfma_f32_16x16x32_bf16 v[58:61], v[152:155], v[176:179], v[58:61]
	v_mfma_f32_16x16x32_bf16 v[46:49], v[142:145], v[184:187], v[46:49]
	v_mfma_f32_16x16x32_bf16 v[42:45], v[152:155], v[184:187], v[42:45]
	v_mfma_f32_16x16x32_bf16 v[30:33], v[142:145], v[196:199], v[30:33]
	v_mfma_f32_16x16x32_bf16 v[26:29], v[152:155], v[196:199], v[26:29]
	v_mfma_f32_16x16x32_bf16 v[14:17], v[142:145], v[204:207], v[14:17]
	v_mfma_f32_16x16x32_bf16 v[10:13], v[152:155], v[204:207], v[10:13]
	v_mfma_f32_16x16x32_bf16 v[62:65], v[148:151], v[180:183], v[62:65]
	v_mfma_f32_16x16x32_bf16 v[58:61], v[156:159], v[180:183], v[58:61]
	v_mfma_f32_16x16x32_bf16 v[46:49], v[148:151], v[188:191], v[46:49]
	v_mfma_f32_16x16x32_bf16 v[42:45], v[156:159], v[188:191], v[42:45]
	v_mfma_f32_16x16x32_bf16 v[30:33], v[148:151], v[200:203], v[30:33]
	v_mfma_f32_16x16x32_bf16 v[26:29], v[156:159], v[200:203], v[26:29]
	v_mfma_f32_16x16x32_bf16 v[14:17], v[148:151], v[208:211], v[14:17]
	v_mfma_f32_16x16x32_bf16 v[10:13], v[156:159], v[208:211], v[10:13]
	v_mfma_f32_16x16x32_bf16 v[54:57], v[160:163], v[176:179], v[54:57]
	v_mfma_f32_16x16x32_bf16 v[50:53], v[168:171], v[176:179], v[50:53]
	v_mfma_f32_16x16x32_bf16 v[38:41], v[160:163], v[184:187], v[38:41]
	v_mfma_f32_16x16x32_bf16 v[34:37], v[168:171], v[184:187], v[34:37]
	v_mfma_f32_16x16x32_bf16 v[22:25], v[160:163], v[196:199], v[22:25]
	v_mfma_f32_16x16x32_bf16 v[18:21], v[168:171], v[196:199], v[18:21]
	v_mfma_f32_16x16x32_bf16 v[6:9], v[160:163], v[204:207], v[6:9]
	v_mfma_f32_16x16x32_bf16 v[2:5], v[168:171], v[204:207], v[2:5]
	v_mfma_f32_16x16x32_bf16 v[54:57], v[164:167], v[180:183], v[54:57]
	v_mfma_f32_16x16x32_bf16 v[50:53], v[172:175], v[180:183], v[50:53]
	v_mfma_f32_16x16x32_bf16 v[38:41], v[164:167], v[188:191], v[38:41]
	v_mfma_f32_16x16x32_bf16 v[34:37], v[172:175], v[188:191], v[34:37]
	v_mfma_f32_16x16x32_bf16 v[22:25], v[164:167], v[200:203], v[22:25]
	v_mfma_f32_16x16x32_bf16 v[18:21], v[172:175], v[200:203], v[18:21]
	v_mfma_f32_16x16x32_bf16 v[6:9], v[164:167], v[208:211], v[6:9]
	v_mfma_f32_16x16x32_bf16 v[2:5], v[172:175], v[208:211], v[2:5]
	s_setprio 0
	s_barrier
	s_add_i32 s27, s27, 2
	s_add_u32 s36, s36, 0x100
	s_addc_u32 s37, s37, 0
	s_add_u32 s15, s15, 0x100
	s_addc_u32 s25, s25, 0
	s_cmp_gt_u32 s27, 13
	s_cbranch_scc0 .LBB0_205
	s_and_b64 vcc, exec, s[22:23]
	s_cbranch_vccz .LBB0_208
	s_barrier

; #define PG8_STAGE(bufoff, gbase, voff) do { _Pragma("unroll") for (int _i = 0; _i < 2; ++_i) \
;         __builtin_amdgcn_global_load_lds((const unsigned*)((const char*)(gbase) + (voff)[_i]), (LAS unsigned*)(lds + (bufoff) + ldsw + _i * 8192), 16, 0, 0); } while (0)
; #define PG8_LDA(dst, b, h) do { _Pragma("unroll") for (int m = 0; m < 4; ++m) _Pragma("unroll") for (int k = 0; k < 2; ++k) dst[m][k] = *(const LAS bf16x8*)(lds + PG8_SA(b, h) + aoff + m * 2048 + k * 1024); } while (0)
; #define PG8_LDB(dst, b, h) do { _Pragma("unroll") for (int n = 0; n < 2; ++n) _Pragma("unroll") for (int k = 0; k < 2; ++k) dst[n][k] = *(const LAS bf16x8*)(lds + PG8_SB(b, h) + boff + n * 2048 + k * 1024); } while (0)
; #define PG8_MMA(ai, bj, At, Bt) do { __builtin_amdgcn_s_setprio(1); _Pragma("unroll") for (int m = 0; m < 4; ++m) _Pragma("unroll") for (int n = 0; n < 2; ++n) _Pragma("unroll") for (int k = 0; k < 2; ++k) \
;         acc[ai][bj][m][n] = __builtin_amdgcn_mfma_f32_16x16x32_bf16(Bt[n][k], At[m][k], acc[ai][bj][m][n], 0, 0, 0); __builtin_amdgcn_s_setprio(0); } while (0)
; #define PG8_WAIT_V(n) asm volatile("s_waitcnt vmcnt(" #n ")" ::: "memory")
; #define PG8_WAIT_L(n) asm volatile("s_waitcnt lgkmcnt(" #n ")" ::: "memory")
; #define PG8_BAR __builtin_amdgcn_s_barrier()
; template <class Epi, class Sched, bool ALIGN_EPI = true, bool SP2 = true>
; __device__ __forceinline__ void gemm_phase(LAS unsigned char* lds, const Gemm g, const Sched& S, const Epi& E) {
;     ...
;         for (int t = 0; t < nt; t += 2) {
;             const bool last = (t == nt - 2);
;             const char* a1 = cA + (size_t)(t + 1) * kstep;
;             const char* a2 = last ? nA : cA + (size_t)(t + 2) * kstep; const char* b2 = last ? nB : cB + (size_t)(t + 2) * kstep;
;             const char* a3 = a2 + kstep; const char* b3 = b2 + kstep;
;             PG8_LDB(B0, 0, 0); PG8_LDB(B1, 0, 1); PG8_SCHED; PG8_LDA(At, 0, 0); PG8_STAGE(PG8_SA(1, 1), a1 + hstepA, voffA);
;             PG8_WAIT_V(8); PG8_WAIT_L(0); PG8_BAR; PG8_MMA(0, 0, At, B0); PG8_MMA(0, 1, At, B1); PG8_BAR; PG8_SCHED;
;             PG8_LDA(At, 0, 1); PG8_STAGE(PG8_SB(0, 0), b2, voffB); PG8_STAGE(PG8_SB(0, 1), b2 + hstepB, voffB); PG8_STAGE(PG8_SA(0, 0), a2, voffA);
;             PG8_WAIT_V(8); PG8_WAIT_L(0); PG8_BAR; PG8_MMA(1, 0, At, B0); PG8_MMA(1, 1, At, B1); PG8_BAR; PG8_SCHED;
.LBB0_458:
	s_add_u32 s18, s50, 0xfffc0080
	s_addc_u32 s19, s51, -1
	s_add_i32 s58, 0, 0x10000
	s_cmp_eq_u32 s60, 12
	s_cselect_b32 s21, s22, s19
	s_cselect_b32 s20, s23, s18
	v_add_u32_e32 v146, s58, v144
	s_cselect_b32 s19, s2, s45
	s_cselect_b32 s18, s43, s30
	s_add_i32 s61, 0, 0x14000
	ds_read_b128 v[140:143], v146
	ds_read_b128 v[164:167], v146 offset:1024
	ds_read_b128 v[168:171], v146 offset:2048
	ds_read_b128 v[172:175], v146 offset:3072
	v_add_u32_e32 v146, s61, v144
	ds_read_b128 v[198:201], v146
	ds_read_b128 v[202:205], v146 offset:1024
	ds_read_b128 v[206:209], v146 offset:2048
	ds_read_b128 v[210:213], v146 offset:3072
	v_lshl_add_u64 v[146:147], s[50:51], 0, v[136:137]
	s_add_i32 m0, s53, 0xc000
	ds_read_b128 v[218:221], v145
	ds_read_b128 v[222:225], v145 offset:1024
	ds_read_b128 v[226:229], v145 offset:2048
	ds_read_b128 v[230:233], v145 offset:3072
	ds_read_b128 v[234:237], v145 offset:4096
	ds_read_b128 v[238:241], v145 offset:5120
	ds_read_b128 v[242:245], v145 offset:6144
	ds_read_b128 v[246:249], v145 offset:7168
	global_load_lds_dwordx4 v[146:147], off
	v_lshl_add_u64 v[146:147], s[50:51], 0, v[138:139]
	s_add_i32 m0, s53, 0xe000
	s_nop 0
	global_load_lds_dwordx4 v[146:147], off
	s_waitcnt vmcnt(8)
	s_waitcnt lgkmcnt(0)
	s_barrier
	s_setprio 1
	s_waitcnt lgkmcnt(0)
	v_mfma_f32_16x16x32_bf16 v[128:131], v[140:143], v[218:221], v[128:131]
	v_mfma_f32_16x16x32_bf16 v[124:127], v[168:171], v[218:221], v[124:127]
	v_mfma_f32_16x16x32_bf16 v[120:123], v[140:143], v[226:229], v[120:123]
	v_mfma_f32_16x16x32_bf16 v[112:115], v[168:171], v[226:229], v[112:115]
	v_mfma_f32_16x16x32_bf16 v[104:107], v[140:143], v[234:237], v[104:107]
	v_mfma_f32_16x16x32_bf16 v[96:99], v[168:171], v[234:237], v[96:99]
	v_mfma_f32_16x16x32_bf16 v[88:91], v[140:143], v[242:245], v[88:91]
	v_mfma_f32_16x16x32_bf16 v[80:83], v[168:171], v[242:245], v[80:83]
	v_mfma_f32_16x16x32_bf16 v[128:131], v[164:167], v[222:225], v[128:131]
	v_mfma_f32_16x16x32_bf16 v[124:127], v[172:175], v[222:225], v[124:127]
	v_mfma_f32_16x16x32_bf16 v[120:123], v[164:167], v[230:233], v[120:123]
	v_mfma_f32_16x16x32_bf16 v[112:115], v[172:175], v[230:233], v[112:115]
	v_mfma_f32_16x16x32_bf16 v[104:107], v[164:167], v[238:241], v[104:107]
	v_mfma_f32_16x16x32_bf16 v[96:99], v[172:175], v[238:241], v[96:99]
	v_mfma_f32_16x16x32_bf16 v[88:91], v[164:167], v[246:249], v[88:91]
	v_mfma_f32_16x16x32_bf16 v[80:83], v[172:175], v[246:249], v[80:83]
	v_mfma_f32_16x16x32_bf16 v[116:119], v[198:201], v[218:221], v[116:119]
	v_mfma_f32_16x16x32_bf16 v[108:111], v[206:209], v[218:221], v[108:111]
	v_mfma_f32_16x16x32_bf16 v[100:103], v[198:201], v[226:229], v[100:103]
	v_mfma_f32_16x16x32_bf16 v[92:95], v[206:209], v[226:229], v[92:95]
	v_mfma_f32_16x16x32_bf16 v[84:87], v[198:201], v[234:237], v[84:87]
	v_mfma_f32_16x16x32_bf16 v[76:79], v[206:209], v[234:237], v[76:79]
	v_mfma_f32_16x16x32_bf16 v[72:75], v[198:201], v[242:245], v[72:75]
	v_mfma_f32_16x16x32_bf16 v[68:71], v[206:209], v[242:245], v[68:71]
	v_mfma_f32_16x16x32_bf16 v[116:119], v[202:205], v[222:225], v[116:119]
	v_mfma_f32_16x16x32_bf16 v[108:111], v[210:213], v[222:225], v[108:111]
	v_mfma_f32_16x16x32_bf16 v[100:103], v[202:205], v[230:233], v[100:103]
	v_mfma_f32_16x16x32_bf16 v[92:95], v[210:213], v[230:233], v[92:95]
	v_mfma_f32_16x16x32_bf16 v[84:87], v[202:205], v[238:241], v[84:87]
	v_mfma_f32_16x16x32_bf16 v[76:79], v[210:213], v[238:241], v[76:79]
	v_mfma_f32_16x16x32_bf16 v[72:75], v[202:205], v[246:249], v[72:75]
	v_mfma_f32_16x16x32_bf16 v[68:71], v[210:213], v[246:249], v[68:71]
	s_setprio 0
	s_barrier
	s_add_i32 s58, s58, s39
	v_lshl_add_u64 v[146:147], s[18:19], 0, v[18:19]
	s_mov_b32 m0, s58
	ds_read_b128 v[218:221], v145 offset:16384
	ds_read_b128 v[222:225], v145 offset:17408
	ds_read_b128 v[226:229], v145 offset:18432
	ds_read_b128 v[230:233], v145 offset:19456
	ds_read_b128 v[234:237], v145 offset:20480
	ds_read_b128 v[238:241], v145 offset:21504
	ds_read_b128 v[242:245], v145 offset:22528
	ds_read_b128 v[246:249], v145 offset:23552
	global_load_lds_dwordx4 v[146:147], off
	s_add_i32 m0, s58, 0x2000
	s_add_u32 s58, s18, 0x40000
	v_lshl_add_u64 v[148:149], s[18:19], 0, v[16:17]
	s_addc_u32 s59, s19, 0
	s_add_i32 s61, s61, s39
	global_load_lds_dwordx4 v[148:149], off
	v_lshl_add_u64 v[150:151], s[58:59], 0, v[18:19]
	s_mov_b32 m0, s61
	v_lshl_add_u64 v[152:153], s[20:21], 0, v[132:133]
	global_load_lds_dwordx4 v[150:151], off
	v_lshl_add_u64 v[150:151], s[58:59], 0, v[16:17]
	s_add_i32 m0, s61, 0x2000
	s_nop 0
	global_load_lds_dwordx4 v[150:151], off
	v_lshl_add_u64 v[150:151], s[20:21], 0, v[134:135]
	s_mov_b32 m0, s53
	s_nop 0
	global_load_lds_dwordx4 v[150:151], off
	s_mov_b32 m0, s0
	s_nop 0
	global_load_lds_dwordx4 v[152:153], off
	s_waitcnt vmcnt(8)
	s_waitcnt lgkmcnt(0)
	s_barrier
; #define PG8_STAGE(bufoff, gbase, voff) do { _Pragma("unroll") for (int _i = 0; _i < 2; ++_i) \
;         __builtin_amdgcn_global_load_lds((const unsigned*)((const char*)(gbase) + (voff)[_i]), (LAS unsigned*)(lds + (bufoff) + ldsw + _i * 8192), 16, 0, 0); } while (0)
; #define PG8_LDA(dst, b, h) do { _Pragma("unroll") for (int m = 0; m < 4; ++m) _Pragma("unroll") for (int k = 0; k < 2; ++k) dst[m][k] = *(const LAS bf16x8*)(lds + PG8_SA(b, h) + aoff + m * 2048 + k * 1024); } while (0)
; #define PG8_LDB(dst, b, h) do { _Pragma("unroll") for (int n = 0; n < 2; ++n) _Pragma("unroll") for (int k = 0; k < 2; ++k) dst[n][k] = *(const LAS bf16x8*)(lds + PG8_SB(b, h) + boff + n * 2048 + k * 1024); } while (0)
; #define PG8_MMA(ai, bj, At, Bt) do { __builtin_amdgcn_s_setprio(1); _Pragma("unroll") for (int m = 0; m < 4; ++m) _Pragma("unroll") for (int n = 0; n < 2; ++n) _Pragma("unroll") for (int k = 0; k < 2; ++k) \
;         acc[ai][bj][m][n] = __builtin_amdgcn_mfma_f32_16x16x32_bf16(Bt[n][k], At[m][k], acc[ai][bj][m][n], 0, 0, 0); __builtin_amdgcn_s_setprio(0); } while (0)
; #define PG8_WAIT_V(n) asm volatile("s_waitcnt vmcnt(" #n ")" ::: "memory")
; #define PG8_WAIT_L(n) asm volatile("s_waitcnt lgkmcnt(" #n ")" ::: "memory")
; #define PG8_BAR __builtin_amdgcn_s_barrier()
; #define PG8_SCHED __builtin_amdgcn_sched_barrier(0)
; template <class Epi, class Sched, bool ALIGN_EPI = true, bool SP2 = true>
; __device__ __forceinline__ void gemm_phase(LAS unsigned char* lds, const Gemm g, const Sched& S, const Epi& E) {
;     ...
;             PG8_WAIT_V(8); PG8_WAIT_L(0); PG8_BAR; PG8_MMA(1, 0, At, B0); PG8_MMA(1, 1, At, B1); PG8_BAR; PG8_SCHED;
;             PG8_LDB(B0, 1, 0); PG8_LDB(B1, 1, 1); PG8_SCHED; PG8_LDA(At, 1, 0); PG8_STAGE(PG8_SA(0, 1), a2 + hstepA, voffA);
;             PG8_WAIT_V(8); PG8_WAIT_L(0); PG8_BAR; PG8_MMA(0, 0, At, B0); PG8_MMA(0, 1, At, B1); PG8_BAR; PG8_SCHED;
	s_setprio 1
	s_waitcnt lgkmcnt(0)
	v_mfma_f32_16x16x32_bf16 v[64:67], v[140:143], v[218:221], v[64:67]
	v_mfma_f32_16x16x32_bf16 v[60:63], v[168:171], v[218:221], v[60:63]
	v_mfma_f32_16x16x32_bf16 v[56:59], v[140:143], v[226:229], v[56:59]
	v_mfma_f32_16x16x32_bf16 v[48:51], v[168:171], v[226:229], v[48:51]
	v_mfma_f32_16x16x32_bf16 v[40:43], v[140:143], v[234:237], v[40:43]
	v_mfma_f32_16x16x32_bf16 v[32:35], v[168:171], v[234:237], v[32:35]
	v_mfma_f32_16x16x32_bf16 v[24:27], v[140:143], v[242:245], v[24:27]
	v_mfma_f32_16x16x32_bf16 v[12:15], v[168:171], v[242:245], v[12:15]
	v_mfma_f32_16x16x32_bf16 v[64:67], v[164:167], v[222:225], v[64:67]
	v_mfma_f32_16x16x32_bf16 v[60:63], v[172:175], v[222:225], v[60:63]
	v_mfma_f32_16x16x32_bf16 v[56:59], v[164:167], v[230:233], v[56:59]
	v_mfma_f32_16x16x32_bf16 v[48:51], v[172:175], v[230:233], v[48:51]
	v_mfma_f32_16x16x32_bf16 v[40:43], v[164:167], v[238:241], v[40:43]
	v_mfma_f32_16x16x32_bf16 v[32:35], v[172:175], v[238:241], v[32:35]
	v_mfma_f32_16x16x32_bf16 v[24:27], v[164:167], v[246:249], v[24:27]
	v_mfma_f32_16x16x32_bf16 v[12:15], v[172:175], v[246:249], v[12:15]
	v_mfma_f32_16x16x32_bf16 v[52:55], v[198:201], v[218:221], v[52:55]
	v_mfma_f32_16x16x32_bf16 v[44:47], v[206:209], v[218:221], v[44:47]
	v_mfma_f32_16x16x32_bf16 v[36:39], v[198:201], v[226:229], v[36:39]
	v_mfma_f32_16x16x32_bf16 v[28:31], v[206:209], v[226:229], v[28:31]
	v_mfma_f32_16x16x32_bf16 v[20:23], v[198:201], v[234:237], v[20:23]
	v_mfma_f32_16x16x32_bf16 v[8:11], v[206:209], v[234:237], v[8:11]
	v_mfma_f32_16x16x32_bf16 v[4:7], v[198:201], v[242:245], v[4:7]
	v_mfma_f32_16x16x32_bf16 v[0:3], v[206:209], v[242:245], v[0:3]
	v_mfma_f32_16x16x32_bf16 v[52:55], v[202:205], v[222:225], v[52:55]
	v_mfma_f32_16x16x32_bf16 v[44:47], v[210:213], v[222:225], v[44:47]
	v_mfma_f32_16x16x32_bf16 v[36:39], v[202:205], v[230:233], v[36:39]
	v_mfma_f32_16x16x32_bf16 v[28:31], v[210:213], v[230:233], v[28:31]
	v_mfma_f32_16x16x32_bf16 v[20:23], v[202:205], v[238:241], v[20:23]
	v_mfma_f32_16x16x32_bf16 v[8:11], v[210:213], v[238:241], v[8:11]
	v_mfma_f32_16x16x32_bf16 v[4:7], v[202:205], v[246:249], v[4:7]
	v_mfma_f32_16x16x32_bf16 v[0:3], v[210:213], v[246:249], v[0:3]
	s_setprio 0
	s_barrier
	s_add_i32 s58, 0, 0x18000
	v_add_u32_e32 v154, s58, v144
	s_add_i32 s59, 0, 0x1c000
	ds_read_b128 v[140:143], v154
	ds_read_b128 v[164:167], v154 offset:1024
	ds_read_b128 v[168:171], v154 offset:2048
	ds_read_b128 v[172:175], v154 offset:3072
	v_add_u32_e32 v154, s59, v144
	ds_read_b128 v[198:201], v154
	ds_read_b128 v[202:205], v154 offset:1024
	ds_read_b128 v[206:209], v154 offset:2048
	ds_read_b128 v[210:213], v154 offset:3072
	s_add_u32 s20, s20, 0x40000
	s_addc_u32 s21, s21, 0
	s_mov_b32 m0, s1
	v_lshl_add_u64 v[154:155], s[20:21], 0, v[134:135]
	ds_read_b128 v[218:221], v145 offset:32768
	ds_read_b128 v[222:225], v145 offset:33792
	ds_read_b128 v[226:229], v145 offset:34816
	ds_read_b128 v[230:233], v145 offset:35840
	ds_read_b128 v[234:237], v145 offset:36864
	ds_read_b128 v[238:241], v145 offset:37888
	ds_read_b128 v[242:245], v145 offset:38912
	ds_read_b128 v[246:249], v145 offset:39936
	global_load_lds_dwordx4 v[154:155], off
	v_lshl_add_u64 v[154:155], s[20:21], 0, v[132:133]
	s_mov_b32 m0, s8
	s_nop 0
	global_load_lds_dwordx4 v[154:155], off
	s_waitcnt vmcnt(8)
	s_waitcnt lgkmcnt(0)
	s_barrier
	s_setprio 1
	s_waitcnt lgkmcnt(0)
	v_mfma_f32_16x16x32_bf16 v[128:131], v[140:143], v[218:221], v[128:131]
	v_mfma_f32_16x16x32_bf16 v[124:127], v[168:171], v[218:221], v[124:127]
	v_mfma_f32_16x16x32_bf16 v[120:123], v[140:143], v[226:229], v[120:123]
	v_mfma_f32_16x16x32_bf16 v[112:115], v[168:171], v[226:229], v[112:115]
	v_mfma_f32_16x16x32_bf16 v[104:107], v[140:143], v[234:237], v[104:107]
	v_mfma_f32_16x16x32_bf16 v[96:99], v[168:171], v[234:237], v[96:99]
	v_mfma_f32_16x16x32_bf16 v[88:91], v[140:143], v[242:245], v[88:91]
	v_mfma_f32_16x16x32_bf16 v[80:83], v[168:171], v[242:245], v[80:83]
	v_mfma_f32_16x16x32_bf16 v[128:131], v[164:167], v[222:225], v[128:131]
	v_mfma_f32_16x16x32_bf16 v[124:127], v[172:175], v[222:225], v[124:127]
	v_mfma_f32_16x16x32_bf16 v[120:123], v[164:167], v[230:233], v[120:123]
	v_mfma_f32_16x16x32_bf16 v[112:115], v[172:175], v[230:233], v[112:115]
	v_mfma_f32_16x16x32_bf16 v[104:107], v[164:167], v[238:241], v[104:107]
	v_mfma_f32_16x16x32_bf16 v[96:99], v[172:175], v[238:241], v[96:99]
	v_mfma_f32_16x16x32_bf16 v[88:91], v[164:167], v[246:249], v[88:91]
	v_mfma_f32_16x16x32_bf16 v[80:83], v[172:175], v[246:249], v[80:83]
	v_mfma_f32_16x16x32_bf16 v[116:119], v[198:201], v[218:221], v[116:119]
	v_mfma_f32_16x16x32_bf16 v[108:111], v[206:209], v[218:221], v[108:111]
	v_mfma_f32_16x16x32_bf16 v[100:103], v[198:201], v[226:229], v[100:103]
	v_mfma_f32_16x16x32_bf16 v[92:95], v[206:209], v[226:229], v[92:95]
	v_mfma_f32_16x16x32_bf16 v[84:87], v[198:201], v[234:237], v[84:87]
	v_mfma_f32_16x16x32_bf16 v[76:79], v[206:209], v[234:237], v[76:79]
	v_mfma_f32_16x16x32_bf16 v[72:75], v[198:201], v[242:245], v[72:75]
	v_mfma_f32_16x16x32_bf16 v[68:71], v[206:209], v[242:245], v[68:71]
	v_mfma_f32_16x16x32_bf16 v[116:119], v[202:205], v[222:225], v[116:119]
	v_mfma_f32_16x16x32_bf16 v[108:111], v[210:213], v[222:225], v[108:111]
	v_mfma_f32_16x16x32_bf16 v[100:103], v[202:205], v[230:233], v[100:103]
	v_mfma_f32_16x16x32_bf16 v[92:95], v[210:213], v[230:233], v[92:95]
	v_mfma_f32_16x16x32_bf16 v[84:87], v[202:205], v[238:241], v[84:87]
	v_mfma_f32_16x16x32_bf16 v[76:79], v[210:213], v[238:241], v[76:79]
	v_mfma_f32_16x16x32_bf16 v[72:75], v[202:205], v[246:249], v[72:75]
	v_mfma_f32_16x16x32_bf16 v[68:71], v[210:213], v[246:249], v[68:71]
	s_setprio 0
	s_barrier
; #define PG8_STAGE(bufoff, gbase, voff) do { _Pragma("unroll") for (int _i = 0; _i < 2; ++_i) \
;         __builtin_amdgcn_global_load_lds((const unsigned*)((const char*)(gbase) + (voff)[_i]), (LAS unsigned*)(lds + (bufoff) + ldsw + _i * 8192), 16, 0, 0); } while (0)
; #define PG8_LDA(dst, b, h) do { _Pragma("unroll") for (int m = 0; m < 4; ++m) _Pragma("unroll") for (int k = 0; k < 2; ++k) dst[m][k] = *(const LAS bf16x8*)(lds + PG8_SA(b, h) + aoff + m * 2048 + k * 1024); } while (0)
; #define PG8_MMA(ai, bj, At, Bt) do { __builtin_amdgcn_s_setprio(1); _Pragma("unroll") for (int m = 0; m < 4; ++m) _Pragma("unroll") for (int n = 0; n < 2; ++n) _Pragma("unroll") for (int k = 0; k < 2; ++k) \
;         acc[ai][bj][m][n] = __builtin_amdgcn_mfma_f32_16x16x32_bf16(Bt[n][k], At[m][k], acc[ai][bj][m][n], 0, 0, 0); __builtin_amdgcn_s_setprio(0); } while (0)
; #define PG8_WAIT_V(n) asm volatile("s_waitcnt vmcnt(" #n ")" ::: "memory")
; #define PG8_WAIT_L(n) asm volatile("s_waitcnt lgkmcnt(" #n ")" ::: "memory")
; #define PG8_BAR __builtin_amdgcn_s_barrier()
; #define PG8_SCHED __builtin_amdgcn_sched_barrier(0)
; template <class Epi, class Sched, bool ALIGN_EPI = true, bool SP2 = true>
; __device__ __forceinline__ void gemm_phase(LAS unsigned char* lds, const Gemm g, const Sched& S, const Epi& E) {
;     ...
;             PG8_LDA(At, 1, 1); PG8_STAGE(PG8_SB(1, 0), b3, voffB); PG8_STAGE(PG8_SB(1, 1), b3 + hstepB, voffB); PG8_STAGE(PG8_SA(1, 0), a3, voffA);
;             PG8_WAIT_V(8); PG8_WAIT_L(0); PG8_BAR; PG8_MMA(1, 0, At, B0); PG8_MMA(1, 1, At, B1); PG8_BAR; PG8_SCHED;
;         }
	s_add_i32 s20, s58, s39
	v_lshl_add_u64 v[146:147], v[146:147], 0, s[14:15]
	s_mov_b32 m0, s20
	ds_read_b128 v[218:221], v145 offset:49152
	ds_read_b128 v[222:225], v145 offset:50176
	ds_read_b128 v[226:229], v145 offset:51200
	ds_read_b128 v[230:233], v145 offset:52224
	ds_read_b128 v[234:237], v145 offset:53248
	ds_read_b128 v[238:241], v145 offset:54272
	ds_read_b128 v[242:245], v145 offset:55296
	ds_read_b128 v[246:249], v145 offset:56320
	global_load_lds_dwordx4 v[146:147], off
	s_add_i32 m0, s20, 0x2000
	s_add_u32 s18, s18, 0x40080
	v_lshl_add_u64 v[146:147], v[148:149], 0, s[14:15]
	s_addc_u32 s19, s19, 0
	s_add_i32 s20, s59, s39
	global_load_lds_dwordx4 v[146:147], off
	v_lshl_add_u64 v[146:147], s[18:19], 0, v[18:19]
	s_mov_b32 m0, s20
	s_nop 0
	global_load_lds_dwordx4 v[146:147], off
	v_lshl_add_u64 v[146:147], s[18:19], 0, v[16:17]
	s_add_i32 m0, s20, 0x2000
	s_nop 0
	global_load_lds_dwordx4 v[146:147], off
	v_lshl_add_u64 v[146:147], v[150:151], 0, s[14:15]
	s_mov_b32 m0, s54
	s_nop 0
	global_load_lds_dwordx4 v[146:147], off
	v_lshl_add_u64 v[146:147], v[152:153], 0, s[14:15]
	s_mov_b32 m0, s55
	s_nop 0
	global_load_lds_dwordx4 v[146:147], off
	s_waitcnt vmcnt(8)
	s_waitcnt lgkmcnt(0)
	s_barrier
	s_setprio 1
	s_waitcnt lgkmcnt(0)
	v_mfma_f32_16x16x32_bf16 v[64:67], v[140:143], v[218:221], v[64:67]
	v_mfma_f32_16x16x32_bf16 v[60:63], v[168:171], v[218:221], v[60:63]
	v_mfma_f32_16x16x32_bf16 v[56:59], v[140:143], v[226:229], v[56:59]
	v_mfma_f32_16x16x32_bf16 v[48:51], v[168:171], v[226:229], v[48:51]
	v_mfma_f32_16x16x32_bf16 v[40:43], v[140:143], v[234:237], v[40:43]
	v_mfma_f32_16x16x32_bf16 v[32:35], v[168:171], v[234:237], v[32:35]
	v_mfma_f32_16x16x32_bf16 v[24:27], v[140:143], v[242:245], v[24:27]
	v_mfma_f32_16x16x32_bf16 v[12:15], v[168:171], v[242:245], v[12:15]
	v_mfma_f32_16x16x32_bf16 v[64:67], v[164:167], v[222:225], v[64:67]
	v_mfma_f32_16x16x32_bf16 v[60:63], v[172:175], v[222:225], v[60:63]
	v_mfma_f32_16x16x32_bf16 v[56:59], v[164:167], v[230:233], v[56:59]
	v_mfma_f32_16x16x32_bf16 v[48:51], v[172:175], v[230:233], v[48:51]
	v_mfma_f32_16x16x32_bf16 v[40:43], v[164:167], v[238:241], v[40:43]
	v_mfma_f32_16x16x32_bf16 v[32:35], v[172:175], v[238:241], v[32:35]
	v_mfma_f32_16x16x32_bf16 v[24:27], v[164:167], v[246:249], v[24:27]
	v_mfma_f32_16x16x32_bf16 v[12:15], v[172:175], v[246:249], v[12:15]
	v_mfma_f32_16x16x32_bf16 v[52:55], v[198:201], v[218:221], v[52:55]
	v_mfma_f32_16x16x32_bf16 v[44:47], v[206:209], v[218:221], v[44:47]
	v_mfma_f32_16x16x32_bf16 v[36:39], v[198:201], v[226:229], v[36:39]
	v_mfma_f32_16x16x32_bf16 v[28:31], v[206:209], v[226:229], v[28:31]
	v_mfma_f32_16x16x32_bf16 v[20:23], v[198:201], v[234:237], v[20:23]
	v_mfma_f32_16x16x32_bf16 v[8:11], v[206:209], v[234:237], v[8:11]
	v_mfma_f32_16x16x32_bf16 v[4:7], v[198:201], v[242:245], v[4:7]
	v_mfma_f32_16x16x32_bf16 v[0:3], v[206:209], v[242:245], v[0:3]
	v_mfma_f32_16x16x32_bf16 v[52:55], v[202:205], v[222:225], v[52:55]
	v_mfma_f32_16x16x32_bf16 v[44:47], v[210:213], v[222:225], v[44:47]
	v_mfma_f32_16x16x32_bf16 v[36:39], v[202:205], v[230:233], v[36:39]
	v_mfma_f32_16x16x32_bf16 v[28:31], v[210:213], v[230:233], v[28:31]
	v_mfma_f32_16x16x32_bf16 v[20:23], v[202:205], v[238:241], v[20:23]
	v_mfma_f32_16x16x32_bf16 v[8:11], v[210:213], v[238:241], v[8:11]
	v_mfma_f32_16x16x32_bf16 v[4:7], v[202:205], v[246:249], v[4:7]
	v_mfma_f32_16x16x32_bf16 v[0:3], v[210:213], v[246:249], v[0:3]
	s_setprio 0
	s_barrier
	s_add_i32 s60, s60, 2
	s_add_u32 s50, s50, 0x100
	s_addc_u32 s51, s51, 0
	s_add_u32 s30, s30, 0x100
	s_addc_u32 s45, s45, 0
	s_cmp_gt_u32 s60, 13
	s_cbranch_scc0 .LBB0_458
	s_and_b64 vcc, exec, s[36:37]
	s_cbranch_vccz .LBB0_461
	s_barrier

; #define PG8_STAGE(bufoff, gbase, voff) do { _Pragma("unroll") for (int _i = 0; _i < 2; ++_i) \
;         __builtin_amdgcn_global_load_lds((const unsigned*)((const char*)(gbase) + (voff)[_i]), (LAS unsigned*)(lds + (bufoff) + ldsw + _i * 8192), 16, 0, 0); } while (0)
; #define PG8_LDA(dst, b, h) do { _Pragma("unroll") for (int m = 0; m < 4; ++m) _Pragma("unroll") for (int k = 0; k < 2; ++k) dst[m][k] = *(const LAS bf16x8*)(lds + PG8_SA(b, h) + aoff + m * 2048 + k * 1024); } while (0)
; #define PG8_LDB(dst, b, h) do { _Pragma("unroll") for (int n = 0; n < 2; ++n) _Pragma("unroll") for (int k = 0; k < 2; ++k) dst[n][k] = *(const LAS bf16x8*)(lds + PG8_SB(b, h) + boff + n * 2048 + k * 1024); } while (0)
; #define PG8_MMA(ai, bj, At, Bt) do { __builtin_amdgcn_s_setprio(1); _Pragma("unroll") for (int m = 0; m < 4; ++m) _Pragma("unroll") for (int n = 0; n < 2; ++n) _Pragma("unroll") for (int k = 0; k < 2; ++k) \
;         acc[ai][bj][m][n] = __builtin_amdgcn_mfma_f32_16x16x32_bf16(Bt[n][k], At[m][k], acc[ai][bj][m][n], 0, 0, 0); __builtin_amdgcn_s_setprio(0); } while (0)
; template <class Epi, class Sched, bool ALIGN_EPI = true, bool SP2 = true>
; __device__ __forceinline__ void gemm_phase(LAS unsigned char* lds, const Gemm g, const Sched& S, const Epi& E) {
;     ...
;         for (int t = 0; t < nt; t += 2) {
;             const bool last = (t == nt - 2);
;             const char* a1 = cA + (size_t)(t + 1) * kstep;
;             const char* a2 = last ? nA : cA + (size_t)(t + 2) * kstep; const char* b2 = last ? nB : cB + (size_t)(t + 2) * kstep;
;             const char* a3 = a2 + kstep; const char* b3 = b2 + kstep;
;             PG8_LDB(B0, 0, 0); PG8_LDB(B1, 0, 1); PG8_SCHED; PG8_LDA(At, 0, 0); PG8_STAGE(PG8_SA(1, 1), a1 + hstepA, voffA);
;             PG8_WAIT_V(8); PG8_WAIT_L(0); PG8_BAR; PG8_MMA(0, 0, At, B0); PG8_MMA(0, 1, At, B1); PG8_BAR; PG8_SCHED;
;             PG8_LDA(At, 0, 1); PG8_STAGE(PG8_SB(0, 0), b2, voffB); PG8_STAGE(PG8_SB(0, 1), b2 + hstepB, voffB); PG8_STAGE(PG8_SA(0, 0), a2, voffA);
;             PG8_WAIT_V(8); PG8_WAIT_L(0); PG8_BAR; PG8_MMA(1, 0, At, B0); PG8_MMA(1, 1, At, B1); PG8_BAR; PG8_SCHED;
;             PG8_LDB(B0, 1, 0); PG8_LDB(B1, 1, 1); PG8_SCHED; PG8_LDA(At, 1, 0); PG8_STAGE(PG8_SA(0, 1), a2 + hstepA, voffA);
;             PG8_WAIT_V(8); PG8_WAIT_L(0); PG8_BAR; PG8_MMA(0, 0, At, B0); PG8_MMA(0, 1, At, B1); PG8_BAR; PG8_SCHED;
.LBB0_627:
	s_add_i32 s42, 0, 0x10000
	s_add_i32 s30, 0, 0x14000
	v_add_u32_e32 v8, s42, v166
	v_add_u32_e32 v9, s30, v166
	ds_read_b128 v[10:13], v8
	ds_read_b128 v[20:23], v8 offset:1024
	ds_read_b128 v[24:27], v8 offset:2048
	ds_read_b128 v[28:31], v8 offset:3072
	ds_read_b128 v[32:35], v9
	ds_read_b128 v[36:39], v9 offset:1024
	ds_read_b128 v[40:43], v9 offset:2048
	ds_read_b128 v[44:47], v9 offset:3072
	s_add_u32 s8, s16, 0x30080
	s_addc_u32 s9, s17, 0
	s_add_i32 s58, s22, 0xc000
	v_lshl_add_u64 v[14:15], s[8:9], 0, v[16:17]
	s_mov_b32 m0, s58
	s_add_i32 s2, s22, 0xe000
	ds_read_b128 v[0:3], v167
	ds_read_b128 v[4:7], v167 offset:1024
	ds_read_b128 v[48:51], v167 offset:2048
	ds_read_b128 v[52:55], v167 offset:3072
	ds_read_b128 v[56:59], v167 offset:4096
	ds_read_b128 v[60:63], v167 offset:5120
	ds_read_b128 v[64:67], v167 offset:6144
	s_waitcnt vmcnt(0)
	ds_read_b128 v[68:71], v167 offset:7168
	global_load_lds_dwordx4 v[14:15], off
	v_lshl_add_u64 v[14:15], s[8:9], 0, v[134:135]
	s_mov_b32 m0, s2
	s_nop 0
	global_load_lds_dwordx4 v[14:15], off
	s_waitcnt vmcnt(8)
	s_waitcnt lgkmcnt(0)
	s_barrier
	s_setprio 1
	s_waitcnt lgkmcnt(0)
	v_mfma_f32_16x16x32_bf16 v[72:75], v[10:13], v[0:3], 0
	v_mfma_f32_16x16x32_bf16 v[76:79], v[24:27], v[0:3], 0
	v_mfma_f32_16x16x32_bf16 v[80:83], v[10:13], v[48:51], 0
	v_mfma_f32_16x16x32_bf16 v[84:87], v[24:27], v[48:51], 0
	v_mfma_f32_16x16x32_bf16 v[88:91], v[10:13], v[56:59], 0
	v_mfma_f32_16x16x32_bf16 v[92:95], v[24:27], v[56:59], 0
	v_mfma_f32_16x16x32_bf16 v[96:99], v[10:13], v[64:67], 0
	v_mfma_f32_16x16x32_bf16 v[100:103], v[24:27], v[64:67], 0
	v_mfma_f32_16x16x32_bf16 v[72:75], v[20:23], v[4:7], v[72:75]
	v_mfma_f32_16x16x32_bf16 v[76:79], v[28:31], v[4:7], v[76:79]
	v_mfma_f32_16x16x32_bf16 v[80:83], v[20:23], v[52:55], v[80:83]
	v_mfma_f32_16x16x32_bf16 v[84:87], v[28:31], v[52:55], v[84:87]
	v_mfma_f32_16x16x32_bf16 v[88:91], v[20:23], v[60:63], v[88:91]
	v_mfma_f32_16x16x32_bf16 v[92:95], v[28:31], v[60:63], v[92:95]
	v_mfma_f32_16x16x32_bf16 v[96:99], v[20:23], v[68:71], v[96:99]
	v_mfma_f32_16x16x32_bf16 v[100:103], v[28:31], v[68:71], v[100:103]
	v_mfma_f32_16x16x32_bf16 v[104:107], v[32:35], v[0:3], 0
	v_mfma_f32_16x16x32_bf16 v[0:3], v[40:43], v[0:3], 0
	v_mfma_f32_16x16x32_bf16 v[108:111], v[44:47], v[4:7], v[0:3]
	v_mfma_f32_16x16x32_bf16 v[0:3], v[32:35], v[48:51], 0
	v_mfma_f32_16x16x32_bf16 v[112:115], v[36:39], v[52:55], v[0:3]
	v_mfma_f32_16x16x32_bf16 v[0:3], v[40:43], v[48:51], 0
	v_mfma_f32_16x16x32_bf16 v[48:51], v[44:47], v[52:55], v[0:3]
	v_mfma_f32_16x16x32_bf16 v[0:3], v[32:35], v[56:59], 0
	v_mfma_f32_16x16x32_bf16 v[52:55], v[36:39], v[60:63], v[0:3]
	v_mfma_f32_16x16x32_bf16 v[0:3], v[40:43], v[56:59], 0
	v_mfma_f32_16x16x32_bf16 v[56:59], v[44:47], v[60:63], v[0:3]
	v_mfma_f32_16x16x32_bf16 v[0:3], v[32:35], v[64:67], 0
	v_mfma_f32_16x16x32_bf16 v[60:63], v[36:39], v[68:71], v[0:3]
	v_mfma_f32_16x16x32_bf16 v[0:3], v[40:43], v[64:67], 0
	v_mfma_f32_16x16x32_bf16 v[104:107], v[36:39], v[4:7], v[104:107]
	v_mfma_f32_16x16x32_bf16 v[64:67], v[44:47], v[68:71], v[0:3]
	s_setprio 0
	s_barrier
	s_nop 3
	v_lshl_add_u64 v[0:1], s[44:45], 0, v[132:133]
	s_mov_b64 s[64:65], 0x100
	s_add_i32 s42, s42, s21
	v_lshl_add_u64 v[2:3], v[0:1], 0, s[64:65]
	s_mov_b32 m0, s42
	s_add_i32 s8, s42, 0x2000
	ds_read_b128 v[68:71], v167 offset:16384
	ds_read_b128 v[116:119], v167 offset:17408
	ds_read_b128 v[120:123], v167 offset:18432
	s_waitcnt vmcnt(0)
	ds_read_b128 v[124:127], v167 offset:19456
	ds_read_b128 v[128:131], v167 offset:20480
	ds_read_b128 v[138:141], v167 offset:21504
	ds_read_b128 v[142:145], v167 offset:22528
	ds_read_b128 v[168:171], v167 offset:23552
	global_load_lds_dwordx4 v[2:3], off
	v_lshl_add_u64 v[2:3], s[44:45], 0, v[136:137]
	s_add_u32 s60, s44, 0x18100
	v_lshl_add_u64 v[4:5], v[2:3], 0, s[64:65]
	s_mov_b32 m0, s8
	s_addc_u32 s61, s45, 0
	s_add_i32 s9, s30, s21
	global_load_lds_dwordx4 v[4:5], off
	v_lshl_add_u64 v[4:5], s[60:61], 0, v[132:133]
	s_mov_b32 m0, s9
	s_add_i32 s30, s9, 0x2000
	global_load_lds_dwordx4 v[4:5], off
	v_lshl_add_u64 v[4:5], s[60:61], 0, v[136:137]
	s_mov_b32 m0, s30
	s_nop 0
	global_load_lds_dwordx4 v[4:5], off
	v_lshl_add_u64 v[4:5], s[16:17], 0, v[16:17]
	v_lshl_add_u64 v[6:7], v[4:5], 0, s[64:65]
	s_mov_b32 m0, s22
	s_nop 0
	global_load_lds_dwordx4 v[6:7], off
	v_lshl_add_u64 v[6:7], s[16:17], 0, v[134:135]
	v_lshl_add_u64 v[14:15], v[6:7], 0, s[64:65]
	s_mov_b32 m0, s23
	s_nop 0
	global_load_lds_dwordx4 v[14:15], off
	s_waitcnt vmcnt(8)
	s_waitcnt lgkmcnt(0)
	s_barrier
	s_setprio 1
	s_waitcnt lgkmcnt(0)
	v_mfma_f32_16x16x32_bf16 v[172:175], v[10:13], v[68:71], 0
	v_mfma_f32_16x16x32_bf16 v[202:205], v[10:13], v[120:123], 0
	v_mfma_f32_16x16x32_bf16 v[210:213], v[10:13], v[128:131], 0
	v_mfma_f32_16x16x32_bf16 v[10:13], v[10:13], v[142:145], 0
	v_mfma_f32_16x16x32_bf16 v[172:175], v[20:23], v[116:119], v[172:175]
	v_mfma_f32_16x16x32_bf16 v[202:205], v[20:23], v[124:127], v[202:205]
	v_mfma_f32_16x16x32_bf16 v[210:213], v[20:23], v[138:141], v[210:213]
	v_mfma_f32_16x16x32_bf16 v[12:15], v[20:23], v[168:171], v[10:13]
	v_mfma_f32_16x16x32_bf16 v[20:23], v[24:27], v[142:145], 0
	v_mfma_f32_16x16x32_bf16 v[198:201], v[24:27], v[68:71], 0
	v_mfma_f32_16x16x32_bf16 v[206:209], v[24:27], v[120:123], 0
	v_mfma_f32_16x16x32_bf16 v[218:221], v[24:27], v[128:131], 0
	v_mfma_f32_16x16x32_bf16 v[20:23], v[28:31], v[168:171], v[20:23]
	v_mfma_f32_16x16x32_bf16 v[198:201], v[28:31], v[116:119], v[198:201]
	v_mfma_f32_16x16x32_bf16 v[206:209], v[28:31], v[124:127], v[206:209]
	v_mfma_f32_16x16x32_bf16 v[218:221], v[28:31], v[138:141], v[218:221]
	v_mfma_f32_16x16x32_bf16 v[24:27], v[32:35], v[68:71], 0
	v_mfma_f32_16x16x32_bf16 v[28:31], v[40:43], v[68:71], 0
	v_mfma_f32_16x16x32_bf16 v[24:27], v[36:39], v[116:119], v[24:27]
	v_mfma_f32_16x16x32_bf16 v[28:31], v[44:47], v[116:119], v[28:31]
	v_mfma_f32_16x16x32_bf16 v[68:71], v[32:35], v[120:123], 0
	v_mfma_f32_16x16x32_bf16 v[116:119], v[40:43], v[120:123], 0
	v_mfma_f32_16x16x32_bf16 v[120:123], v[32:35], v[128:131], 0
	v_mfma_f32_16x16x32_bf16 v[32:35], v[32:35], v[142:145], 0
	v_mfma_f32_16x16x32_bf16 v[68:71], v[36:39], v[124:127], v[68:71]
	v_mfma_f32_16x16x32_bf16 v[116:119], v[44:47], v[124:127], v[116:119]
	v_mfma_f32_16x16x32_bf16 v[120:123], v[36:39], v[138:141], v[120:123]
	v_mfma_f32_16x16x32_bf16 v[124:127], v[40:43], v[128:131], 0
	v_mfma_f32_16x16x32_bf16 v[32:35], v[36:39], v[168:171], v[32:35]
	v_mfma_f32_16x16x32_bf16 v[36:39], v[40:43], v[142:145], 0
	v_mfma_f32_16x16x32_bf16 v[124:127], v[44:47], v[138:141], v[124:127]
	v_mfma_f32_16x16x32_bf16 v[36:39], v[44:47], v[168:171], v[36:39]
	s_setprio 0
	s_barrier
; #define PG8_STAGE(bufoff, gbase, voff) do { _Pragma("unroll") for (int _i = 0; _i < 2; ++_i) \
;         __builtin_amdgcn_global_load_lds((const unsigned*)((const char*)(gbase) + (voff)[_i]), (LAS unsigned*)(lds + (bufoff) + ldsw + _i * 8192), 16, 0, 0); } while (0)
; #define PG8_LDA(dst, b, h) do { _Pragma("unroll") for (int m = 0; m < 4; ++m) _Pragma("unroll") for (int k = 0; k < 2; ++k) dst[m][k] = *(const LAS bf16x8*)(lds + PG8_SA(b, h) + aoff + m * 2048 + k * 1024); } while (0)
; #define PG8_LDB(dst, b, h) do { _Pragma("unroll") for (int n = 0; n < 2; ++n) _Pragma("unroll") for (int k = 0; k < 2; ++k) dst[n][k] = *(const LAS bf16x8*)(lds + PG8_SB(b, h) + boff + n * 2048 + k * 1024); } while (0)
; #define PG8_MMA(ai, bj, At, Bt) do { __builtin_amdgcn_s_setprio(1); _Pragma("unroll") for (int m = 0; m < 4; ++m) _Pragma("unroll") for (int n = 0; n < 2; ++n) _Pragma("unroll") for (int k = 0; k < 2; ++k) \
;         acc[ai][bj][m][n] = __builtin_amdgcn_mfma_f32_16x16x32_bf16(Bt[n][k], At[m][k], acc[ai][bj][m][n], 0, 0, 0); __builtin_amdgcn_s_setprio(0); } while (0)
; #define PG8_WAIT_V(n) asm volatile("s_waitcnt vmcnt(" #n ")" ::: "memory")
; template <class Epi, class Sched, bool ALIGN_EPI = true, bool SP2 = true>
; __device__ __forceinline__ void gemm_phase(LAS unsigned char* lds, const Gemm g, const Sched& S, const Epi& E) {
;     ...
;             PG8_LDB(B0, 0, 0); PG8_LDB(B1, 0, 1); PG8_SCHED; PG8_LDA(At, 0, 0); PG8_STAGE(PG8_SA(1, 1), a1 + hstepA, voffA);
;             PG8_WAIT_V(8); PG8_WAIT_L(0); PG8_BAR; PG8_MMA(0, 0, At, B0); PG8_MMA(0, 1, At, B1); PG8_BAR; PG8_SCHED;
;             PG8_LDA(At, 0, 1); PG8_STAGE(PG8_SB(0, 0), b2, voffB); PG8_STAGE(PG8_SB(0, 1), b2 + hstepB, voffB); PG8_STAGE(PG8_SA(0, 0), a2, voffA);
;             PG8_WAIT_V(8); PG8_WAIT_L(0); PG8_BAR; PG8_MMA(1, 0, At, B0); PG8_MMA(1, 1, At, B1); PG8_BAR; PG8_SCHED;
;             PG8_LDB(B0, 1, 0); PG8_LDB(B1, 1, 1); PG8_SCHED; PG8_LDA(At, 1, 0); PG8_STAGE(PG8_SA(0, 1), a2 + hstepA, voffA);
;             PG8_WAIT_V(8); PG8_WAIT_L(0); PG8_BAR; PG8_MMA(0, 0, At, B0); PG8_MMA(0, 1, At, B1); PG8_BAR; PG8_SCHED;
;             PG8_LDA(At, 1, 1); PG8_STAGE(PG8_SB(1, 0), b3, voffB); PG8_STAGE(PG8_SB(1, 1), b3 + hstepB, voffB); PG8_STAGE(PG8_SA(1, 0), a3, voffA);
;             PG8_WAIT_V(8); PG8_WAIT_L(0); PG8_BAR; PG8_MMA(1, 0, At, B0); PG8_MMA(1, 1, At, B1); PG8_BAR; PG8_SCHED;
	s_add_i32 s43, 0, 0x18000
	s_add_i32 s57, 0, 0x1c000
	v_add_u32_e32 v10, s43, v166
	v_add_u32_e32 v11, s57, v166
	ds_read_b128 v[40:43], v10
	ds_read_b128 v[44:47], v10 offset:1024
	ds_read_b128 v[128:131], v10 offset:2048
	ds_read_b128 v[138:141], v10 offset:3072
	ds_read_b128 v[142:145], v11
	ds_read_b128 v[168:171], v11 offset:1024
	ds_read_b128 v[222:225], v11 offset:2048
	ds_read_b128 v[226:229], v11 offset:3072
	s_add_u32 s60, s16, 0x30100
	s_addc_u32 s61, s17, 0
	s_mov_b32 m0, s24
	v_lshl_add_u64 v[154:155], s[60:61], 0, v[16:17]
	ds_read_b128 v[230:233], v167 offset:32768
	ds_read_b128 v[234:237], v167 offset:33792
	ds_read_b128 v[238:241], v167 offset:34816
	ds_read_b128 v[242:245], v167 offset:35840
	ds_read_b128 v[246:249], v167 offset:36864
	ds_read_b128 v[250:253], v167 offset:37888
	ds_read_b128 v[146:149], v167 offset:38912
	ds_read_b128 v[150:153], v167 offset:39936
	global_load_lds_dwordx4 v[154:155], off
	v_lshl_add_u64 v[154:155], s[60:61], 0, v[134:135]
	s_mov_b32 m0, s31
	s_nop 0
	global_load_lds_dwordx4 v[154:155], off
	s_waitcnt vmcnt(8)
	s_waitcnt lgkmcnt(0)
	s_barrier
	s_setprio 1
	s_waitcnt lgkmcnt(0)
	v_mfma_f32_16x16x32_bf16 v[72:75], v[40:43], v[230:233], v[72:75]
	v_mfma_f32_16x16x32_bf16 v[76:79], v[128:131], v[230:233], v[76:79]
	v_mfma_f32_16x16x32_bf16 v[80:83], v[40:43], v[238:241], v[80:83]
	v_mfma_f32_16x16x32_bf16 v[84:87], v[128:131], v[238:241], v[84:87]
	v_mfma_f32_16x16x32_bf16 v[88:91], v[40:43], v[246:249], v[88:91]
	v_mfma_f32_16x16x32_bf16 v[92:95], v[128:131], v[246:249], v[92:95]
	v_mfma_f32_16x16x32_bf16 v[96:99], v[40:43], v[146:149], v[96:99]
	v_mfma_f32_16x16x32_bf16 v[100:103], v[128:131], v[146:149], v[100:103]
	v_mfma_f32_16x16x32_bf16 v[72:75], v[44:47], v[234:237], v[72:75]
	v_mfma_f32_16x16x32_bf16 v[76:79], v[138:141], v[234:237], v[76:79]
	v_mfma_f32_16x16x32_bf16 v[80:83], v[44:47], v[242:245], v[80:83]
	v_mfma_f32_16x16x32_bf16 v[84:87], v[138:141], v[242:245], v[84:87]
	v_mfma_f32_16x16x32_bf16 v[88:91], v[44:47], v[250:253], v[88:91]
	v_mfma_f32_16x16x32_bf16 v[92:95], v[138:141], v[250:253], v[92:95]
	v_mfma_f32_16x16x32_bf16 v[96:99], v[44:47], v[150:153], v[96:99]
	v_mfma_f32_16x16x32_bf16 v[100:103], v[138:141], v[150:153], v[100:103]
	v_mfma_f32_16x16x32_bf16 v[104:107], v[142:145], v[230:233], v[104:107]
	v_mfma_f32_16x16x32_bf16 v[108:111], v[222:225], v[230:233], v[108:111]
	v_mfma_f32_16x16x32_bf16 v[112:115], v[142:145], v[238:241], v[112:115]
	v_mfma_f32_16x16x32_bf16 v[48:51], v[222:225], v[238:241], v[48:51]
	v_mfma_f32_16x16x32_bf16 v[52:55], v[142:145], v[246:249], v[52:55]
	v_mfma_f32_16x16x32_bf16 v[56:59], v[222:225], v[246:249], v[56:59]
	v_mfma_f32_16x16x32_bf16 v[60:63], v[142:145], v[146:149], v[60:63]
	v_mfma_f32_16x16x32_bf16 v[64:67], v[222:225], v[146:149], v[64:67]
	v_mfma_f32_16x16x32_bf16 v[104:107], v[168:171], v[234:237], v[104:107]
	v_mfma_f32_16x16x32_bf16 v[108:111], v[226:229], v[234:237], v[108:111]
	v_mfma_f32_16x16x32_bf16 v[112:115], v[168:171], v[242:245], v[112:115]
	v_mfma_f32_16x16x32_bf16 v[48:51], v[226:229], v[242:245], v[48:51]
	v_mfma_f32_16x16x32_bf16 v[52:55], v[168:171], v[250:253], v[52:55]
	v_mfma_f32_16x16x32_bf16 v[56:59], v[226:229], v[250:253], v[56:59]
	v_mfma_f32_16x16x32_bf16 v[60:63], v[168:171], v[150:153], v[60:63]
	v_mfma_f32_16x16x32_bf16 v[64:67], v[226:229], v[150:153], v[64:67]
	s_setprio 0
	s_barrier
	s_add_i32 s61, s43, s21
	s_mov_b64 vcc, 0x180
	s_add_i32 s43, s61, 0x2000
	v_lshl_add_u64 v[154:155], v[0:1], 0, vcc
	s_mov_b32 m0, s61
	s_add_u32 s64, s44, 0x18180
	ds_read_b128 v[146:149], v167 offset:49152
	ds_read_b128 v[150:153], v167 offset:50176
	ds_read_b128 v[230:233], v167 offset:51200
	ds_read_b128 v[234:237], v167 offset:52224
	ds_read_b128 v[238:241], v167 offset:53248
	ds_read_b128 v[242:245], v167 offset:54272
	ds_read_b128 v[246:249], v167 offset:55296
	ds_read_b128 v[250:253], v167 offset:56320
	global_load_lds_dwordx4 v[154:155], off
	v_lshl_add_u64 v[154:155], v[2:3], 0, vcc
	s_mov_b32 m0, s43
	s_addc_u32 s65, s45, 0
	s_add_i32 s57, s57, s21
	global_load_lds_dwordx4 v[154:155], off
	v_lshl_add_u64 v[154:155], s[64:65], 0, v[132:133]
	s_mov_b32 m0, s57
	s_add_i32 s59, s57, 0x2000
	global_load_lds_dwordx4 v[154:155], off
	v_lshl_add_u64 v[154:155], s[64:65], 0, v[136:137]
	s_mov_b32 m0, s59
	s_nop 0
	global_load_lds_dwordx4 v[154:155], off
	v_lshl_add_u64 v[154:155], v[4:5], 0, vcc
	s_mov_b32 m0, s52
	s_nop 0
	global_load_lds_dwordx4 v[154:155], off
	v_lshl_add_u64 v[154:155], v[6:7], 0, vcc
	s_mov_b32 m0, s53
	s_nop 0
	global_load_lds_dwordx4 v[154:155], off
	s_waitcnt vmcnt(8)
	s_waitcnt lgkmcnt(0)
	s_barrier
; #define PG8_STAGE(bufoff, gbase, voff) do { _Pragma("unroll") for (int _i = 0; _i < 2; ++_i) \
;         __builtin_amdgcn_global_load_lds((const unsigned*)((const char*)(gbase) + (voff)[_i]), (LAS unsigned*)(lds + (bufoff) + ldsw + _i * 8192), 16, 0, 0); } while (0)
; #define PG8_LDA(dst, b, h) do { _Pragma("unroll") for (int m = 0; m < 4; ++m) _Pragma("unroll") for (int k = 0; k < 2; ++k) dst[m][k] = *(const LAS bf16x8*)(lds + PG8_SA(b, h) + aoff + m * 2048 + k * 1024); } while (0)
; #define PG8_LDB(dst, b, h) do { _Pragma("unroll") for (int n = 0; n < 2; ++n) _Pragma("unroll") for (int k = 0; k < 2; ++k) dst[n][k] = *(const LAS bf16x8*)(lds + PG8_SB(b, h) + boff + n * 2048 + k * 1024); } while (0)
; #define PG8_MMA(ai, bj, At, Bt) do { __builtin_amdgcn_s_setprio(1); _Pragma("unroll") for (int m = 0; m < 4; ++m) _Pragma("unroll") for (int n = 0; n < 2; ++n) _Pragma("unroll") for (int k = 0; k < 2; ++k) \
;         acc[ai][bj][m][n] = __builtin_amdgcn_mfma_f32_16x16x32_bf16(Bt[n][k], At[m][k], acc[ai][bj][m][n], 0, 0, 0); __builtin_amdgcn_s_setprio(0); } while (0)
; #define PG8_WAIT_V(n) asm volatile("s_waitcnt vmcnt(" #n ")" ::: "memory")
; template <class Epi, class Sched, bool ALIGN_EPI = true, bool SP2 = true>
; __device__ __forceinline__ void gemm_phase(LAS unsigned char* lds, const Gemm g, const Sched& S, const Epi& E) {
;     ...
;             PG8_LDB(B0, 0, 0); PG8_LDB(B1, 0, 1); PG8_SCHED; PG8_LDA(At, 0, 0); PG8_STAGE(PG8_SA(1, 1), a1 + hstepA, voffA);
;             PG8_WAIT_V(8); PG8_WAIT_L(0); PG8_BAR; PG8_MMA(0, 0, At, B0); PG8_MMA(0, 1, At, B1); PG8_BAR; PG8_SCHED;
;             PG8_LDA(At, 0, 1); PG8_STAGE(PG8_SB(0, 0), b2, voffB); PG8_STAGE(PG8_SB(0, 1), b2 + hstepB, voffB); PG8_STAGE(PG8_SA(0, 0), a2, voffA);
;             PG8_WAIT_V(8); PG8_WAIT_L(0); PG8_BAR; PG8_MMA(1, 0, At, B0); PG8_MMA(1, 1, At, B1); PG8_BAR; PG8_SCHED;
;             PG8_LDB(B0, 1, 0); PG8_LDB(B1, 1, 1); PG8_SCHED; PG8_LDA(At, 1, 0); PG8_STAGE(PG8_SA(0, 1), a2 + hstepA, voffA);
;             PG8_WAIT_V(8); PG8_WAIT_L(0); PG8_BAR; PG8_MMA(0, 0, At, B0); PG8_MMA(0, 1, At, B1); PG8_BAR; PG8_SCHED;
;             PG8_LDA(At, 1, 1); PG8_STAGE(PG8_SB(1, 0), b3, voffB); PG8_STAGE(PG8_SB(1, 1), b3 + hstepB, voffB); PG8_STAGE(PG8_SA(1, 0), a3, voffA);
;             PG8_WAIT_V(8); PG8_WAIT_L(0); PG8_BAR; PG8_MMA(1, 0, At, B0); PG8_MMA(1, 1, At, B1); PG8_BAR; PG8_SCHED;
	s_setprio 1
	s_waitcnt lgkmcnt(0)
	v_mfma_f32_16x16x32_bf16 v[12:15], v[40:43], v[246:249], v[12:15]
	v_mfma_f32_16x16x32_bf16 v[20:23], v[128:131], v[246:249], v[20:23]
	v_mfma_f32_16x16x32_bf16 v[172:175], v[40:43], v[146:149], v[172:175]
	v_mfma_f32_16x16x32_bf16 v[198:201], v[128:131], v[146:149], v[198:201]
	v_mfma_f32_16x16x32_bf16 v[202:205], v[40:43], v[230:233], v[202:205]
	v_mfma_f32_16x16x32_bf16 v[206:209], v[128:131], v[230:233], v[206:209]
	v_mfma_f32_16x16x32_bf16 v[210:213], v[40:43], v[238:241], v[210:213]
	v_mfma_f32_16x16x32_bf16 v[218:221], v[128:131], v[238:241], v[218:221]
	v_mfma_f32_16x16x32_bf16 v[12:15], v[44:47], v[250:253], v[12:15]
	v_mfma_f32_16x16x32_bf16 v[20:23], v[138:141], v[250:253], v[20:23]
	v_mfma_f32_16x16x32_bf16 v[172:175], v[44:47], v[150:153], v[172:175]
	v_mfma_f32_16x16x32_bf16 v[198:201], v[138:141], v[150:153], v[198:201]
	v_mfma_f32_16x16x32_bf16 v[202:205], v[44:47], v[234:237], v[202:205]
	v_mfma_f32_16x16x32_bf16 v[206:209], v[138:141], v[234:237], v[206:209]
	v_mfma_f32_16x16x32_bf16 v[210:213], v[44:47], v[242:245], v[210:213]
	v_mfma_f32_16x16x32_bf16 v[218:221], v[138:141], v[242:245], v[218:221]
	v_mfma_f32_16x16x32_bf16 v[24:27], v[142:145], v[146:149], v[24:27]
	v_mfma_f32_16x16x32_bf16 v[28:31], v[222:225], v[146:149], v[28:31]
	v_mfma_f32_16x16x32_bf16 v[40:43], v[142:145], v[230:233], v[68:71]
	v_mfma_f32_16x16x32_bf16 v[44:47], v[222:225], v[230:233], v[116:119]
	v_mfma_f32_16x16x32_bf16 v[68:71], v[142:145], v[238:241], v[120:123]
	v_mfma_f32_16x16x32_bf16 v[116:119], v[222:225], v[238:241], v[124:127]
	v_mfma_f32_16x16x32_bf16 v[32:35], v[142:145], v[246:249], v[32:35]
	v_mfma_f32_16x16x32_bf16 v[36:39], v[222:225], v[246:249], v[36:39]
	v_mfma_f32_16x16x32_bf16 v[24:27], v[168:171], v[150:153], v[24:27]
	v_mfma_f32_16x16x32_bf16 v[28:31], v[226:229], v[150:153], v[28:31]
	v_mfma_f32_16x16x32_bf16 v[40:43], v[168:171], v[234:237], v[40:43]
	v_mfma_f32_16x16x32_bf16 v[44:47], v[226:229], v[234:237], v[44:47]
	v_mfma_f32_16x16x32_bf16 v[68:71], v[168:171], v[242:245], v[68:71]
	v_mfma_f32_16x16x32_bf16 v[116:119], v[226:229], v[242:245], v[116:119]
	v_mfma_f32_16x16x32_bf16 v[32:35], v[168:171], v[250:253], v[32:35]
	v_mfma_f32_16x16x32_bf16 v[36:39], v[226:229], v[250:253], v[36:39]
	s_setprio 0
	s_barrier
	ds_read_b128 v[120:123], v8
	ds_read_b128 v[124:127], v8 offset:1024
	ds_read_b128 v[128:131], v8 offset:2048
	ds_read_b128 v[138:141], v8 offset:3072
	ds_read_b128 v[142:145], v9
	ds_read_b128 v[146:149], v9 offset:1024
	ds_read_b128 v[150:153], v9 offset:2048
	ds_read_b128 v[168:171], v9 offset:3072
	s_add_u32 s64, s16, 0x30180
	s_addc_u32 s65, s17, 0
	s_mov_b32 m0, s58
	v_lshl_add_u64 v[154:155], s[64:65], 0, v[16:17]
	ds_read_b128 v[222:225], v167
	ds_read_b128 v[226:229], v167 offset:1024
	ds_read_b128 v[230:233], v167 offset:2048
	ds_read_b128 v[234:237], v167 offset:3072
	ds_read_b128 v[238:241], v167 offset:4096
	ds_read_b128 v[242:245], v167 offset:5120
	ds_read_b128 v[246:249], v167 offset:6144
	ds_read_b128 v[250:253], v167 offset:7168
	global_load_lds_dwordx4 v[154:155], off
	v_lshl_add_u64 v[154:155], s[64:65], 0, v[134:135]
	s_mov_b32 m0, s2
	s_nop 0
	global_load_lds_dwordx4 v[154:155], off
	s_waitcnt vmcnt(8)
	s_waitcnt lgkmcnt(0)
	s_barrier
	s_setprio 1
	s_waitcnt lgkmcnt(0)
	v_mfma_f32_16x16x32_bf16 v[72:75], v[120:123], v[222:225], v[72:75]
	v_mfma_f32_16x16x32_bf16 v[76:79], v[128:131], v[222:225], v[76:79]
	v_mfma_f32_16x16x32_bf16 v[80:83], v[120:123], v[230:233], v[80:83]
	v_mfma_f32_16x16x32_bf16 v[84:87], v[128:131], v[230:233], v[84:87]
	v_mfma_f32_16x16x32_bf16 v[88:91], v[120:123], v[238:241], v[88:91]
	v_mfma_f32_16x16x32_bf16 v[92:95], v[128:131], v[238:241], v[92:95]
	v_mfma_f32_16x16x32_bf16 v[96:99], v[120:123], v[246:249], v[96:99]
	v_mfma_f32_16x16x32_bf16 v[100:103], v[128:131], v[246:249], v[100:103]
	v_mfma_f32_16x16x32_bf16 v[72:75], v[124:127], v[226:229], v[72:75]
	v_mfma_f32_16x16x32_bf16 v[76:79], v[138:141], v[226:229], v[76:79]
	v_mfma_f32_16x16x32_bf16 v[80:83], v[124:127], v[234:237], v[80:83]
	v_mfma_f32_16x16x32_bf16 v[84:87], v[138:141], v[234:237], v[84:87]
	v_mfma_f32_16x16x32_bf16 v[88:91], v[124:127], v[242:245], v[88:91]
	v_mfma_f32_16x16x32_bf16 v[92:95], v[138:141], v[242:245], v[92:95]
	v_mfma_f32_16x16x32_bf16 v[96:99], v[124:127], v[250:253], v[96:99]
	v_mfma_f32_16x16x32_bf16 v[100:103], v[138:141], v[250:253], v[100:103]
	v_mfma_f32_16x16x32_bf16 v[104:107], v[142:145], v[222:225], v[104:107]
	v_mfma_f32_16x16x32_bf16 v[108:111], v[150:153], v[222:225], v[108:111]
	v_mfma_f32_16x16x32_bf16 v[112:115], v[142:145], v[230:233], v[112:115]
	v_mfma_f32_16x16x32_bf16 v[48:51], v[150:153], v[230:233], v[48:51]
	v_mfma_f32_16x16x32_bf16 v[52:55], v[142:145], v[238:241], v[52:55]
	v_mfma_f32_16x16x32_bf16 v[56:59], v[150:153], v[238:241], v[56:59]
	v_mfma_f32_16x16x32_bf16 v[60:63], v[142:145], v[246:249], v[60:63]
	v_mfma_f32_16x16x32_bf16 v[64:67], v[150:153], v[246:249], v[64:67]
	v_mfma_f32_16x16x32_bf16 v[104:107], v[146:149], v[226:229], v[104:107]
	v_mfma_f32_16x16x32_bf16 v[108:111], v[168:171], v[226:229], v[108:111]
	v_mfma_f32_16x16x32_bf16 v[112:115], v[146:149], v[234:237], v[112:115]
	v_mfma_f32_16x16x32_bf16 v[48:51], v[168:171], v[234:237], v[48:51]
	v_mfma_f32_16x16x32_bf16 v[52:55], v[146:149], v[242:245], v[52:55]
	v_mfma_f32_16x16x32_bf16 v[56:59], v[168:171], v[242:245], v[56:59]
	v_mfma_f32_16x16x32_bf16 v[60:63], v[146:149], v[250:253], v[60:63]
	v_mfma_f32_16x16x32_bf16 v[64:67], v[168:171], v[250:253], v[64:67]
	s_setprio 0
	s_barrier
; #define PG8_STAGE(bufoff, gbase, voff) do { _Pragma("unroll") for (int _i = 0; _i < 2; ++_i) \
;         __builtin_amdgcn_global_load_lds((const unsigned*)((const char*)(gbase) + (voff)[_i]), (LAS unsigned*)(lds + (bufoff) + ldsw + _i * 8192), 16, 0, 0); } while (0)
; #define PG8_LDA(dst, b, h) do { _Pragma("unroll") for (int m = 0; m < 4; ++m) _Pragma("unroll") for (int k = 0; k < 2; ++k) dst[m][k] = *(const LAS bf16x8*)(lds + PG8_SA(b, h) + aoff + m * 2048 + k * 1024); } while (0)
; #define PG8_LDB(dst, b, h) do { _Pragma("unroll") for (int n = 0; n < 2; ++n) _Pragma("unroll") for (int k = 0; k < 2; ++k) dst[n][k] = *(const LAS bf16x8*)(lds + PG8_SB(b, h) + boff + n * 2048 + k * 1024); } while (0)
; #define PG8_MMA(ai, bj, At, Bt) do { __builtin_amdgcn_s_setprio(1); _Pragma("unroll") for (int m = 0; m < 4; ++m) _Pragma("unroll") for (int n = 0; n < 2; ++n) _Pragma("unroll") for (int k = 0; k < 2; ++k) \
;         acc[ai][bj][m][n] = __builtin_amdgcn_mfma_f32_16x16x32_bf16(Bt[n][k], At[m][k], acc[ai][bj][m][n], 0, 0, 0); __builtin_amdgcn_s_setprio(0); } while (0)
; #define PG8_WAIT_V(n) asm volatile("s_waitcnt vmcnt(" #n ")" ::: "memory")
; template <class Epi, class Sched, bool ALIGN_EPI = true, bool SP2 = true>
; __device__ __forceinline__ void gemm_phase(LAS unsigned char* lds, const Gemm g, const Sched& S, const Epi& E) {
;     ...
;             PG8_LDB(B0, 0, 0); PG8_LDB(B1, 0, 1); PG8_SCHED; PG8_LDA(At, 0, 0); PG8_STAGE(PG8_SA(1, 1), a1 + hstepA, voffA);
;             PG8_WAIT_V(8); PG8_WAIT_L(0); PG8_BAR; PG8_MMA(0, 0, At, B0); PG8_MMA(0, 1, At, B1); PG8_BAR; PG8_SCHED;
;             PG8_LDA(At, 0, 1); PG8_STAGE(PG8_SB(0, 0), b2, voffB); PG8_STAGE(PG8_SB(0, 1), b2 + hstepB, voffB); PG8_STAGE(PG8_SA(0, 0), a2, voffA);
;             PG8_WAIT_V(8); PG8_WAIT_L(0); PG8_BAR; PG8_MMA(1, 0, At, B0); PG8_MMA(1, 1, At, B1); PG8_BAR; PG8_SCHED;
;             PG8_LDB(B0, 1, 0); PG8_LDB(B1, 1, 1); PG8_SCHED; PG8_LDA(At, 1, 0); PG8_STAGE(PG8_SA(0, 1), a2 + hstepA, voffA);
;             PG8_WAIT_V(8); PG8_WAIT_L(0); PG8_BAR; PG8_MMA(0, 0, At, B0); PG8_MMA(0, 1, At, B1); PG8_BAR; PG8_SCHED;
;             PG8_LDA(At, 1, 1); PG8_STAGE(PG8_SB(1, 0), b3, voffB); PG8_STAGE(PG8_SB(1, 1), b3 + hstepB, voffB); PG8_STAGE(PG8_SA(1, 0), a3, voffA);
;             PG8_WAIT_V(8); PG8_WAIT_L(0); PG8_BAR; PG8_MMA(1, 0, At, B0); PG8_MMA(1, 1, At, B1); PG8_BAR; PG8_SCHED;
	s_mov_b64 vcc, 0x200
	s_mov_b32 m0, s42
	v_lshl_add_u64 v[154:155], v[0:1], 0, vcc
	s_add_u32 s64, s44, 0x18200
	ds_read_b128 v[222:225], v167 offset:16384
	ds_read_b128 v[226:229], v167 offset:17408
	ds_read_b128 v[230:233], v167 offset:18432
	ds_read_b128 v[234:237], v167 offset:19456
	ds_read_b128 v[238:241], v167 offset:20480
	ds_read_b128 v[242:245], v167 offset:21504
	ds_read_b128 v[246:249], v167 offset:22528
	ds_read_b128 v[250:253], v167 offset:23552
	global_load_lds_dwordx4 v[154:155], off
	v_lshl_add_u64 v[154:155], v[2:3], 0, vcc
	s_mov_b32 m0, s8
	s_addc_u32 s65, s45, 0
	global_load_lds_dwordx4 v[154:155], off
	v_lshl_add_u64 v[154:155], s[64:65], 0, v[132:133]
	s_mov_b32 m0, s9
	s_nop 0
	global_load_lds_dwordx4 v[154:155], off
	v_lshl_add_u64 v[154:155], s[64:65], 0, v[136:137]
	s_mov_b32 m0, s30
	s_nop 0
	global_load_lds_dwordx4 v[154:155], off
	v_lshl_add_u64 v[154:155], v[4:5], 0, vcc
	s_mov_b32 m0, s22
	s_nop 0
	global_load_lds_dwordx4 v[154:155], off
	v_lshl_add_u64 v[154:155], v[6:7], 0, vcc
	s_mov_b32 m0, s23
	s_nop 0
	global_load_lds_dwordx4 v[154:155], off
	s_waitcnt vmcnt(8)
	s_waitcnt lgkmcnt(0)
	s_barrier
	s_setprio 1
	s_waitcnt lgkmcnt(0)
	v_mfma_f32_16x16x32_bf16 v[12:15], v[120:123], v[246:249], v[12:15]
	v_mfma_f32_16x16x32_bf16 v[20:23], v[128:131], v[246:249], v[20:23]
	v_mfma_f32_16x16x32_bf16 v[172:175], v[120:123], v[222:225], v[172:175]
	v_mfma_f32_16x16x32_bf16 v[198:201], v[128:131], v[222:225], v[198:201]
	v_mfma_f32_16x16x32_bf16 v[202:205], v[120:123], v[230:233], v[202:205]
	v_mfma_f32_16x16x32_bf16 v[206:209], v[128:131], v[230:233], v[206:209]
	v_mfma_f32_16x16x32_bf16 v[210:213], v[120:123], v[238:241], v[210:213]
	v_mfma_f32_16x16x32_bf16 v[218:221], v[128:131], v[238:241], v[218:221]
	v_mfma_f32_16x16x32_bf16 v[12:15], v[124:127], v[250:253], v[12:15]
	v_mfma_f32_16x16x32_bf16 v[20:23], v[138:141], v[250:253], v[20:23]
	v_mfma_f32_16x16x32_bf16 v[172:175], v[124:127], v[226:229], v[172:175]
	v_mfma_f32_16x16x32_bf16 v[198:201], v[138:141], v[226:229], v[198:201]
	v_mfma_f32_16x16x32_bf16 v[202:205], v[124:127], v[234:237], v[202:205]
	v_mfma_f32_16x16x32_bf16 v[206:209], v[138:141], v[234:237], v[206:209]
	v_mfma_f32_16x16x32_bf16 v[210:213], v[124:127], v[242:245], v[210:213]
	v_mfma_f32_16x16x32_bf16 v[218:221], v[138:141], v[242:245], v[218:221]
	v_mfma_f32_16x16x32_bf16 v[24:27], v[142:145], v[222:225], v[24:27]
	v_mfma_f32_16x16x32_bf16 v[28:31], v[150:153], v[222:225], v[28:31]
	v_mfma_f32_16x16x32_bf16 v[40:43], v[142:145], v[230:233], v[40:43]
	v_mfma_f32_16x16x32_bf16 v[44:47], v[150:153], v[230:233], v[44:47]
	v_mfma_f32_16x16x32_bf16 v[68:71], v[142:145], v[238:241], v[68:71]
	v_mfma_f32_16x16x32_bf16 v[116:119], v[150:153], v[238:241], v[116:119]
	v_mfma_f32_16x16x32_bf16 v[32:35], v[142:145], v[246:249], v[32:35]
	v_mfma_f32_16x16x32_bf16 v[36:39], v[150:153], v[246:249], v[36:39]
	v_mfma_f32_16x16x32_bf16 v[24:27], v[146:149], v[226:229], v[24:27]
	v_mfma_f32_16x16x32_bf16 v[28:31], v[168:171], v[226:229], v[28:31]
	v_mfma_f32_16x16x32_bf16 v[40:43], v[146:149], v[234:237], v[40:43]
	v_mfma_f32_16x16x32_bf16 v[44:47], v[168:171], v[234:237], v[44:47]
	v_mfma_f32_16x16x32_bf16 v[68:71], v[146:149], v[242:245], v[68:71]
	v_mfma_f32_16x16x32_bf16 v[116:119], v[168:171], v[242:245], v[116:119]
	v_mfma_f32_16x16x32_bf16 v[32:35], v[146:149], v[250:253], v[32:35]
	v_mfma_f32_16x16x32_bf16 v[36:39], v[168:171], v[250:253], v[36:39]
	s_setprio 0
	s_barrier
	ds_read_b128 v[120:123], v10
	ds_read_b128 v[124:127], v10 offset:1024
	ds_read_b128 v[128:131], v10 offset:2048
	ds_read_b128 v[138:141], v10 offset:3072
	ds_read_b128 v[142:145], v11
	ds_read_b128 v[146:149], v11 offset:1024
	ds_read_b128 v[150:153], v11 offset:2048
	ds_read_b128 v[168:171], v11 offset:3072
	s_add_u32 s64, s16, 0x30200
	s_addc_u32 s65, s17, 0
	s_mov_b32 m0, s24
	v_lshl_add_u64 v[154:155], s[64:65], 0, v[16:17]
	ds_read_b128 v[222:225], v167 offset:32768
	ds_read_b128 v[226:229], v167 offset:33792
	ds_read_b128 v[230:233], v167 offset:34816
	ds_read_b128 v[234:237], v167 offset:35840
	ds_read_b128 v[238:241], v167 offset:36864
	ds_read_b128 v[242:245], v167 offset:37888
	ds_read_b128 v[246:249], v167 offset:38912
	ds_read_b128 v[250:253], v167 offset:39936
	global_load_lds_dwordx4 v[154:155], off
	v_lshl_add_u64 v[154:155], s[64:65], 0, v[134:135]
	s_mov_b32 m0, s31
	s_nop 0
	global_load_lds_dwordx4 v[154:155], off
	s_waitcnt vmcnt(8)
	s_waitcnt lgkmcnt(0)
	s_barrier
	s_setprio 1
	s_waitcnt lgkmcnt(0)
	v_mfma_f32_16x16x32_bf16 v[72:75], v[120:123], v[222:225], v[72:75]
	v_mfma_f32_16x16x32_bf16 v[76:79], v[128:131], v[222:225], v[76:79]
	v_mfma_f32_16x16x32_bf16 v[80:83], v[120:123], v[230:233], v[80:83]
	v_mfma_f32_16x16x32_bf16 v[84:87], v[128:131], v[230:233], v[84:87]
	v_mfma_f32_16x16x32_bf16 v[88:91], v[120:123], v[238:241], v[88:91]
	v_mfma_f32_16x16x32_bf16 v[92:95], v[128:131], v[238:241], v[92:95]
	v_mfma_f32_16x16x32_bf16 v[96:99], v[120:123], v[246:249], v[96:99]
	v_mfma_f32_16x16x32_bf16 v[100:103], v[128:131], v[246:249], v[100:103]
	v_mfma_f32_16x16x32_bf16 v[72:75], v[124:127], v[226:229], v[72:75]
	v_mfma_f32_16x16x32_bf16 v[76:79], v[138:141], v[226:229], v[76:79]
	v_mfma_f32_16x16x32_bf16 v[80:83], v[124:127], v[234:237], v[80:83]
	v_mfma_f32_16x16x32_bf16 v[84:87], v[138:141], v[234:237], v[84:87]
	v_mfma_f32_16x16x32_bf16 v[88:91], v[124:127], v[242:245], v[88:91]
	v_mfma_f32_16x16x32_bf16 v[92:95], v[138:141], v[242:245], v[92:95]
	v_mfma_f32_16x16x32_bf16 v[96:99], v[124:127], v[250:253], v[96:99]
	v_mfma_f32_16x16x32_bf16 v[100:103], v[138:141], v[250:253], v[100:103]
	v_mfma_f32_16x16x32_bf16 v[104:107], v[142:145], v[222:225], v[104:107]
	v_mfma_f32_16x16x32_bf16 v[108:111], v[150:153], v[222:225], v[108:111]
	v_mfma_f32_16x16x32_bf16 v[112:115], v[142:145], v[230:233], v[112:115]
	v_mfma_f32_16x16x32_bf16 v[48:51], v[150:153], v[230:233], v[48:51]
	v_mfma_f32_16x16x32_bf16 v[52:55], v[142:145], v[238:241], v[52:55]
	v_mfma_f32_16x16x32_bf16 v[56:59], v[150:153], v[238:241], v[56:59]
	v_mfma_f32_16x16x32_bf16 v[60:63], v[142:145], v[246:249], v[60:63]
	v_mfma_f32_16x16x32_bf16 v[64:67], v[150:153], v[246:249], v[64:67]
	v_mfma_f32_16x16x32_bf16 v[104:107], v[146:149], v[226:229], v[104:107]
	v_mfma_f32_16x16x32_bf16 v[108:111], v[168:171], v[226:229], v[108:111]
	v_mfma_f32_16x16x32_bf16 v[112:115], v[146:149], v[234:237], v[112:115]
	v_mfma_f32_16x16x32_bf16 v[48:51], v[168:171], v[234:237], v[48:51]
	v_mfma_f32_16x16x32_bf16 v[52:55], v[146:149], v[242:245], v[52:55]
	v_mfma_f32_16x16x32_bf16 v[56:59], v[168:171], v[242:245], v[56:59]
	v_mfma_f32_16x16x32_bf16 v[60:63], v[146:149], v[250:253], v[60:63]
	v_mfma_f32_16x16x32_bf16 v[64:67], v[168:171], v[250:253], v[64:67]
	s_setprio 0
	s_barrier
; #define PG8_STAGE(bufoff, gbase, voff) do { _Pragma("unroll") for (int _i = 0; _i < 2; ++_i) \
;         __builtin_amdgcn_global_load_lds((const unsigned*)((const char*)(gbase) + (voff)[_i]), (LAS unsigned*)(lds + (bufoff) + ldsw + _i * 8192), 16, 0, 0); } while (0)
; #define PG8_LDA(dst, b, h) do { _Pragma("unroll") for (int m = 0; m < 4; ++m) _Pragma("unroll") for (int k = 0; k < 2; ++k) dst[m][k] = *(const LAS bf16x8*)(lds + PG8_SA(b, h) + aoff + m * 2048 + k * 1024); } while (0)
; #define PG8_LDB(dst, b, h) do { _Pragma("unroll") for (int n = 0; n < 2; ++n) _Pragma("unroll") for (int k = 0; k < 2; ++k) dst[n][k] = *(const LAS bf16x8*)(lds + PG8_SB(b, h) + boff + n * 2048 + k * 1024); } while (0)
; #define PG8_MMA(ai, bj, At, Bt) do { __builtin_amdgcn_s_setprio(1); _Pragma("unroll") for (int m = 0; m < 4; ++m) _Pragma("unroll") for (int n = 0; n < 2; ++n) _Pragma("unroll") for (int k = 0; k < 2; ++k) \
;         acc[ai][bj][m][n] = __builtin_amdgcn_mfma_f32_16x16x32_bf16(Bt[n][k], At[m][k], acc[ai][bj][m][n], 0, 0, 0); __builtin_amdgcn_s_setprio(0); } while (0)
; #define PG8_WAIT_V(n) asm volatile("s_waitcnt vmcnt(" #n ")" ::: "memory")
; template <class Epi, class Sched, bool ALIGN_EPI = true, bool SP2 = true>
; __device__ __forceinline__ void gemm_phase(LAS unsigned char* lds, const Gemm g, const Sched& S, const Epi& E) {
;     ...
;             PG8_LDB(B0, 0, 0); PG8_LDB(B1, 0, 1); PG8_SCHED; PG8_LDA(At, 0, 0); PG8_STAGE(PG8_SA(1, 1), a1 + hstepA, voffA);
;             PG8_WAIT_V(8); PG8_WAIT_L(0); PG8_BAR; PG8_MMA(0, 0, At, B0); PG8_MMA(0, 1, At, B1); PG8_BAR; PG8_SCHED;
;             PG8_LDA(At, 0, 1); PG8_STAGE(PG8_SB(0, 0), b2, voffB); PG8_STAGE(PG8_SB(0, 1), b2 + hstepB, voffB); PG8_STAGE(PG8_SA(0, 0), a2, voffA);
;             PG8_WAIT_V(8); PG8_WAIT_L(0); PG8_BAR; PG8_MMA(1, 0, At, B0); PG8_MMA(1, 1, At, B1); PG8_BAR; PG8_SCHED;
;             PG8_LDB(B0, 1, 0); PG8_LDB(B1, 1, 1); PG8_SCHED; PG8_LDA(At, 1, 0); PG8_STAGE(PG8_SA(0, 1), a2 + hstepA, voffA);
;             PG8_WAIT_V(8); PG8_WAIT_L(0); PG8_BAR; PG8_MMA(0, 0, At, B0); PG8_MMA(0, 1, At, B1); PG8_BAR; PG8_SCHED;
;             PG8_LDA(At, 1, 1); PG8_STAGE(PG8_SB(1, 0), b3, voffB); PG8_STAGE(PG8_SB(1, 1), b3 + hstepB, voffB); PG8_STAGE(PG8_SA(1, 0), a3, voffA);
;             PG8_WAIT_V(8); PG8_WAIT_L(0); PG8_BAR; PG8_MMA(1, 0, At, B0); PG8_MMA(1, 1, At, B1); PG8_BAR; PG8_SCHED;
	s_mov_b64 s[64:65], 0x280
	s_mov_b32 m0, s61
	v_lshl_add_u64 v[0:1], v[0:1], 0, s[64:65]
	s_add_u32 s44, s44, 0x18280
	ds_read_b128 v[222:225], v167 offset:49152
	ds_read_b128 v[226:229], v167 offset:50176
	ds_read_b128 v[230:233], v167 offset:51200
	ds_read_b128 v[234:237], v167 offset:52224
	ds_read_b128 v[238:241], v167 offset:53248
	ds_read_b128 v[242:245], v167 offset:54272
	ds_read_b128 v[246:249], v167 offset:55296
	ds_read_b128 v[250:253], v167 offset:56320
	global_load_lds_dwordx4 v[0:1], off
	v_lshl_add_u64 v[0:1], v[2:3], 0, s[64:65]
	s_mov_b32 m0, s43
	s_addc_u32 s45, s45, 0
	global_load_lds_dwordx4 v[0:1], off
	v_lshl_add_u64 v[0:1], s[44:45], 0, v[132:133]
	s_mov_b32 m0, s57
	s_nop 0
	global_load_lds_dwordx4 v[0:1], off
	v_lshl_add_u64 v[0:1], s[44:45], 0, v[136:137]
	s_mov_b32 m0, s59
	s_nop 0
	global_load_lds_dwordx4 v[0:1], off
	v_lshl_add_u64 v[0:1], v[4:5], 0, s[64:65]
	s_mov_b32 m0, s52
	s_nop 0
	global_load_lds_dwordx4 v[0:1], off
	v_lshl_add_u64 v[0:1], v[6:7], 0, s[64:65]
	s_mov_b32 m0, s53
	s_nop 0
	global_load_lds_dwordx4 v[0:1], off
	s_waitcnt vmcnt(8)
	s_waitcnt lgkmcnt(0)
	s_barrier
	s_setprio 1
	s_waitcnt lgkmcnt(0)
	v_mfma_f32_16x16x32_bf16 v[0:3], v[120:123], v[222:225], v[172:175]
	v_mfma_f32_16x16x32_bf16 v[4:7], v[128:131], v[222:225], v[198:201]
	v_mfma_f32_16x16x32_bf16 v[12:15], v[120:123], v[246:249], v[12:15]
	v_mfma_f32_16x16x32_bf16 v[20:23], v[128:131], v[246:249], v[20:23]
	v_mfma_f32_16x16x32_bf16 v[0:3], v[124:127], v[226:229], v[0:3]
	v_mfma_f32_16x16x32_bf16 v[4:7], v[138:141], v[226:229], v[4:7]
	v_mfma_f32_16x16x32_bf16 v[172:175], v[120:123], v[230:233], v[202:205]
	v_mfma_f32_16x16x32_bf16 v[198:201], v[128:131], v[230:233], v[206:209]
	v_mfma_f32_16x16x32_bf16 v[202:205], v[120:123], v[238:241], v[210:213]
	v_mfma_f32_16x16x32_bf16 v[206:209], v[128:131], v[238:241], v[218:221]
	v_mfma_f32_16x16x32_bf16 v[12:15], v[124:127], v[250:253], v[12:15]
	v_mfma_f32_16x16x32_bf16 v[20:23], v[138:141], v[250:253], v[20:23]
	v_mfma_f32_16x16x32_bf16 v[172:175], v[124:127], v[234:237], v[172:175]
	v_mfma_f32_16x16x32_bf16 v[198:201], v[138:141], v[234:237], v[198:201]
	v_mfma_f32_16x16x32_bf16 v[202:205], v[124:127], v[242:245], v[202:205]
	v_mfma_f32_16x16x32_bf16 v[206:209], v[138:141], v[242:245], v[206:209]
	v_mfma_f32_16x16x32_bf16 v[24:27], v[142:145], v[222:225], v[24:27]
	v_mfma_f32_16x16x32_bf16 v[28:31], v[150:153], v[222:225], v[28:31]
	v_mfma_f32_16x16x32_bf16 v[40:43], v[142:145], v[230:233], v[40:43]
	v_mfma_f32_16x16x32_bf16 v[44:47], v[150:153], v[230:233], v[44:47]
	v_mfma_f32_16x16x32_bf16 v[68:71], v[142:145], v[238:241], v[68:71]
	v_mfma_f32_16x16x32_bf16 v[116:119], v[150:153], v[238:241], v[116:119]
	v_mfma_f32_16x16x32_bf16 v[32:35], v[142:145], v[246:249], v[32:35]
	v_mfma_f32_16x16x32_bf16 v[36:39], v[150:153], v[246:249], v[36:39]
	v_mfma_f32_16x16x32_bf16 v[24:27], v[146:149], v[226:229], v[24:27]
	v_mfma_f32_16x16x32_bf16 v[28:31], v[168:171], v[226:229], v[28:31]
	v_mfma_f32_16x16x32_bf16 v[40:43], v[146:149], v[234:237], v[40:43]
	v_mfma_f32_16x16x32_bf16 v[44:47], v[168:171], v[234:237], v[44:47]
	v_mfma_f32_16x16x32_bf16 v[68:71], v[146:149], v[242:245], v[68:71]
	v_mfma_f32_16x16x32_bf16 v[116:119], v[168:171], v[242:245], v[116:119]
	v_mfma_f32_16x16x32_bf16 v[32:35], v[146:149], v[250:253], v[32:35]
	v_mfma_f32_16x16x32_bf16 v[36:39], v[168:171], v[250:253], v[36:39]
	s_setprio 0
	s_barrier
	ds_read_b128 v[120:123], v8
	ds_read_b128 v[124:127], v8 offset:1024
	ds_read_b128 v[128:131], v8 offset:2048
	ds_read_b128 v[138:141], v8 offset:3072
	ds_read_b128 v[142:145], v9
	ds_read_b128 v[146:149], v9 offset:1024
	ds_read_b128 v[150:153], v9 offset:2048
	ds_read_b128 v[168:171], v9 offset:3072
	s_add_u32 s16, s16, 0x30280
	s_addc_u32 s17, s17, 0
	s_mov_b32 m0, s58
	v_lshl_add_u64 v[8:9], s[16:17], 0, v[16:17]
	ds_read_b128 v[210:213], v167
	ds_read_b128 v[218:221], v167 offset:1024
	ds_read_b128 v[222:225], v167 offset:2048
	ds_read_b128 v[226:229], v167 offset:3072
	ds_read_b128 v[230:233], v167 offset:4096
	ds_read_b128 v[234:237], v167 offset:5120
	ds_read_b128 v[238:241], v167 offset:6144
	ds_read_b128 v[242:245], v167 offset:7168
	global_load_lds_dwordx4 v[8:9], off
	v_lshl_add_u64 v[8:9], s[16:17], 0, v[134:135]
	s_mov_b32 m0, s2
	s_nop 0
	global_load_lds_dwordx4 v[8:9], off
	s_waitcnt vmcnt(8)
	s_waitcnt lgkmcnt(0)
	s_barrier
	s_setprio 1
	s_waitcnt lgkmcnt(0)
	v_mfma_f32_16x16x32_bf16 v[96:99], v[120:123], v[238:241], v[96:99]
	v_mfma_f32_16x16x32_bf16 v[72:75], v[120:123], v[210:213], v[72:75]
	v_mfma_f32_16x16x32_bf16 v[76:79], v[128:131], v[210:213], v[76:79]
	v_mfma_f32_16x16x32_bf16 v[80:83], v[120:123], v[222:225], v[80:83]
	v_mfma_f32_16x16x32_bf16 v[84:87], v[128:131], v[222:225], v[84:87]
	v_mfma_f32_16x16x32_bf16 v[88:91], v[120:123], v[230:233], v[88:91]
	v_mfma_f32_16x16x32_bf16 v[92:95], v[128:131], v[230:233], v[92:95]
	v_mfma_f32_16x16x32_bf16 v[246:249], v[124:127], v[242:245], v[96:99]
	v_mfma_f32_16x16x32_bf16 v[96:99], v[128:131], v[238:241], v[100:103]
	v_mfma_f32_16x16x32_bf16 v[72:75], v[124:127], v[218:221], v[72:75]
	v_mfma_f32_16x16x32_bf16 v[76:79], v[138:141], v[218:221], v[76:79]
	v_mfma_f32_16x16x32_bf16 v[80:83], v[124:127], v[226:229], v[80:83]
	v_mfma_f32_16x16x32_bf16 v[84:87], v[138:141], v[226:229], v[84:87]
	v_mfma_f32_16x16x32_bf16 v[88:91], v[124:127], v[234:237], v[88:91]
	v_mfma_f32_16x16x32_bf16 v[92:95], v[138:141], v[234:237], v[92:95]
	v_mfma_f32_16x16x32_bf16 v[100:103], v[138:141], v[242:245], v[96:99]
	v_mfma_f32_16x16x32_bf16 v[96:99], v[142:145], v[210:213], v[104:107]
	v_mfma_f32_16x16x32_bf16 v[104:107], v[146:149], v[218:221], v[96:99]
	v_mfma_f32_16x16x32_bf16 v[96:99], v[150:153], v[210:213], v[108:111]
	v_mfma_f32_16x16x32_bf16 v[48:51], v[150:153], v[222:225], v[48:51]
	v_mfma_f32_16x16x32_bf16 v[52:55], v[142:145], v[230:233], v[52:55]
	v_mfma_f32_16x16x32_bf16 v[56:59], v[150:153], v[230:233], v[56:59]
	v_mfma_f32_16x16x32_bf16 v[60:63], v[142:145], v[238:241], v[60:63]
	v_mfma_f32_16x16x32_bf16 v[64:67], v[150:153], v[238:241], v[64:67]
	v_mfma_f32_16x16x32_bf16 v[210:213], v[168:171], v[218:221], v[96:99]
	v_mfma_f32_16x16x32_bf16 v[96:99], v[142:145], v[222:225], v[112:115]
	v_mfma_f32_16x16x32_bf16 v[48:51], v[168:171], v[226:229], v[48:51]
	v_mfma_f32_16x16x32_bf16 v[52:55], v[146:149], v[234:237], v[52:55]
	v_mfma_f32_16x16x32_bf16 v[56:59], v[168:171], v[234:237], v[56:59]
	v_mfma_f32_16x16x32_bf16 v[60:63], v[146:149], v[242:245], v[60:63]
	v_mfma_f32_16x16x32_bf16 v[64:67], v[168:171], v[242:245], v[64:67]
	v_mfma_f32_16x16x32_bf16 v[218:221], v[146:149], v[226:229], v[96:99]
	s_setprio 0
	s_barrier
; #define PG8_STAGE(bufoff, gbase, voff) do { _Pragma("unroll") for (int _i = 0; _i < 2; ++_i) \
;         __builtin_amdgcn_global_load_lds((const unsigned*)((const char*)(gbase) + (voff)[_i]), (LAS unsigned*)(lds + (bufoff) + ldsw + _i * 8192), 16, 0, 0); } while (0)
; #define PG8_LDA(dst, b, h) do { _Pragma("unroll") for (int m = 0; m < 4; ++m) _Pragma("unroll") for (int k = 0; k < 2; ++k) dst[m][k] = *(const LAS bf16x8*)(lds + PG8_SA(b, h) + aoff + m * 2048 + k * 1024); } while (0)
; #define PG8_LDB(dst, b, h) do { _Pragma("unroll") for (int n = 0; n < 2; ++n) _Pragma("unroll") for (int k = 0; k < 2; ++k) dst[n][k] = *(const LAS bf16x8*)(lds + PG8_SB(b, h) + boff + n * 2048 + k * 1024); } while (0)
; #define PG8_WAIT_V(n) asm volatile("s_waitcnt vmcnt(" #n ")" ::: "memory")
; #define PG8_WAIT_L(n) asm volatile("s_waitcnt lgkmcnt(" #n ")" ::: "memory")
; template <class Epi, class Sched, bool ALIGN_EPI = true, bool SP2 = true>
; __device__ __forceinline__ void gemm_phase(LAS unsigned char* lds, const Gemm g, const Sched& S, const Epi& E) {
;     ...
;             const bool last = (t == nt - 2);
;             const char* a1 = cA + (size_t)(t + 1) * kstep;
;             const char* a2 = last ? nA : cA + (size_t)(t + 2) * kstep; const char* b2 = last ? nB : cB + (size_t)(t + 2) * kstep;
;             const char* a3 = a2 + kstep; const char* b3 = b2 + kstep;
;             PG8_LDB(B0, 0, 0); PG8_LDB(B1, 0, 1); PG8_SCHED; PG8_LDA(At, 0, 0); PG8_STAGE(PG8_SA(1, 1), a1 + hstepA, voffA);
;             PG8_WAIT_V(8); PG8_WAIT_L(0); PG8_BAR; PG8_MMA(0, 0, At, B0); PG8_MMA(0, 1, At, B1); PG8_BAR; PG8_SCHED;
;             PG8_LDA(At, 0, 1); PG8_STAGE(PG8_SB(0, 0), b2, voffB); PG8_STAGE(PG8_SB(0, 1), b2 + hstepB, voffB); PG8_STAGE(PG8_SA(0, 0), a2, voffA);
;             PG8_WAIT_V(8); PG8_WAIT_L(0); PG8_BAR; PG8_MMA(1, 0, At, B0); PG8_MMA(1, 1, At, B1); PG8_BAR; PG8_SCHED;
;             PG8_LDB(B0, 1, 0); PG8_LDB(B1, 1, 1); PG8_SCHED; PG8_LDA(At, 1, 0); PG8_STAGE(PG8_SA(0, 1), a2 + hstepA, voffA);
;             PG8_WAIT_V(8); PG8_WAIT_L(0); PG8_BAR; PG8_MMA(0, 0, At, B0); PG8_MMA(0, 1, At, B1); PG8_BAR; PG8_SCHED;
;             PG8_LDA(At, 1, 1); PG8_STAGE(PG8_SB(1, 0), b3, voffB); PG8_STAGE(PG8_SB(1, 1), b3 + hstepB, voffB); PG8_STAGE(PG8_SA(1, 0), a3, voffA);
;             PG8_WAIT_V(8); PG8_WAIT_L(0); PG8_BAR; PG8_MMA(1, 0, At, B0); PG8_MMA(1, 1, At, B1); PG8_BAR; PG8_SCHED;
	s_mov_b32 m0, s42
	v_lshl_add_u64 v[176:177], s[34:35], 0, v[132:133]
	s_add_u32 s16, s34, 0x18000
	ds_read_b128 v[96:99], v167 offset:16384
	ds_read_b128 v[108:111], v167 offset:17408
	ds_read_b128 v[112:115], v167 offset:18432
	ds_read_b128 v[222:225], v167 offset:19456
	ds_read_b128 v[226:229], v167 offset:20480
	ds_read_b128 v[230:233], v167 offset:21504
	ds_read_b128 v[234:237], v167 offset:22528
	ds_read_b128 v[238:241], v167 offset:23552
	global_load_lds_dwordx4 v[176:177], off
	v_lshl_add_u64 v[214:215], s[34:35], 0, v[136:137]
	s_mov_b32 m0, s8
	s_addc_u32 s17, s35, 0
	global_load_lds_dwordx4 v[214:215], off
	v_lshl_add_u64 v[8:9], s[16:17], 0, v[132:133]
	s_mov_b32 m0, s9
	v_lshl_add_u64 v[182:183], s[46:47], 0, v[16:17]
	global_load_lds_dwordx4 v[8:9], off
	v_lshl_add_u64 v[8:9], s[16:17], 0, v[136:137]
	s_mov_b32 m0, s30
	v_lshl_add_u64 v[178:179], s[46:47], 0, v[134:135]
	global_load_lds_dwordx4 v[8:9], off
	s_mov_b32 m0, s22
	s_nop 0
	global_load_lds_dwordx4 v[182:183], off
	s_mov_b32 m0, s23
	s_nop 0
	global_load_lds_dwordx4 v[178:179], off
	s_waitcnt vmcnt(8)
	s_waitcnt lgkmcnt(0)
	s_barrier
	s_setprio 1
	s_waitcnt lgkmcnt(0)
	v_mfma_f32_16x16x32_bf16 v[0:3], v[120:123], v[96:99], v[0:3]
	v_mfma_f32_16x16x32_bf16 v[4:7], v[128:131], v[96:99], v[4:7]
	v_mfma_f32_16x16x32_bf16 v[12:15], v[120:123], v[234:237], v[12:15]
	v_mfma_f32_16x16x32_bf16 v[20:23], v[128:131], v[234:237], v[20:23]
	v_mfma_f32_16x16x32_bf16 v[0:3], v[124:127], v[108:111], v[0:3]
	v_mfma_f32_16x16x32_bf16 v[4:7], v[138:141], v[108:111], v[4:7]
	v_mfma_f32_16x16x32_bf16 v[172:175], v[120:123], v[112:115], v[172:175]
	v_mfma_f32_16x16x32_bf16 v[198:201], v[128:131], v[112:115], v[198:201]
	v_mfma_f32_16x16x32_bf16 v[202:205], v[120:123], v[226:229], v[202:205]
	v_mfma_f32_16x16x32_bf16 v[206:209], v[128:131], v[226:229], v[206:209]
	v_mfma_f32_16x16x32_bf16 v[12:15], v[124:127], v[238:241], v[12:15]
	v_mfma_f32_16x16x32_bf16 v[20:23], v[138:141], v[238:241], v[20:23]
	v_mfma_f32_16x16x32_bf16 v[172:175], v[124:127], v[222:225], v[172:175]
	v_mfma_f32_16x16x32_bf16 v[198:201], v[138:141], v[222:225], v[198:201]
	v_mfma_f32_16x16x32_bf16 v[202:205], v[124:127], v[230:233], v[202:205]
	v_mfma_f32_16x16x32_bf16 v[206:209], v[138:141], v[230:233], v[206:209]
	v_mfma_f32_16x16x32_bf16 v[28:31], v[150:153], v[96:99], v[28:31]
	v_mfma_f32_16x16x32_bf16 v[138:141], v[168:171], v[108:111], v[28:31]
	v_mfma_f32_16x16x32_bf16 v[28:31], v[142:145], v[112:115], v[40:43]
	v_mfma_f32_16x16x32_bf16 v[40:43], v[146:149], v[222:225], v[28:31]
	v_mfma_f32_16x16x32_bf16 v[28:31], v[150:153], v[112:115], v[44:47]
	v_mfma_f32_16x16x32_bf16 v[222:225], v[168:171], v[222:225], v[28:31]
	v_mfma_f32_16x16x32_bf16 v[28:31], v[142:145], v[226:229], v[68:71]
	v_mfma_f32_16x16x32_bf16 v[242:245], v[146:149], v[230:233], v[28:31]
	v_mfma_f32_16x16x32_bf16 v[28:31], v[150:153], v[226:229], v[116:119]
	v_mfma_f32_16x16x32_bf16 v[24:27], v[142:145], v[96:99], v[24:27]
	v_mfma_f32_16x16x32_bf16 v[226:229], v[168:171], v[230:233], v[28:31]
	v_mfma_f32_16x16x32_bf16 v[28:31], v[142:145], v[234:237], v[32:35]
	v_mfma_f32_16x16x32_bf16 v[24:27], v[146:149], v[108:111], v[24:27]
	v_mfma_f32_16x16x32_bf16 v[142:145], v[146:149], v[238:241], v[28:31]
	v_mfma_f32_16x16x32_bf16 v[28:31], v[150:153], v[234:237], v[36:39]
	v_mfma_f32_16x16x32_bf16 v[146:149], v[168:171], v[238:241], v[28:31]
	s_setprio 0
	s_barrier
	ds_read_b128 v[36:39], v10
	ds_read_b128 v[150:153], v10 offset:1024
	ds_read_b128 v[168:171], v10 offset:2048
	ds_read_b128 v[230:233], v10 offset:3072
	ds_read_b128 v[234:237], v11
	ds_read_b128 v[238:241], v11 offset:1024
	ds_read_b128 v[250:253], v11 offset:2048
	ds_read_b128 v[154:157], v11 offset:3072
	s_add_u32 s8, s46, 0x30000
	s_addc_u32 s9, s47, 0
	s_mov_b32 m0, s24
	v_lshl_add_u64 v[96:97], s[8:9], 0, v[16:17]
	ds_read_b128 v[8:11], v167 offset:32768
	ds_read_b128 v[28:31], v167 offset:33792
	ds_read_b128 v[32:35], v167 offset:34816
	ds_read_b128 v[44:47], v167 offset:35840
	ds_read_b128 v[68:71], v167 offset:36864
	ds_read_b128 v[186:189], v167 offset:37888
	ds_read_b128 v[190:193], v167 offset:38912
	ds_read_b128 v[158:161], v167 offset:39936
	global_load_lds_dwordx4 v[96:97], off
	v_lshl_add_u64 v[96:97], s[8:9], 0, v[134:135]
	s_mov_b32 m0, s31
	s_nop 0
	global_load_lds_dwordx4 v[96:97], off
	s_waitcnt vmcnt(8)
	s_waitcnt lgkmcnt(0)
	s_barrier
; #define PG8_STAGE(bufoff, gbase, voff) do { _Pragma("unroll") for (int _i = 0; _i < 2; ++_i) \
;         __builtin_amdgcn_global_load_lds((const unsigned*)((const char*)(gbase) + (voff)[_i]), (LAS unsigned*)(lds + (bufoff) + ldsw + _i * 8192), 16, 0, 0); } while (0)
; #define PG8_LDA(dst, b, h) do { _Pragma("unroll") for (int m = 0; m < 4; ++m) _Pragma("unroll") for (int k = 0; k < 2; ++k) dst[m][k] = *(const LAS bf16x8*)(lds + PG8_SA(b, h) + aoff + m * 2048 + k * 1024); } while (0)
; #define PG8_LDB(dst, b, h) do { _Pragma("unroll") for (int n = 0; n < 2; ++n) _Pragma("unroll") for (int k = 0; k < 2; ++k) dst[n][k] = *(const LAS bf16x8*)(lds + PG8_SB(b, h) + boff + n * 2048 + k * 1024); } while (0)
; #define PG8_MMA(ai, bj, At, Bt) do { __builtin_amdgcn_s_setprio(1); _Pragma("unroll") for (int m = 0; m < 4; ++m) _Pragma("unroll") for (int n = 0; n < 2; ++n) _Pragma("unroll") for (int k = 0; k < 2; ++k) \
;         acc[ai][bj][m][n] = __builtin_amdgcn_mfma_f32_16x16x32_bf16(Bt[n][k], At[m][k], acc[ai][bj][m][n], 0, 0, 0); __builtin_amdgcn_s_setprio(0); } while (0)
; template <class Epi, class Sched, bool ALIGN_EPI = true, bool SP2 = true>
; __device__ __forceinline__ void gemm_phase(LAS unsigned char* lds, const Gemm g, const Sched& S, const Epi& E) {
;     ...
;             PG8_LDB(B0, 0, 0); PG8_LDB(B1, 0, 1); PG8_SCHED; PG8_LDA(At, 0, 0); PG8_STAGE(PG8_SA(1, 1), a1 + hstepA, voffA);
;             PG8_WAIT_V(8); PG8_WAIT_L(0); PG8_BAR; PG8_MMA(0, 0, At, B0); PG8_MMA(0, 1, At, B1); PG8_BAR; PG8_SCHED;
;             PG8_LDA(At, 0, 1); PG8_STAGE(PG8_SB(0, 0), b2, voffB); PG8_STAGE(PG8_SB(0, 1), b2 + hstepB, voffB); PG8_STAGE(PG8_SA(0, 0), a2, voffA);
;             PG8_WAIT_V(8); PG8_WAIT_L(0); PG8_BAR; PG8_MMA(1, 0, At, B0); PG8_MMA(1, 1, At, B1); PG8_BAR; PG8_SCHED;
;             PG8_LDB(B0, 1, 0); PG8_LDB(B1, 1, 1); PG8_SCHED; PG8_LDA(At, 1, 0); PG8_STAGE(PG8_SA(0, 1), a2 + hstepA, voffA);
;             PG8_WAIT_V(8); PG8_WAIT_L(0); PG8_BAR; PG8_MMA(0, 0, At, B0); PG8_MMA(0, 1, At, B1); PG8_BAR; PG8_SCHED;
;             PG8_LDA(At, 1, 1); PG8_STAGE(PG8_SB(1, 0), b3, voffB); PG8_STAGE(PG8_SB(1, 1), b3 + hstepB, voffB); PG8_STAGE(PG8_SA(1, 0), a3, voffA);
;             PG8_WAIT_V(8); PG8_WAIT_L(0); PG8_BAR; PG8_MMA(1, 0, At, B0); PG8_MMA(1, 1, At, B1); PG8_BAR; PG8_SCHED;
;         }
;         if constexpr (ALIGN_EPI) { if (wr == 0) PG8_BAR; }
	s_setprio 1
	s_waitcnt lgkmcnt(0)
	v_mfma_f32_16x16x32_bf16 v[72:75], v[36:39], v[8:11], v[72:75]
	v_mfma_f32_16x16x32_bf16 v[124:127], v[150:153], v[28:31], v[72:75]
	v_mfma_f32_16x16x32_bf16 v[72:75], v[168:171], v[8:11], v[76:79]
	v_mfma_f32_16x16x32_bf16 v[128:131], v[230:233], v[28:31], v[72:75]
	v_mfma_f32_16x16x32_bf16 v[72:75], v[36:39], v[32:35], v[80:83]
	v_mfma_f32_16x16x32_bf16 v[112:115], v[150:153], v[44:47], v[72:75]
	v_mfma_f32_16x16x32_bf16 v[72:75], v[168:171], v[32:35], v[84:87]
	v_mfma_f32_16x16x32_bf16 v[108:111], v[230:233], v[44:47], v[72:75]
	v_mfma_f32_16x16x32_bf16 v[72:75], v[36:39], v[68:71], v[88:91]
	v_mfma_f32_16x16x32_bf16 v[96:99], v[150:153], v[186:189], v[72:75]
	v_mfma_f32_16x16x32_bf16 v[72:75], v[168:171], v[68:71], v[92:95]
	v_mfma_f32_16x16x32_bf16 v[92:95], v[230:233], v[186:189], v[72:75]
	v_mfma_f32_16x16x32_bf16 v[72:75], v[36:39], v[190:193], v[246:249]
	v_mfma_f32_16x16x32_bf16 v[80:83], v[150:153], v[158:161], v[72:75]
	v_mfma_f32_16x16x32_bf16 v[72:75], v[168:171], v[190:193], v[100:103]
	v_mfma_f32_16x16x32_bf16 v[76:79], v[230:233], v[158:161], v[72:75]
	v_mfma_f32_16x16x32_bf16 v[72:75], v[234:237], v[8:11], v[104:107]
	v_mfma_f32_16x16x32_bf16 v[8:11], v[250:253], v[8:11], v[210:213]
	v_mfma_f32_16x16x32_bf16 v[116:119], v[154:157], v[28:31], v[8:11]
	v_mfma_f32_16x16x32_bf16 v[8:11], v[234:237], v[32:35], v[218:221]
	v_mfma_f32_16x16x32_bf16 v[104:107], v[238:241], v[44:47], v[8:11]
	v_mfma_f32_16x16x32_bf16 v[8:11], v[250:253], v[32:35], v[48:51]
	v_mfma_f32_16x16x32_bf16 v[100:103], v[154:157], v[44:47], v[8:11]
	v_mfma_f32_16x16x32_bf16 v[8:11], v[234:237], v[68:71], v[52:55]
	v_mfma_f32_16x16x32_bf16 v[88:91], v[238:241], v[186:189], v[8:11]
	v_mfma_f32_16x16x32_bf16 v[8:11], v[250:253], v[68:71], v[56:59]
	v_mfma_f32_16x16x32_bf16 v[84:87], v[154:157], v[186:189], v[8:11]
	v_mfma_f32_16x16x32_bf16 v[8:11], v[234:237], v[190:193], v[60:63]
	v_mfma_f32_16x16x32_bf16 v[120:123], v[238:241], v[28:31], v[72:75]
	v_mfma_f32_16x16x32_bf16 v[72:75], v[238:241], v[158:161], v[8:11]
	v_mfma_f32_16x16x32_bf16 v[8:11], v[250:253], v[190:193], v[64:67]
	v_mfma_f32_16x16x32_bf16 v[68:71], v[154:157], v[158:161], v[8:11]
	s_setprio 0
	s_barrier
	s_mov_b32 m0, s61
	s_nop 3
	v_lshl_add_u64 v[8:9], v[176:177], 0, s[14:15]
	s_add_u32 s8, s34, 0x18080
	ds_read_b128 v[52:55], v167 offset:49152
	ds_read_b128 v[158:161], v167 offset:50176
	ds_read_b128 v[186:189], v167 offset:51200
	ds_read_b128 v[190:193], v167 offset:52224
	ds_read_b128 v[210:213], v167 offset:53248
	ds_read_b128 v[218:221], v167 offset:54272
	ds_read_b128 v[246:249], v167 offset:55296
	ds_read_b128 v[162:165], v167 offset:56320
	global_load_lds_dwordx4 v[8:9], off
	v_lshl_add_u64 v[8:9], v[214:215], 0, s[14:15]
	s_mov_b32 m0, s43
	s_addc_u32 s9, s35, 0
	global_load_lds_dwordx4 v[8:9], off
	v_lshl_add_u64 v[8:9], s[8:9], 0, v[132:133]
	s_mov_b32 m0, s57
	s_nop 0
	global_load_lds_dwordx4 v[8:9], off
	v_lshl_add_u64 v[8:9], s[8:9], 0, v[136:137]
	s_mov_b32 m0, s59
	s_nop 0
	global_load_lds_dwordx4 v[8:9], off
	v_lshl_add_u64 v[8:9], v[182:183], 0, s[14:15]
	s_mov_b32 m0, s52
	s_nop 0
	global_load_lds_dwordx4 v[8:9], off
	v_lshl_add_u64 v[8:9], v[178:179], 0, s[14:15]
	s_mov_b32 m0, s53
	s_nop 0
	global_load_lds_dwordx4 v[8:9], off
	s_waitcnt vmcnt(8)
	s_waitcnt lgkmcnt(0)
	s_barrier
	s_setprio 1
	s_waitcnt lgkmcnt(0)
	v_mfma_f32_16x16x32_bf16 v[0:3], v[36:39], v[52:55], v[0:3]
	v_mfma_f32_16x16x32_bf16 v[64:67], v[150:153], v[158:161], v[0:3]
	v_mfma_f32_16x16x32_bf16 v[0:3], v[168:171], v[52:55], v[4:7]
	v_mfma_f32_16x16x32_bf16 v[60:63], v[230:233], v[158:161], v[0:3]
	v_mfma_f32_16x16x32_bf16 v[0:3], v[36:39], v[186:189], v[172:175]
	v_mfma_f32_16x16x32_bf16 v[48:51], v[150:153], v[190:193], v[0:3]
	v_mfma_f32_16x16x32_bf16 v[0:3], v[168:171], v[186:189], v[198:201]
	v_mfma_f32_16x16x32_bf16 v[44:47], v[230:233], v[190:193], v[0:3]
	v_mfma_f32_16x16x32_bf16 v[0:3], v[36:39], v[210:213], v[202:205]
	v_mfma_f32_16x16x32_bf16 v[32:35], v[150:153], v[218:221], v[0:3]
	v_mfma_f32_16x16x32_bf16 v[0:3], v[168:171], v[210:213], v[206:209]
	v_mfma_f32_16x16x32_bf16 v[28:31], v[230:233], v[218:221], v[0:3]
	v_mfma_f32_16x16x32_bf16 v[0:3], v[36:39], v[246:249], v[12:15]
	v_mfma_f32_16x16x32_bf16 v[12:15], v[150:153], v[162:165], v[0:3]
	v_mfma_f32_16x16x32_bf16 v[0:3], v[168:171], v[246:249], v[20:23]
	v_mfma_f32_16x16x32_bf16 v[8:11], v[230:233], v[162:165], v[0:3]
	v_mfma_f32_16x16x32_bf16 v[0:3], v[234:237], v[52:55], v[24:27]
	v_mfma_f32_16x16x32_bf16 v[56:59], v[238:241], v[158:161], v[0:3]
	v_mfma_f32_16x16x32_bf16 v[0:3], v[250:253], v[52:55], v[138:141]
	v_mfma_f32_16x16x32_bf16 v[52:55], v[154:157], v[158:161], v[0:3]
	v_mfma_f32_16x16x32_bf16 v[0:3], v[234:237], v[186:189], v[40:43]
	v_mfma_f32_16x16x32_bf16 v[40:43], v[238:241], v[190:193], v[0:3]
	v_mfma_f32_16x16x32_bf16 v[0:3], v[250:253], v[186:189], v[222:225]
	v_mfma_f32_16x16x32_bf16 v[36:39], v[154:157], v[190:193], v[0:3]
	v_mfma_f32_16x16x32_bf16 v[0:3], v[234:237], v[210:213], v[242:245]
	v_mfma_f32_16x16x32_bf16 v[24:27], v[238:241], v[218:221], v[0:3]
	v_mfma_f32_16x16x32_bf16 v[0:3], v[250:253], v[210:213], v[226:229]
	v_mfma_f32_16x16x32_bf16 v[20:23], v[154:157], v[218:221], v[0:3]
	v_mfma_f32_16x16x32_bf16 v[0:3], v[234:237], v[246:249], v[142:145]
	v_mfma_f32_16x16x32_bf16 v[4:7], v[238:241], v[162:165], v[0:3]
	v_mfma_f32_16x16x32_bf16 v[0:3], v[250:253], v[246:249], v[146:149]
	v_mfma_f32_16x16x32_bf16 v[0:3], v[154:157], v[162:165], v[0:3]
	s_setprio 0
	s_barrier
	s_andn2_b64 vcc, exec, s[62:63]
	s_cbranch_vccnz .LBB0_629
	s_barrier

; #define PG8_STAGE(bufoff, gbase, voff) do { _Pragma("unroll") for (int _i = 0; _i < 2; ++_i) \
;         __builtin_amdgcn_global_load_lds((const unsigned*)((const char*)(gbase) + (voff)[_i]), (LAS unsigned*)(lds + (bufoff) + ldsw + _i * 8192), 16, 0, 0); } while (0)
; #define PG8_LDA(dst, b, h) do { _Pragma("unroll") for (int m = 0; m < 4; ++m) _Pragma("unroll") for (int k = 0; k < 2; ++k) dst[m][k] = *(const LAS bf16x8*)(lds + PG8_SA(b, h) + aoff + m * 2048 + k * 1024); } while (0)
; #define PG8_LDB(dst, b, h) do { _Pragma("unroll") for (int n = 0; n < 2; ++n) _Pragma("unroll") for (int k = 0; k < 2; ++k) dst[n][k] = *(const LAS bf16x8*)(lds + PG8_SB(b, h) + boff + n * 2048 + k * 1024); } while (0)
; #define PG8_WAIT_V(n) asm volatile("s_waitcnt vmcnt(" #n ")" ::: "memory")
; template <class Epi, class Sched, bool ALIGN_EPI = true, bool SP2 = true>
; __device__ __forceinline__ void gemm_phase(LAS unsigned char* lds, const Gemm g, const Sched& S, const Epi& E) {
;     ...
;         for (int t = 0; t < nt; t += 2) {
;             const bool last = (t == nt - 2);
;             const char* a1 = cA + (size_t)(t + 1) * kstep;
;             const char* a2 = last ? nA : cA + (size_t)(t + 2) * kstep; const char* b2 = last ? nB : cB + (size_t)(t + 2) * kstep;
;             const char* a3 = a2 + kstep; const char* b3 = b2 + kstep;
;             PG8_LDB(B0, 0, 0); PG8_LDB(B1, 0, 1); PG8_SCHED; PG8_LDA(At, 0, 0); PG8_STAGE(PG8_SA(1, 1), a1 + hstepA, voffA);
;             PG8_WAIT_V(8); PG8_WAIT_L(0); PG8_BAR; PG8_MMA(0, 0, At, B0); PG8_MMA(0, 1, At, B1); PG8_BAR; PG8_SCHED;
;             PG8_LDA(At, 0, 1); PG8_STAGE(PG8_SB(0, 0), b2, voffB); PG8_STAGE(PG8_SB(0, 1), b2 + hstepB, voffB); PG8_STAGE(PG8_SA(0, 0), a2, voffA);
;             PG8_WAIT_V(8); PG8_WAIT_L(0); PG8_BAR; PG8_MMA(1, 0, At, B0); PG8_MMA(1, 1, At, B1); PG8_BAR; PG8_SCHED;
;             PG8_LDB(B0, 1, 0); PG8_LDB(B1, 1, 1); PG8_SCHED; PG8_LDA(At, 1, 0); PG8_STAGE(PG8_SA(0, 1), a2 + hstepA, voffA);
;             PG8_WAIT_V(8); PG8_WAIT_L(0); PG8_BAR; PG8_MMA(0, 0, At, B0); PG8_MMA(0, 1, At, B1); PG8_BAR; PG8_SCHED;
;             PG8_LDA(At, 1, 1); PG8_STAGE(PG8_SB(1, 0), b3, voffB); PG8_STAGE(PG8_SB(1, 1), b3 + hstepB, voffB); PG8_STAGE(PG8_SA(1, 0), a3, voffA);
;             PG8_WAIT_V(8); PG8_WAIT_L(0); PG8_BAR; PG8_MMA(1, 0, At, B0); PG8_MMA(1, 1, At, B1); PG8_BAR; PG8_SCHED;
.LBB0_676:
	s_add_u32 s22, s50, s9
	s_addc_u32 s23, s51, 0
	s_add_u32 s30, s22, 0x100
	s_addc_u32 s38, s23, 0
	s_and_b64 s[20:21], s[18:19], exec
	s_cselect_b32 s55, s47, s38
	s_cselect_b32 s54, s46, s30
	s_add_u32 s9, s16, s9
	s_addc_u32 s20, s17, 0
	s_add_u32 s9, s9, 0x100
	s_addc_u32 s20, s20, 0
	s_add_i32 s38, 0, 0x10000
	s_and_b64 s[18:19], s[18:19], exec
	s_cselect_b32 s63, s2, s20
	s_cselect_b32 s62, s8, s9
	s_add_i32 s19, 0, 0x14000
	s_add_u32 s22, s22, 0x30080
	s_addc_u32 s23, s23, 0
	s_add_i32 s67, s38, s52
	s_add_i32 m0, s39, 0xc000
	s_add_i32 s28, s39, 0xe000
	s_add_i32 s59, s67, 0x2000
	s_add_u32 vcc_lo, s62, 0x10000
	v_add_u32_e32 v150, s38, v144
	v_add_u32_e32 v166, s19, v144
	s_addc_u32 vcc_hi, s63, 0
	s_add_i32 s66, s19, s52
	ds_read_b128 v[136:139], v150
	ds_read_b128 v[140:143], v150 offset:1024
	ds_read_b128 v[146:149], v150 offset:2048
	ds_read_b128 v[150:153], v150 offset:3072
	ds_read_b128 v[154:157], v166
	ds_read_b128 v[158:161], v166 offset:1024
	ds_read_b128 v[162:165], v166 offset:2048
	ds_read_b128 v[166:169], v166 offset:3072
	s_add_i32 s61, s66, 0x2000
	s_add_i32 s58, 0, 0x18000
	s_add_i32 s45, 0, 0x1c000
	s_add_u32 s20, s54, 0x30000
	s_addc_u32 s21, s55, 0
	s_add_i32 s30, s58, s52
	s_add_i32 s9, s30, 0x2000
	s_add_u32 s18, s62, 0x10080
	s_addc_u32 s19, s63, 0
	s_add_i32 s60, s45, s52
	s_add_i32 s38, s60, 0x2000
	v_lshl_add_u64 v[178:179], s[22:23], 0, v[134:135]
	ds_read_b128 v[170:173], v145
	ds_read_b128 v[174:177], v145 offset:1024
	ds_read_b128 v[186:189], v145 offset:2048
	ds_read_b128 v[190:193], v145 offset:3072
	ds_read_b128 v[198:201], v145 offset:4096
	ds_read_b128 v[202:205], v145 offset:5120
	ds_read_b128 v[206:209], v145 offset:6144
	ds_read_b128 v[210:213], v145 offset:7168
	global_load_lds_dwordx4 v[178:179], off
	v_lshl_add_u64 v[178:179], s[22:23], 0, v[132:133]
	s_mov_b32 m0, s28
	s_nop 0
	global_load_lds_dwordx4 v[178:179], off
	s_waitcnt vmcnt(8)
	s_waitcnt lgkmcnt(0)
	s_barrier
	s_setprio 1
	s_waitcnt lgkmcnt(0)
	v_mfma_f32_16x16x32_bf16 v[128:131], v[136:139], v[170:173], v[128:131]
	v_mfma_f32_16x16x32_bf16 v[124:127], v[146:149], v[170:173], v[124:127]
	v_mfma_f32_16x16x32_bf16 v[112:115], v[136:139], v[186:189], v[112:115]
	v_mfma_f32_16x16x32_bf16 v[108:111], v[146:149], v[186:189], v[108:111]
	v_mfma_f32_16x16x32_bf16 v[96:99], v[136:139], v[198:201], v[96:99]
	v_mfma_f32_16x16x32_bf16 v[92:95], v[146:149], v[198:201], v[92:95]
	v_mfma_f32_16x16x32_bf16 v[80:83], v[136:139], v[206:209], v[80:83]
	v_mfma_f32_16x16x32_bf16 v[76:79], v[146:149], v[206:209], v[76:79]
	v_mfma_f32_16x16x32_bf16 v[128:131], v[140:143], v[174:177], v[128:131]
	v_mfma_f32_16x16x32_bf16 v[124:127], v[150:153], v[174:177], v[124:127]
	v_mfma_f32_16x16x32_bf16 v[112:115], v[140:143], v[190:193], v[112:115]
	v_mfma_f32_16x16x32_bf16 v[108:111], v[150:153], v[190:193], v[108:111]
	v_mfma_f32_16x16x32_bf16 v[96:99], v[140:143], v[202:205], v[96:99]
	v_mfma_f32_16x16x32_bf16 v[92:95], v[150:153], v[202:205], v[92:95]
	v_mfma_f32_16x16x32_bf16 v[80:83], v[140:143], v[210:213], v[80:83]
	v_mfma_f32_16x16x32_bf16 v[76:79], v[150:153], v[210:213], v[76:79]
	v_mfma_f32_16x16x32_bf16 v[120:123], v[154:157], v[170:173], v[120:123]
	v_mfma_f32_16x16x32_bf16 v[116:119], v[162:165], v[170:173], v[116:119]
	v_mfma_f32_16x16x32_bf16 v[104:107], v[154:157], v[186:189], v[104:107]
	v_mfma_f32_16x16x32_bf16 v[100:103], v[162:165], v[186:189], v[100:103]
	v_mfma_f32_16x16x32_bf16 v[88:91], v[154:157], v[198:201], v[88:91]
	v_mfma_f32_16x16x32_bf16 v[84:87], v[162:165], v[198:201], v[84:87]
	v_mfma_f32_16x16x32_bf16 v[72:75], v[154:157], v[206:209], v[72:75]
	v_mfma_f32_16x16x32_bf16 v[68:71], v[162:165], v[206:209], v[68:71]
	v_mfma_f32_16x16x32_bf16 v[120:123], v[158:161], v[174:177], v[120:123]
	v_mfma_f32_16x16x32_bf16 v[116:119], v[166:169], v[174:177], v[116:119]
	v_mfma_f32_16x16x32_bf16 v[104:107], v[158:161], v[190:193], v[104:107]
	v_mfma_f32_16x16x32_bf16 v[100:103], v[166:169], v[190:193], v[100:103]
	v_mfma_f32_16x16x32_bf16 v[88:91], v[158:161], v[202:205], v[88:91]
	v_mfma_f32_16x16x32_bf16 v[84:87], v[166:169], v[202:205], v[84:87]
	v_mfma_f32_16x16x32_bf16 v[72:75], v[158:161], v[210:213], v[72:75]
	v_mfma_f32_16x16x32_bf16 v[68:71], v[166:169], v[210:213], v[68:71]
	s_setprio 0
	s_barrier
	s_mov_b32 m0, s67
	v_lshl_add_u64 v[178:179], s[62:63], 0, v[18:19]
	ds_read_b128 v[170:173], v145 offset:16384
	ds_read_b128 v[174:177], v145 offset:17408
	ds_read_b128 v[186:189], v145 offset:18432
	ds_read_b128 v[190:193], v145 offset:19456
	ds_read_b128 v[198:201], v145 offset:20480
	ds_read_b128 v[202:205], v145 offset:21504
	ds_read_b128 v[206:209], v145 offset:22528
	ds_read_b128 v[210:213], v145 offset:23552
	global_load_lds_dwordx4 v[178:179], off
	v_lshl_add_u64 v[182:183], s[62:63], 0, v[16:17]
	s_mov_b32 m0, s59
	v_lshl_add_u64 v[214:215], vcc, 0, v[18:19]
	global_load_lds_dwordx4 v[182:183], off
	s_mov_b32 m0, s66
	v_lshl_add_u64 v[218:219], s[54:55], 0, v[132:133]
	global_load_lds_dwordx4 v[214:215], off
	v_lshl_add_u64 v[214:215], vcc, 0, v[16:17]
	s_mov_b32 m0, s61
	s_nop 0
	global_load_lds_dwordx4 v[214:215], off
	v_lshl_add_u64 v[214:215], s[54:55], 0, v[134:135]
	s_mov_b32 m0, s39
	s_nop 0
	global_load_lds_dwordx4 v[214:215], off
	s_mov_b32 m0, s56
	s_nop 0
	global_load_lds_dwordx4 v[218:219], off
	s_waitcnt vmcnt(8)
	s_waitcnt lgkmcnt(0)
	s_barrier
; #define PG8_STAGE(bufoff, gbase, voff) do { _Pragma("unroll") for (int _i = 0; _i < 2; ++_i) \
;         __builtin_amdgcn_global_load_lds((const unsigned*)((const char*)(gbase) + (voff)[_i]), (LAS unsigned*)(lds + (bufoff) + ldsw + _i * 8192), 16, 0, 0); } while (0)
; #define PG8_LDA(dst, b, h) do { _Pragma("unroll") for (int m = 0; m < 4; ++m) _Pragma("unroll") for (int k = 0; k < 2; ++k) dst[m][k] = *(const LAS bf16x8*)(lds + PG8_SA(b, h) + aoff + m * 2048 + k * 1024); } while (0)
; #define PG8_LDB(dst, b, h) do { _Pragma("unroll") for (int n = 0; n < 2; ++n) _Pragma("unroll") for (int k = 0; k < 2; ++k) dst[n][k] = *(const LAS bf16x8*)(lds + PG8_SB(b, h) + boff + n * 2048 + k * 1024); } while (0)
; #define PG8_MMA(ai, bj, At, Bt) do { __builtin_amdgcn_s_setprio(1); _Pragma("unroll") for (int m = 0; m < 4; ++m) _Pragma("unroll") for (int n = 0; n < 2; ++n) _Pragma("unroll") for (int k = 0; k < 2; ++k) \
;         acc[ai][bj][m][n] = __builtin_amdgcn_mfma_f32_16x16x32_bf16(Bt[n][k], At[m][k], acc[ai][bj][m][n], 0, 0, 0); __builtin_amdgcn_s_setprio(0); } while (0)
; #define PG8_WAIT_V(n) asm volatile("s_waitcnt vmcnt(" #n ")" ::: "memory")
; template <class Epi, class Sched, bool ALIGN_EPI = true, bool SP2 = true>
; __device__ __forceinline__ void gemm_phase(LAS unsigned char* lds, const Gemm g, const Sched& S, const Epi& E) {
;     ...
;             PG8_LDB(B0, 0, 0); PG8_LDB(B1, 0, 1); PG8_SCHED; PG8_LDA(At, 0, 0); PG8_STAGE(PG8_SA(1, 1), a1 + hstepA, voffA);
;             PG8_WAIT_V(8); PG8_WAIT_L(0); PG8_BAR; PG8_MMA(0, 0, At, B0); PG8_MMA(0, 1, At, B1); PG8_BAR; PG8_SCHED;
;             PG8_LDA(At, 0, 1); PG8_STAGE(PG8_SB(0, 0), b2, voffB); PG8_STAGE(PG8_SB(0, 1), b2 + hstepB, voffB); PG8_STAGE(PG8_SA(0, 0), a2, voffA);
;             PG8_WAIT_V(8); PG8_WAIT_L(0); PG8_BAR; PG8_MMA(1, 0, At, B0); PG8_MMA(1, 1, At, B1); PG8_BAR; PG8_SCHED;
;             PG8_LDB(B0, 1, 0); PG8_LDB(B1, 1, 1); PG8_SCHED; PG8_LDA(At, 1, 0); PG8_STAGE(PG8_SA(0, 1), a2 + hstepA, voffA);
;             PG8_WAIT_V(8); PG8_WAIT_L(0); PG8_BAR; PG8_MMA(0, 0, At, B0); PG8_MMA(0, 1, At, B1); PG8_BAR; PG8_SCHED;
;             PG8_LDA(At, 1, 1); PG8_STAGE(PG8_SB(1, 0), b3, voffB); PG8_STAGE(PG8_SB(1, 1), b3 + hstepB, voffB); PG8_STAGE(PG8_SA(1, 0), a3, voffA);
;             PG8_WAIT_V(8); PG8_WAIT_L(0); PG8_BAR; PG8_MMA(1, 0, At, B0); PG8_MMA(1, 1, At, B1); PG8_BAR; PG8_SCHED;
	s_setprio 1
	s_waitcnt lgkmcnt(0)
	v_mfma_f32_16x16x32_bf16 v[64:67], v[136:139], v[170:173], v[64:67]
	v_mfma_f32_16x16x32_bf16 v[60:63], v[146:149], v[170:173], v[60:63]
	v_mfma_f32_16x16x32_bf16 v[48:51], v[136:139], v[186:189], v[48:51]
	v_mfma_f32_16x16x32_bf16 v[44:47], v[146:149], v[186:189], v[44:47]
	v_mfma_f32_16x16x32_bf16 v[32:35], v[136:139], v[198:201], v[32:35]
	v_mfma_f32_16x16x32_bf16 v[28:31], v[146:149], v[198:201], v[28:31]
	v_mfma_f32_16x16x32_bf16 v[12:15], v[136:139], v[206:209], v[12:15]
	v_mfma_f32_16x16x32_bf16 v[8:11], v[146:149], v[206:209], v[8:11]
	v_mfma_f32_16x16x32_bf16 v[64:67], v[140:143], v[174:177], v[64:67]
	v_mfma_f32_16x16x32_bf16 v[60:63], v[150:153], v[174:177], v[60:63]
	v_mfma_f32_16x16x32_bf16 v[48:51], v[140:143], v[190:193], v[48:51]
	v_mfma_f32_16x16x32_bf16 v[44:47], v[150:153], v[190:193], v[44:47]
	v_mfma_f32_16x16x32_bf16 v[32:35], v[140:143], v[202:205], v[32:35]
	v_mfma_f32_16x16x32_bf16 v[28:31], v[150:153], v[202:205], v[28:31]
	v_mfma_f32_16x16x32_bf16 v[12:15], v[140:143], v[210:213], v[12:15]
	v_mfma_f32_16x16x32_bf16 v[8:11], v[150:153], v[210:213], v[8:11]
	v_mfma_f32_16x16x32_bf16 v[56:59], v[154:157], v[170:173], v[56:59]
	v_mfma_f32_16x16x32_bf16 v[52:55], v[162:165], v[170:173], v[52:55]
	v_mfma_f32_16x16x32_bf16 v[40:43], v[154:157], v[186:189], v[40:43]
	v_mfma_f32_16x16x32_bf16 v[36:39], v[162:165], v[186:189], v[36:39]
	v_mfma_f32_16x16x32_bf16 v[24:27], v[154:157], v[198:201], v[24:27]
	v_mfma_f32_16x16x32_bf16 v[20:23], v[162:165], v[198:201], v[20:23]
	v_mfma_f32_16x16x32_bf16 v[4:7], v[154:157], v[206:209], v[4:7]
	v_mfma_f32_16x16x32_bf16 v[0:3], v[162:165], v[206:209], v[0:3]
	v_mfma_f32_16x16x32_bf16 v[56:59], v[158:161], v[174:177], v[56:59]
	v_mfma_f32_16x16x32_bf16 v[52:55], v[166:169], v[174:177], v[52:55]
	v_mfma_f32_16x16x32_bf16 v[40:43], v[158:161], v[190:193], v[40:43]
	v_mfma_f32_16x16x32_bf16 v[36:39], v[166:169], v[190:193], v[36:39]
	v_mfma_f32_16x16x32_bf16 v[24:27], v[158:161], v[202:205], v[24:27]
	v_mfma_f32_16x16x32_bf16 v[20:23], v[166:169], v[202:205], v[20:23]
	v_mfma_f32_16x16x32_bf16 v[4:7], v[158:161], v[210:213], v[4:7]
	v_mfma_f32_16x16x32_bf16 v[0:3], v[166:169], v[210:213], v[0:3]
	s_setprio 0
	s_barrier
	v_add_u32_e32 v150, s58, v144
	v_add_u32_e32 v166, s45, v144
	ds_read_b128 v[136:139], v150
	ds_read_b128 v[140:143], v150 offset:1024
	ds_read_b128 v[146:149], v150 offset:2048
	ds_read_b128 v[150:153], v150 offset:3072
	ds_read_b128 v[154:157], v166
	ds_read_b128 v[158:161], v166 offset:1024
	ds_read_b128 v[162:165], v166 offset:2048
	ds_read_b128 v[166:169], v166 offset:3072
	s_mov_b32 m0, s57
	v_lshl_add_u64 v[220:221], s[20:21], 0, v[134:135]
	ds_read_b128 v[170:173], v145 offset:32768
	ds_read_b128 v[174:177], v145 offset:33792
	ds_read_b128 v[186:189], v145 offset:34816
	ds_read_b128 v[190:193], v145 offset:35840
	ds_read_b128 v[198:201], v145 offset:36864
	ds_read_b128 v[202:205], v145 offset:37888
	ds_read_b128 v[206:209], v145 offset:38912
	ds_read_b128 v[210:213], v145 offset:39936
	global_load_lds_dwordx4 v[220:221], off
	v_lshl_add_u64 v[220:221], s[20:21], 0, v[132:133]
	s_mov_b32 m0, s25
	s_nop 0
	global_load_lds_dwordx4 v[220:221], off
	s_waitcnt vmcnt(8)
	s_waitcnt lgkmcnt(0)
	s_barrier
	s_setprio 1
	s_waitcnt lgkmcnt(0)
	v_mfma_f32_16x16x32_bf16 v[128:131], v[136:139], v[170:173], v[128:131]
	v_mfma_f32_16x16x32_bf16 v[124:127], v[146:149], v[170:173], v[124:127]
	v_mfma_f32_16x16x32_bf16 v[112:115], v[136:139], v[186:189], v[112:115]
	v_mfma_f32_16x16x32_bf16 v[108:111], v[146:149], v[186:189], v[108:111]
	v_mfma_f32_16x16x32_bf16 v[96:99], v[136:139], v[198:201], v[96:99]
	v_mfma_f32_16x16x32_bf16 v[92:95], v[146:149], v[198:201], v[92:95]
	v_mfma_f32_16x16x32_bf16 v[80:83], v[136:139], v[206:209], v[80:83]
	v_mfma_f32_16x16x32_bf16 v[76:79], v[146:149], v[206:209], v[76:79]
	v_mfma_f32_16x16x32_bf16 v[128:131], v[140:143], v[174:177], v[128:131]
	v_mfma_f32_16x16x32_bf16 v[124:127], v[150:153], v[174:177], v[124:127]
	v_mfma_f32_16x16x32_bf16 v[112:115], v[140:143], v[190:193], v[112:115]
	v_mfma_f32_16x16x32_bf16 v[108:111], v[150:153], v[190:193], v[108:111]
	v_mfma_f32_16x16x32_bf16 v[96:99], v[140:143], v[202:205], v[96:99]
	v_mfma_f32_16x16x32_bf16 v[92:95], v[150:153], v[202:205], v[92:95]
	v_mfma_f32_16x16x32_bf16 v[80:83], v[140:143], v[210:213], v[80:83]
	v_mfma_f32_16x16x32_bf16 v[76:79], v[150:153], v[210:213], v[76:79]
	v_mfma_f32_16x16x32_bf16 v[120:123], v[154:157], v[170:173], v[120:123]
	v_mfma_f32_16x16x32_bf16 v[116:119], v[162:165], v[170:173], v[116:119]
	v_mfma_f32_16x16x32_bf16 v[104:107], v[154:157], v[186:189], v[104:107]
	v_mfma_f32_16x16x32_bf16 v[100:103], v[162:165], v[186:189], v[100:103]
	v_mfma_f32_16x16x32_bf16 v[88:91], v[154:157], v[198:201], v[88:91]
	v_mfma_f32_16x16x32_bf16 v[84:87], v[162:165], v[198:201], v[84:87]
	v_mfma_f32_16x16x32_bf16 v[72:75], v[154:157], v[206:209], v[72:75]
	v_mfma_f32_16x16x32_bf16 v[68:71], v[162:165], v[206:209], v[68:71]
	v_mfma_f32_16x16x32_bf16 v[120:123], v[158:161], v[174:177], v[120:123]
	v_mfma_f32_16x16x32_bf16 v[116:119], v[166:169], v[174:177], v[116:119]
	v_mfma_f32_16x16x32_bf16 v[104:107], v[158:161], v[190:193], v[104:107]
	v_mfma_f32_16x16x32_bf16 v[100:103], v[166:169], v[190:193], v[100:103]
	v_mfma_f32_16x16x32_bf16 v[88:91], v[158:161], v[202:205], v[88:91]
	v_mfma_f32_16x16x32_bf16 v[84:87], v[166:169], v[202:205], v[84:87]
	v_mfma_f32_16x16x32_bf16 v[72:75], v[158:161], v[210:213], v[72:75]
	v_mfma_f32_16x16x32_bf16 v[68:71], v[166:169], v[210:213], v[68:71]
	s_setprio 0
	s_barrier
; #define PG8_STAGE(bufoff, gbase, voff) do { _Pragma("unroll") for (int _i = 0; _i < 2; ++_i) \
;         __builtin_amdgcn_global_load_lds((const unsigned*)((const char*)(gbase) + (voff)[_i]), (LAS unsigned*)(lds + (bufoff) + ldsw + _i * 8192), 16, 0, 0); } while (0)
; #define PG8_LDA(dst, b, h) do { _Pragma("unroll") for (int m = 0; m < 4; ++m) _Pragma("unroll") for (int k = 0; k < 2; ++k) dst[m][k] = *(const LAS bf16x8*)(lds + PG8_SA(b, h) + aoff + m * 2048 + k * 1024); } while (0)
; #define PG8_LDB(dst, b, h) do { _Pragma("unroll") for (int n = 0; n < 2; ++n) _Pragma("unroll") for (int k = 0; k < 2; ++k) dst[n][k] = *(const LAS bf16x8*)(lds + PG8_SB(b, h) + boff + n * 2048 + k * 1024); } while (0)
; #define PG8_MMA(ai, bj, At, Bt) do { __builtin_amdgcn_s_setprio(1); _Pragma("unroll") for (int m = 0; m < 4; ++m) _Pragma("unroll") for (int n = 0; n < 2; ++n) _Pragma("unroll") for (int k = 0; k < 2; ++k) \
;         acc[ai][bj][m][n] = __builtin_amdgcn_mfma_f32_16x16x32_bf16(Bt[n][k], At[m][k], acc[ai][bj][m][n], 0, 0, 0); __builtin_amdgcn_s_setprio(0); } while (0)
; template <class Epi, class Sched, bool ALIGN_EPI = true, bool SP2 = true>
; __device__ __forceinline__ void gemm_phase(LAS unsigned char* lds, const Gemm g, const Sched& S, const Epi& E) {
;     ...
;             PG8_LDB(B0, 0, 0); PG8_LDB(B1, 0, 1); PG8_SCHED; PG8_LDA(At, 0, 0); PG8_STAGE(PG8_SA(1, 1), a1 + hstepA, voffA);
;             PG8_WAIT_V(8); PG8_WAIT_L(0); PG8_BAR; PG8_MMA(0, 0, At, B0); PG8_MMA(0, 1, At, B1); PG8_BAR; PG8_SCHED;
;             PG8_LDA(At, 0, 1); PG8_STAGE(PG8_SB(0, 0), b2, voffB); PG8_STAGE(PG8_SB(0, 1), b2 + hstepB, voffB); PG8_STAGE(PG8_SA(0, 0), a2, voffA);
;             PG8_WAIT_V(8); PG8_WAIT_L(0); PG8_BAR; PG8_MMA(1, 0, At, B0); PG8_MMA(1, 1, At, B1); PG8_BAR; PG8_SCHED;
;             PG8_LDB(B0, 1, 0); PG8_LDB(B1, 1, 1); PG8_SCHED; PG8_LDA(At, 1, 0); PG8_STAGE(PG8_SA(0, 1), a2 + hstepA, voffA);
;             PG8_WAIT_V(8); PG8_WAIT_L(0); PG8_BAR; PG8_MMA(0, 0, At, B0); PG8_MMA(0, 1, At, B1); PG8_BAR; PG8_SCHED;
;             PG8_LDA(At, 1, 1); PG8_STAGE(PG8_SB(1, 0), b3, voffB); PG8_STAGE(PG8_SB(1, 1), b3 + hstepB, voffB); PG8_STAGE(PG8_SA(1, 0), a3, voffA);
;             PG8_WAIT_V(8); PG8_WAIT_L(0); PG8_BAR; PG8_MMA(1, 0, At, B0); PG8_MMA(1, 1, At, B1); PG8_BAR; PG8_SCHED;
;         }
;         if constexpr (ALIGN_EPI) { if (wr == 0) PG8_BAR; }
	s_mov_b32 m0, s30
	v_lshl_add_u64 v[178:179], v[178:179], 0, s[14:15]
	ds_read_b128 v[170:173], v145 offset:49152
	ds_read_b128 v[174:177], v145 offset:50176
	ds_read_b128 v[186:189], v145 offset:51200
	ds_read_b128 v[190:193], v145 offset:52224
	ds_read_b128 v[198:201], v145 offset:53248
	ds_read_b128 v[202:205], v145 offset:54272
	ds_read_b128 v[206:209], v145 offset:55296
	ds_read_b128 v[210:213], v145 offset:56320
	global_load_lds_dwordx4 v[178:179], off
	v_lshl_add_u64 v[178:179], v[182:183], 0, s[14:15]
	s_mov_b32 m0, s9
	s_nop 0
	global_load_lds_dwordx4 v[178:179], off
	v_lshl_add_u64 v[178:179], s[18:19], 0, v[18:19]
	s_mov_b32 m0, s60
	s_nop 0
	global_load_lds_dwordx4 v[178:179], off
	v_lshl_add_u64 v[178:179], s[18:19], 0, v[16:17]
	s_mov_b32 m0, s38
	s_nop 0
	global_load_lds_dwordx4 v[178:179], off
	v_lshl_add_u64 v[178:179], v[214:215], 0, s[14:15]
	s_mov_b32 m0, s31
	s_nop 0
	global_load_lds_dwordx4 v[178:179], off
	v_lshl_add_u64 v[178:179], v[218:219], 0, s[14:15]
	s_mov_b32 m0, s6
	s_nop 0
	global_load_lds_dwordx4 v[178:179], off
	s_waitcnt vmcnt(8)
	s_waitcnt lgkmcnt(0)
	s_barrier
	s_setprio 1
	s_waitcnt lgkmcnt(0)
	v_mfma_f32_16x16x32_bf16 v[64:67], v[136:139], v[170:173], v[64:67]
	v_mfma_f32_16x16x32_bf16 v[60:63], v[146:149], v[170:173], v[60:63]
	v_mfma_f32_16x16x32_bf16 v[48:51], v[136:139], v[186:189], v[48:51]
	v_mfma_f32_16x16x32_bf16 v[44:47], v[146:149], v[186:189], v[44:47]
	v_mfma_f32_16x16x32_bf16 v[32:35], v[136:139], v[198:201], v[32:35]
	v_mfma_f32_16x16x32_bf16 v[28:31], v[146:149], v[198:201], v[28:31]
	v_mfma_f32_16x16x32_bf16 v[12:15], v[136:139], v[206:209], v[12:15]
	v_mfma_f32_16x16x32_bf16 v[8:11], v[146:149], v[206:209], v[8:11]
	v_mfma_f32_16x16x32_bf16 v[64:67], v[140:143], v[174:177], v[64:67]
	v_mfma_f32_16x16x32_bf16 v[60:63], v[150:153], v[174:177], v[60:63]
	v_mfma_f32_16x16x32_bf16 v[48:51], v[140:143], v[190:193], v[48:51]
	v_mfma_f32_16x16x32_bf16 v[44:47], v[150:153], v[190:193], v[44:47]
	v_mfma_f32_16x16x32_bf16 v[32:35], v[140:143], v[202:205], v[32:35]
	v_mfma_f32_16x16x32_bf16 v[28:31], v[150:153], v[202:205], v[28:31]
	v_mfma_f32_16x16x32_bf16 v[12:15], v[140:143], v[210:213], v[12:15]
	v_mfma_f32_16x16x32_bf16 v[8:11], v[150:153], v[210:213], v[8:11]
	v_mfma_f32_16x16x32_bf16 v[56:59], v[154:157], v[170:173], v[56:59]
	v_mfma_f32_16x16x32_bf16 v[52:55], v[162:165], v[170:173], v[52:55]
	v_mfma_f32_16x16x32_bf16 v[40:43], v[154:157], v[186:189], v[40:43]
	v_mfma_f32_16x16x32_bf16 v[36:39], v[162:165], v[186:189], v[36:39]
	v_mfma_f32_16x16x32_bf16 v[24:27], v[154:157], v[198:201], v[24:27]
	v_mfma_f32_16x16x32_bf16 v[20:23], v[162:165], v[198:201], v[20:23]
	v_mfma_f32_16x16x32_bf16 v[4:7], v[154:157], v[206:209], v[4:7]
	v_mfma_f32_16x16x32_bf16 v[0:3], v[162:165], v[206:209], v[0:3]
	v_mfma_f32_16x16x32_bf16 v[56:59], v[158:161], v[174:177], v[56:59]
	v_mfma_f32_16x16x32_bf16 v[52:55], v[166:169], v[174:177], v[52:55]
	v_mfma_f32_16x16x32_bf16 v[40:43], v[158:161], v[190:193], v[40:43]
	v_mfma_f32_16x16x32_bf16 v[36:39], v[166:169], v[190:193], v[36:39]
	v_mfma_f32_16x16x32_bf16 v[24:27], v[158:161], v[202:205], v[24:27]
	v_mfma_f32_16x16x32_bf16 v[20:23], v[166:169], v[202:205], v[20:23]
	v_mfma_f32_16x16x32_bf16 v[4:7], v[158:161], v[210:213], v[4:7]
	v_mfma_f32_16x16x32_bf16 v[0:3], v[166:169], v[210:213], v[0:3]
	s_setprio 0
	s_barrier
	s_movk_i32 s9, 0x100
	s_andn2_b64 vcc, exec, s[42:43]
	s_mov_b64 s[18:19], -1
	s_mov_b64 s[42:43], 0
	s_cbranch_vccz .LBB0_676
	s_and_b64 vcc, exec, s[34:35]
	s_cbranch_vccz .LBB0_679
	s_barrier

; #define PG8_STAGE(bufoff, gbase, voff) do { _Pragma("unroll") for (int _i = 0; _i < 2; ++_i) \
;         __builtin_amdgcn_global_load_lds((const unsigned*)((const char*)(gbase) + (voff)[_i]), (LAS unsigned*)(lds + (bufoff) + ldsw + _i * 8192), 16, 0, 0); } while (0)
; #define PG8_LDA(dst, b, h) do { _Pragma("unroll") for (int m = 0; m < 4; ++m) _Pragma("unroll") for (int k = 0; k < 2; ++k) dst[m][k] = *(const LAS bf16x8*)(lds + PG8_SA(b, h) + aoff + m * 2048 + k * 1024); } while (0)
; #define PG8_LDB(dst, b, h) do { _Pragma("unroll") for (int n = 0; n < 2; ++n) _Pragma("unroll") for (int k = 0; k < 2; ++k) dst[n][k] = *(const LAS bf16x8*)(lds + PG8_SB(b, h) + boff + n * 2048 + k * 1024); } while (0)
; #define PG8_WAIT_V(n) asm volatile("s_waitcnt vmcnt(" #n ")" ::: "memory")
; template <class Epi, class Sched, bool ALIGN_EPI = true, bool SP2 = true>
; __device__ __forceinline__ void gemm_phase(LAS unsigned char* lds, const Gemm g, const Sched& S, const Epi& E) {
;     ...
;         for (int t = 0; t < nt; t += 2) {
;             const bool last = (t == nt - 2);
;             const char* a1 = cA + (size_t)(t + 1) * kstep;
;             const char* a2 = last ? nA : cA + (size_t)(t + 2) * kstep; const char* b2 = last ? nB : cB + (size_t)(t + 2) * kstep;
;             const char* a3 = a2 + kstep; const char* b3 = b2 + kstep;
;             PG8_LDB(B0, 0, 0); PG8_LDB(B1, 0, 1); PG8_SCHED; PG8_LDA(At, 0, 0); PG8_STAGE(PG8_SA(1, 1), a1 + hstepA, voffA);
;             PG8_WAIT_V(8); PG8_WAIT_L(0); PG8_BAR; PG8_MMA(0, 0, At, B0); PG8_MMA(0, 1, At, B1); PG8_BAR; PG8_SCHED;
;             PG8_LDA(At, 0, 1); PG8_STAGE(PG8_SB(0, 0), b2, voffB); PG8_STAGE(PG8_SB(0, 1), b2 + hstepB, voffB); PG8_STAGE(PG8_SA(0, 0), a2, voffA);
;             PG8_WAIT_V(8); PG8_WAIT_L(0); PG8_BAR; PG8_MMA(1, 0, At, B0); PG8_MMA(1, 1, At, B1); PG8_BAR; PG8_SCHED;
;             PG8_LDB(B0, 1, 0); PG8_LDB(B1, 1, 1); PG8_SCHED; PG8_LDA(At, 1, 0); PG8_STAGE(PG8_SA(0, 1), a2 + hstepA, voffA);
;             PG8_WAIT_V(8); PG8_WAIT_L(0); PG8_BAR; PG8_MMA(0, 0, At, B0); PG8_MMA(0, 1, At, B1); PG8_BAR; PG8_SCHED;
;             PG8_LDA(At, 1, 1); PG8_STAGE(PG8_SB(1, 0), b3, voffB); PG8_STAGE(PG8_SB(1, 1), b3 + hstepB, voffB); PG8_STAGE(PG8_SA(1, 0), a3, voffA);
;             PG8_WAIT_V(8); PG8_WAIT_L(0); PG8_BAR; PG8_MMA(1, 0, At, B0); PG8_MMA(1, 1, At, B1); PG8_BAR; PG8_SCHED;
.LBB0_884:
	s_add_u32 s18, s54, 0xfffc0080
	s_addc_u32 s19, s55, -1
	s_add_i32 s58, 0, 0x10000
	s_cmp_eq_u32 s49, 12
	s_cselect_b32 s21, s22, s19
	s_cselect_b32 s20, s23, s18
	v_add_u32_e32 v140, s58, v142
	s_cselect_b32 s19, s2, s45
	s_cselect_b32 s18, s43, s30
	s_add_i32 s61, 0, 0x14000
	ds_read_b128 v[144:147], v140
	ds_read_b128 v[148:151], v140 offset:1024
	ds_read_b128 v[152:155], v140 offset:2048
	ds_read_b128 v[156:159], v140 offset:3072
	v_add_u32_e32 v140, s61, v142
	ds_read_b128 v[160:163], v140
	ds_read_b128 v[164:167], v140 offset:1024
	ds_read_b128 v[168:171], v140 offset:2048
	ds_read_b128 v[172:175], v140 offset:3072
	v_lshl_add_u64 v[140:141], s[54:55], 0, v[136:137]
	s_add_i32 m0, s53, 0xc000
	ds_read_b128 v[186:189], v143
	ds_read_b128 v[190:193], v143 offset:1024
	ds_read_b128 v[198:201], v143 offset:2048
	ds_read_b128 v[202:205], v143 offset:3072
	ds_read_b128 v[206:209], v143 offset:4096
	ds_read_b128 v[210:213], v143 offset:5120
	ds_read_b128 v[218:221], v143 offset:6144
	ds_read_b128 v[222:225], v143 offset:7168
	global_load_lds_dwordx4 v[140:141], off
	v_lshl_add_u64 v[140:141], s[54:55], 0, v[138:139]
	s_add_i32 m0, s53, 0xe000
	s_nop 0
	global_load_lds_dwordx4 v[140:141], off
	s_waitcnt vmcnt(8)
	s_waitcnt lgkmcnt(0)
	s_barrier
	s_setprio 1
	s_waitcnt lgkmcnt(0)
	v_mfma_f32_16x16x32_bf16 v[128:131], v[144:147], v[186:189], v[128:131]
	v_mfma_f32_16x16x32_bf16 v[124:127], v[152:155], v[186:189], v[124:127]
	v_mfma_f32_16x16x32_bf16 v[120:123], v[144:147], v[198:201], v[120:123]
	v_mfma_f32_16x16x32_bf16 v[112:115], v[152:155], v[198:201], v[112:115]
	v_mfma_f32_16x16x32_bf16 v[104:107], v[144:147], v[206:209], v[104:107]
	v_mfma_f32_16x16x32_bf16 v[96:99], v[152:155], v[206:209], v[96:99]
	v_mfma_f32_16x16x32_bf16 v[88:91], v[144:147], v[218:221], v[88:91]
	v_mfma_f32_16x16x32_bf16 v[80:83], v[152:155], v[218:221], v[80:83]
	v_mfma_f32_16x16x32_bf16 v[128:131], v[148:151], v[190:193], v[128:131]
	v_mfma_f32_16x16x32_bf16 v[124:127], v[156:159], v[190:193], v[124:127]
	v_mfma_f32_16x16x32_bf16 v[120:123], v[148:151], v[202:205], v[120:123]
	v_mfma_f32_16x16x32_bf16 v[112:115], v[156:159], v[202:205], v[112:115]
	v_mfma_f32_16x16x32_bf16 v[104:107], v[148:151], v[210:213], v[104:107]
	v_mfma_f32_16x16x32_bf16 v[96:99], v[156:159], v[210:213], v[96:99]
	v_mfma_f32_16x16x32_bf16 v[88:91], v[148:151], v[222:225], v[88:91]
	v_mfma_f32_16x16x32_bf16 v[80:83], v[156:159], v[222:225], v[80:83]
	v_mfma_f32_16x16x32_bf16 v[116:119], v[160:163], v[186:189], v[116:119]
	v_mfma_f32_16x16x32_bf16 v[108:111], v[168:171], v[186:189], v[108:111]
	v_mfma_f32_16x16x32_bf16 v[100:103], v[160:163], v[198:201], v[100:103]
	v_mfma_f32_16x16x32_bf16 v[92:95], v[168:171], v[198:201], v[92:95]
	v_mfma_f32_16x16x32_bf16 v[84:87], v[160:163], v[206:209], v[84:87]
	v_mfma_f32_16x16x32_bf16 v[76:79], v[168:171], v[206:209], v[76:79]
	v_mfma_f32_16x16x32_bf16 v[72:75], v[160:163], v[218:221], v[72:75]
	v_mfma_f32_16x16x32_bf16 v[68:71], v[168:171], v[218:221], v[68:71]
	v_mfma_f32_16x16x32_bf16 v[116:119], v[164:167], v[190:193], v[116:119]
	v_mfma_f32_16x16x32_bf16 v[108:111], v[172:175], v[190:193], v[108:111]
	v_mfma_f32_16x16x32_bf16 v[100:103], v[164:167], v[202:205], v[100:103]
	v_mfma_f32_16x16x32_bf16 v[92:95], v[172:175], v[202:205], v[92:95]
	v_mfma_f32_16x16x32_bf16 v[84:87], v[164:167], v[210:213], v[84:87]
	v_mfma_f32_16x16x32_bf16 v[76:79], v[172:175], v[210:213], v[76:79]
	v_mfma_f32_16x16x32_bf16 v[72:75], v[164:167], v[222:225], v[72:75]
	v_mfma_f32_16x16x32_bf16 v[68:71], v[172:175], v[222:225], v[68:71]
	s_setprio 0
	s_barrier
	s_add_i32 s58, s58, s39
	v_lshl_add_u64 v[140:141], s[18:19], 0, v[18:19]
	s_mov_b32 m0, s58
	ds_read_b128 v[186:189], v143 offset:16384
	ds_read_b128 v[190:193], v143 offset:17408
	ds_read_b128 v[198:201], v143 offset:18432
	ds_read_b128 v[202:205], v143 offset:19456
	ds_read_b128 v[206:209], v143 offset:20480
	ds_read_b128 v[210:213], v143 offset:21504
	ds_read_b128 v[218:221], v143 offset:22528
	ds_read_b128 v[222:225], v143 offset:23552
	global_load_lds_dwordx4 v[140:141], off
	s_add_i32 m0, s58, 0x2000
	s_add_u32 s58, s18, 0x40000
	v_lshl_add_u64 v[176:177], s[18:19], 0, v[16:17]
	s_addc_u32 s59, s19, 0
	s_add_i32 s61, s61, s39
	global_load_lds_dwordx4 v[176:177], off
	v_lshl_add_u64 v[178:179], s[58:59], 0, v[18:19]
	s_mov_b32 m0, s61
	v_lshl_add_u64 v[182:183], s[20:21], 0, v[132:133]
	global_load_lds_dwordx4 v[178:179], off
	v_lshl_add_u64 v[178:179], s[58:59], 0, v[16:17]
	s_add_i32 m0, s61, 0x2000
	s_nop 0
	global_load_lds_dwordx4 v[178:179], off
	v_lshl_add_u64 v[178:179], s[20:21], 0, v[134:135]
	s_mov_b32 m0, s53
	s_nop 0
	global_load_lds_dwordx4 v[178:179], off
	s_mov_b32 m0, s56
	s_nop 0
	global_load_lds_dwordx4 v[182:183], off
	s_waitcnt vmcnt(8)
	s_waitcnt lgkmcnt(0)
	s_barrier
; #define PG8_STAGE(bufoff, gbase, voff) do { _Pragma("unroll") for (int _i = 0; _i < 2; ++_i) \
;         __builtin_amdgcn_global_load_lds((const unsigned*)((const char*)(gbase) + (voff)[_i]), (LAS unsigned*)(lds + (bufoff) + ldsw + _i * 8192), 16, 0, 0); } while (0)
; #define PG8_LDA(dst, b, h) do { _Pragma("unroll") for (int m = 0; m < 4; ++m) _Pragma("unroll") for (int k = 0; k < 2; ++k) dst[m][k] = *(const LAS bf16x8*)(lds + PG8_SA(b, h) + aoff + m * 2048 + k * 1024); } while (0)
; #define PG8_LDB(dst, b, h) do { _Pragma("unroll") for (int n = 0; n < 2; ++n) _Pragma("unroll") for (int k = 0; k < 2; ++k) dst[n][k] = *(const LAS bf16x8*)(lds + PG8_SB(b, h) + boff + n * 2048 + k * 1024); } while (0)
; #define PG8_MMA(ai, bj, At, Bt) do { __builtin_amdgcn_s_setprio(1); _Pragma("unroll") for (int m = 0; m < 4; ++m) _Pragma("unroll") for (int n = 0; n < 2; ++n) _Pragma("unroll") for (int k = 0; k < 2; ++k) \
;         acc[ai][bj][m][n] = __builtin_amdgcn_mfma_f32_16x16x32_bf16(Bt[n][k], At[m][k], acc[ai][bj][m][n], 0, 0, 0); __builtin_amdgcn_s_setprio(0); } while (0)
; #define PG8_WAIT_V(n) asm volatile("s_waitcnt vmcnt(" #n ")" ::: "memory")
; template <class Epi, class Sched, bool ALIGN_EPI = true, bool SP2 = true>
; __device__ __forceinline__ void gemm_phase(LAS unsigned char* lds, const Gemm g, const Sched& S, const Epi& E) {
;     ...
;             PG8_LDB(B0, 0, 0); PG8_LDB(B1, 0, 1); PG8_SCHED; PG8_LDA(At, 0, 0); PG8_STAGE(PG8_SA(1, 1), a1 + hstepA, voffA);
;             PG8_WAIT_V(8); PG8_WAIT_L(0); PG8_BAR; PG8_MMA(0, 0, At, B0); PG8_MMA(0, 1, At, B1); PG8_BAR; PG8_SCHED;
;             PG8_LDA(At, 0, 1); PG8_STAGE(PG8_SB(0, 0), b2, voffB); PG8_STAGE(PG8_SB(0, 1), b2 + hstepB, voffB); PG8_STAGE(PG8_SA(0, 0), a2, voffA);
;             PG8_WAIT_V(8); PG8_WAIT_L(0); PG8_BAR; PG8_MMA(1, 0, At, B0); PG8_MMA(1, 1, At, B1); PG8_BAR; PG8_SCHED;
;             PG8_LDB(B0, 1, 0); PG8_LDB(B1, 1, 1); PG8_SCHED; PG8_LDA(At, 1, 0); PG8_STAGE(PG8_SA(0, 1), a2 + hstepA, voffA);
;             PG8_WAIT_V(8); PG8_WAIT_L(0); PG8_BAR; PG8_MMA(0, 0, At, B0); PG8_MMA(0, 1, At, B1); PG8_BAR; PG8_SCHED;
;             PG8_LDA(At, 1, 1); PG8_STAGE(PG8_SB(1, 0), b3, voffB); PG8_STAGE(PG8_SB(1, 1), b3 + hstepB, voffB); PG8_STAGE(PG8_SA(1, 0), a3, voffA);
;             PG8_WAIT_V(8); PG8_WAIT_L(0); PG8_BAR; PG8_MMA(1, 0, At, B0); PG8_MMA(1, 1, At, B1); PG8_BAR; PG8_SCHED;
	s_setprio 1
	s_waitcnt lgkmcnt(0)
	v_mfma_f32_16x16x32_bf16 v[64:67], v[144:147], v[186:189], v[64:67]
	v_mfma_f32_16x16x32_bf16 v[60:63], v[152:155], v[186:189], v[60:63]
	v_mfma_f32_16x16x32_bf16 v[56:59], v[144:147], v[198:201], v[56:59]
	v_mfma_f32_16x16x32_bf16 v[48:51], v[152:155], v[198:201], v[48:51]
	v_mfma_f32_16x16x32_bf16 v[40:43], v[144:147], v[206:209], v[40:43]
	v_mfma_f32_16x16x32_bf16 v[32:35], v[152:155], v[206:209], v[32:35]
	v_mfma_f32_16x16x32_bf16 v[24:27], v[144:147], v[218:221], v[24:27]
	v_mfma_f32_16x16x32_bf16 v[12:15], v[152:155], v[218:221], v[12:15]
	v_mfma_f32_16x16x32_bf16 v[64:67], v[148:151], v[190:193], v[64:67]
	v_mfma_f32_16x16x32_bf16 v[60:63], v[156:159], v[190:193], v[60:63]
	v_mfma_f32_16x16x32_bf16 v[56:59], v[148:151], v[202:205], v[56:59]
	v_mfma_f32_16x16x32_bf16 v[48:51], v[156:159], v[202:205], v[48:51]
	v_mfma_f32_16x16x32_bf16 v[40:43], v[148:151], v[210:213], v[40:43]
	v_mfma_f32_16x16x32_bf16 v[32:35], v[156:159], v[210:213], v[32:35]
	v_mfma_f32_16x16x32_bf16 v[24:27], v[148:151], v[222:225], v[24:27]
	v_mfma_f32_16x16x32_bf16 v[12:15], v[156:159], v[222:225], v[12:15]
	v_mfma_f32_16x16x32_bf16 v[52:55], v[160:163], v[186:189], v[52:55]
	v_mfma_f32_16x16x32_bf16 v[44:47], v[168:171], v[186:189], v[44:47]
	v_mfma_f32_16x16x32_bf16 v[36:39], v[160:163], v[198:201], v[36:39]
	v_mfma_f32_16x16x32_bf16 v[28:31], v[168:171], v[198:201], v[28:31]
	v_mfma_f32_16x16x32_bf16 v[20:23], v[160:163], v[206:209], v[20:23]
	v_mfma_f32_16x16x32_bf16 v[8:11], v[168:171], v[206:209], v[8:11]
	v_mfma_f32_16x16x32_bf16 v[4:7], v[160:163], v[218:221], v[4:7]
	v_mfma_f32_16x16x32_bf16 v[0:3], v[168:171], v[218:221], v[0:3]
	v_mfma_f32_16x16x32_bf16 v[52:55], v[164:167], v[190:193], v[52:55]
	v_mfma_f32_16x16x32_bf16 v[44:47], v[172:175], v[190:193], v[44:47]
	v_mfma_f32_16x16x32_bf16 v[36:39], v[164:167], v[202:205], v[36:39]
	v_mfma_f32_16x16x32_bf16 v[28:31], v[172:175], v[202:205], v[28:31]
	v_mfma_f32_16x16x32_bf16 v[20:23], v[164:167], v[210:213], v[20:23]
	v_mfma_f32_16x16x32_bf16 v[8:11], v[172:175], v[210:213], v[8:11]
	v_mfma_f32_16x16x32_bf16 v[4:7], v[164:167], v[222:225], v[4:7]
	v_mfma_f32_16x16x32_bf16 v[0:3], v[172:175], v[222:225], v[0:3]
	s_setprio 0
	s_barrier
	s_add_i32 s58, 0, 0x18000
	s_add_i32 s59, 0, 0x1c000
	v_add_u32_e32 v156, s58, v142
	v_add_u32_e32 v172, s59, v142
	ds_read_b128 v[144:147], v156
	ds_read_b128 v[148:151], v156 offset:1024
	ds_read_b128 v[152:155], v156 offset:2048
	ds_read_b128 v[156:159], v156 offset:3072
	ds_read_b128 v[160:163], v172
	ds_read_b128 v[164:167], v172 offset:1024
	ds_read_b128 v[168:171], v172 offset:2048
	ds_read_b128 v[172:175], v172 offset:3072
	s_add_u32 s20, s20, 0x40000
	s_addc_u32 s21, s21, 0
	s_mov_b32 m0, s57
	v_lshl_add_u64 v[214:215], s[20:21], 0, v[134:135]
	ds_read_b128 v[186:189], v143 offset:32768
	ds_read_b128 v[190:193], v143 offset:33792
	ds_read_b128 v[198:201], v143 offset:34816
	ds_read_b128 v[202:205], v143 offset:35840
	ds_read_b128 v[206:209], v143 offset:36864
	ds_read_b128 v[210:213], v143 offset:37888
	ds_read_b128 v[218:221], v143 offset:38912
	ds_read_b128 v[222:225], v143 offset:39936
	global_load_lds_dwordx4 v[214:215], off
	v_lshl_add_u64 v[214:215], s[20:21], 0, v[132:133]
	s_mov_b32 m0, s60
	s_nop 0
	global_load_lds_dwordx4 v[214:215], off
	s_waitcnt vmcnt(8)
	s_waitcnt lgkmcnt(0)
	s_barrier
	s_setprio 1
	s_waitcnt lgkmcnt(0)
	v_mfma_f32_16x16x32_bf16 v[128:131], v[144:147], v[186:189], v[128:131]
	v_mfma_f32_16x16x32_bf16 v[124:127], v[152:155], v[186:189], v[124:127]
	v_mfma_f32_16x16x32_bf16 v[120:123], v[144:147], v[198:201], v[120:123]
	v_mfma_f32_16x16x32_bf16 v[112:115], v[152:155], v[198:201], v[112:115]
	v_mfma_f32_16x16x32_bf16 v[104:107], v[144:147], v[206:209], v[104:107]
	v_mfma_f32_16x16x32_bf16 v[96:99], v[152:155], v[206:209], v[96:99]
	v_mfma_f32_16x16x32_bf16 v[88:91], v[144:147], v[218:221], v[88:91]
	v_mfma_f32_16x16x32_bf16 v[80:83], v[152:155], v[218:221], v[80:83]
	v_mfma_f32_16x16x32_bf16 v[128:131], v[148:151], v[190:193], v[128:131]
	v_mfma_f32_16x16x32_bf16 v[124:127], v[156:159], v[190:193], v[124:127]
	v_mfma_f32_16x16x32_bf16 v[120:123], v[148:151], v[202:205], v[120:123]
	v_mfma_f32_16x16x32_bf16 v[112:115], v[156:159], v[202:205], v[112:115]
	v_mfma_f32_16x16x32_bf16 v[104:107], v[148:151], v[210:213], v[104:107]
	v_mfma_f32_16x16x32_bf16 v[96:99], v[156:159], v[210:213], v[96:99]
	v_mfma_f32_16x16x32_bf16 v[88:91], v[148:151], v[222:225], v[88:91]
	v_mfma_f32_16x16x32_bf16 v[80:83], v[156:159], v[222:225], v[80:83]
	v_mfma_f32_16x16x32_bf16 v[116:119], v[160:163], v[186:189], v[116:119]
	v_mfma_f32_16x16x32_bf16 v[108:111], v[168:171], v[186:189], v[108:111]
	v_mfma_f32_16x16x32_bf16 v[100:103], v[160:163], v[198:201], v[100:103]
	v_mfma_f32_16x16x32_bf16 v[92:95], v[168:171], v[198:201], v[92:95]
	v_mfma_f32_16x16x32_bf16 v[84:87], v[160:163], v[206:209], v[84:87]
	v_mfma_f32_16x16x32_bf16 v[76:79], v[168:171], v[206:209], v[76:79]
	v_mfma_f32_16x16x32_bf16 v[72:75], v[160:163], v[218:221], v[72:75]
	v_mfma_f32_16x16x32_bf16 v[68:71], v[168:171], v[218:221], v[68:71]
	v_mfma_f32_16x16x32_bf16 v[116:119], v[164:167], v[190:193], v[116:119]
	v_mfma_f32_16x16x32_bf16 v[108:111], v[172:175], v[190:193], v[108:111]
	v_mfma_f32_16x16x32_bf16 v[100:103], v[164:167], v[202:205], v[100:103]
	v_mfma_f32_16x16x32_bf16 v[92:95], v[172:175], v[202:205], v[92:95]
	v_mfma_f32_16x16x32_bf16 v[84:87], v[164:167], v[210:213], v[84:87]
	v_mfma_f32_16x16x32_bf16 v[76:79], v[172:175], v[210:213], v[76:79]
	v_mfma_f32_16x16x32_bf16 v[72:75], v[164:167], v[222:225], v[72:75]
	v_mfma_f32_16x16x32_bf16 v[68:71], v[172:175], v[222:225], v[68:71]
	s_setprio 0
	s_barrier
; #define PG8_STAGE(bufoff, gbase, voff) do { _Pragma("unroll") for (int _i = 0; _i < 2; ++_i) \
;         __builtin_amdgcn_global_load_lds((const unsigned*)((const char*)(gbase) + (voff)[_i]), (LAS unsigned*)(lds + (bufoff) + ldsw + _i * 8192), 16, 0, 0); } while (0)
; #define PG8_LDA(dst, b, h) do { _Pragma("unroll") for (int m = 0; m < 4; ++m) _Pragma("unroll") for (int k = 0; k < 2; ++k) dst[m][k] = *(const LAS bf16x8*)(lds + PG8_SA(b, h) + aoff + m * 2048 + k * 1024); } while (0)
; #define PG8_LDB(dst, b, h) do { _Pragma("unroll") for (int n = 0; n < 2; ++n) _Pragma("unroll") for (int k = 0; k < 2; ++k) dst[n][k] = *(const LAS bf16x8*)(lds + PG8_SB(b, h) + boff + n * 2048 + k * 1024); } while (0)
; #define PG8_MMA(ai, bj, At, Bt) do { __builtin_amdgcn_s_setprio(1); _Pragma("unroll") for (int m = 0; m < 4; ++m) _Pragma("unroll") for (int n = 0; n < 2; ++n) _Pragma("unroll") for (int k = 0; k < 2; ++k) \
;         acc[ai][bj][m][n] = __builtin_amdgcn_mfma_f32_16x16x32_bf16(Bt[n][k], At[m][k], acc[ai][bj][m][n], 0, 0, 0); __builtin_amdgcn_s_setprio(0); } while (0)
; template <class Epi, class Sched, bool ALIGN_EPI = true, bool SP2 = true>
; __device__ __forceinline__ void gemm_phase(LAS unsigned char* lds, const Gemm g, const Sched& S, const Epi& E) {
;     ...
;             PG8_LDB(B0, 0, 0); PG8_LDB(B1, 0, 1); PG8_SCHED; PG8_LDA(At, 0, 0); PG8_STAGE(PG8_SA(1, 1), a1 + hstepA, voffA);
;             PG8_WAIT_V(8); PG8_WAIT_L(0); PG8_BAR; PG8_MMA(0, 0, At, B0); PG8_MMA(0, 1, At, B1); PG8_BAR; PG8_SCHED;
;             PG8_LDA(At, 0, 1); PG8_STAGE(PG8_SB(0, 0), b2, voffB); PG8_STAGE(PG8_SB(0, 1), b2 + hstepB, voffB); PG8_STAGE(PG8_SA(0, 0), a2, voffA);
;             PG8_WAIT_V(8); PG8_WAIT_L(0); PG8_BAR; PG8_MMA(1, 0, At, B0); PG8_MMA(1, 1, At, B1); PG8_BAR; PG8_SCHED;
;             PG8_LDB(B0, 1, 0); PG8_LDB(B1, 1, 1); PG8_SCHED; PG8_LDA(At, 1, 0); PG8_STAGE(PG8_SA(0, 1), a2 + hstepA, voffA);
;             PG8_WAIT_V(8); PG8_WAIT_L(0); PG8_BAR; PG8_MMA(0, 0, At, B0); PG8_MMA(0, 1, At, B1); PG8_BAR; PG8_SCHED;
;             PG8_LDA(At, 1, 1); PG8_STAGE(PG8_SB(1, 0), b3, voffB); PG8_STAGE(PG8_SB(1, 1), b3 + hstepB, voffB); PG8_STAGE(PG8_SA(1, 0), a3, voffA);
;             PG8_WAIT_V(8); PG8_WAIT_L(0); PG8_BAR; PG8_MMA(1, 0, At, B0); PG8_MMA(1, 1, At, B1); PG8_BAR; PG8_SCHED;
;         }
;         if constexpr (ALIGN_EPI) { if (wr == 0) PG8_BAR; }
	s_add_i32 s20, s58, s39
	v_lshl_add_u64 v[140:141], v[140:141], 0, s[14:15]
	s_mov_b32 m0, s20
	ds_read_b128 v[186:189], v143 offset:49152
	ds_read_b128 v[190:193], v143 offset:50176
	ds_read_b128 v[198:201], v143 offset:51200
	ds_read_b128 v[202:205], v143 offset:52224
	ds_read_b128 v[206:209], v143 offset:53248
	ds_read_b128 v[210:213], v143 offset:54272
	ds_read_b128 v[218:221], v143 offset:55296
	ds_read_b128 v[222:225], v143 offset:56320
	global_load_lds_dwordx4 v[140:141], off
	s_add_i32 m0, s20, 0x2000
	s_add_u32 s18, s18, 0x40080
	v_lshl_add_u64 v[140:141], v[176:177], 0, s[14:15]
	s_addc_u32 s19, s19, 0
	s_add_i32 s20, s59, s39
	global_load_lds_dwordx4 v[140:141], off
	v_lshl_add_u64 v[140:141], s[18:19], 0, v[18:19]
	s_mov_b32 m0, s20
	s_nop 0
	global_load_lds_dwordx4 v[140:141], off
	v_lshl_add_u64 v[140:141], s[18:19], 0, v[16:17]
	s_add_i32 m0, s20, 0x2000
	s_nop 0
	global_load_lds_dwordx4 v[140:141], off
	v_lshl_add_u64 v[140:141], v[178:179], 0, s[14:15]
	s_mov_b32 m0, s8
	s_nop 0
	global_load_lds_dwordx4 v[140:141], off
	v_lshl_add_u64 v[140:141], v[182:183], 0, s[14:15]
	s_mov_b32 m0, s9
	s_nop 0
	global_load_lds_dwordx4 v[140:141], off
	s_waitcnt vmcnt(8)
	s_waitcnt lgkmcnt(0)
	s_barrier
	s_setprio 1
	s_waitcnt lgkmcnt(0)
	v_mfma_f32_16x16x32_bf16 v[64:67], v[144:147], v[186:189], v[64:67]
	v_mfma_f32_16x16x32_bf16 v[60:63], v[152:155], v[186:189], v[60:63]
	v_mfma_f32_16x16x32_bf16 v[56:59], v[144:147], v[198:201], v[56:59]
	v_mfma_f32_16x16x32_bf16 v[48:51], v[152:155], v[198:201], v[48:51]
	v_mfma_f32_16x16x32_bf16 v[40:43], v[144:147], v[206:209], v[40:43]
	v_mfma_f32_16x16x32_bf16 v[32:35], v[152:155], v[206:209], v[32:35]
	v_mfma_f32_16x16x32_bf16 v[24:27], v[144:147], v[218:221], v[24:27]
	v_mfma_f32_16x16x32_bf16 v[12:15], v[152:155], v[218:221], v[12:15]
	v_mfma_f32_16x16x32_bf16 v[64:67], v[148:151], v[190:193], v[64:67]
	v_mfma_f32_16x16x32_bf16 v[60:63], v[156:159], v[190:193], v[60:63]
	v_mfma_f32_16x16x32_bf16 v[56:59], v[148:151], v[202:205], v[56:59]
	v_mfma_f32_16x16x32_bf16 v[48:51], v[156:159], v[202:205], v[48:51]
	v_mfma_f32_16x16x32_bf16 v[40:43], v[148:151], v[210:213], v[40:43]
	v_mfma_f32_16x16x32_bf16 v[32:35], v[156:159], v[210:213], v[32:35]
	v_mfma_f32_16x16x32_bf16 v[24:27], v[148:151], v[222:225], v[24:27]
	v_mfma_f32_16x16x32_bf16 v[12:15], v[156:159], v[222:225], v[12:15]
	v_mfma_f32_16x16x32_bf16 v[52:55], v[160:163], v[186:189], v[52:55]
	v_mfma_f32_16x16x32_bf16 v[44:47], v[168:171], v[186:189], v[44:47]
	v_mfma_f32_16x16x32_bf16 v[36:39], v[160:163], v[198:201], v[36:39]
	v_mfma_f32_16x16x32_bf16 v[28:31], v[168:171], v[198:201], v[28:31]
	v_mfma_f32_16x16x32_bf16 v[20:23], v[160:163], v[206:209], v[20:23]
	v_mfma_f32_16x16x32_bf16 v[8:11], v[168:171], v[206:209], v[8:11]
	v_mfma_f32_16x16x32_bf16 v[4:7], v[160:163], v[218:221], v[4:7]
	v_mfma_f32_16x16x32_bf16 v[0:3], v[168:171], v[218:221], v[0:3]
	v_mfma_f32_16x16x32_bf16 v[52:55], v[164:167], v[190:193], v[52:55]
	v_mfma_f32_16x16x32_bf16 v[44:47], v[172:175], v[190:193], v[44:47]
	v_mfma_f32_16x16x32_bf16 v[36:39], v[164:167], v[202:205], v[36:39]
	v_mfma_f32_16x16x32_bf16 v[28:31], v[172:175], v[202:205], v[28:31]
	v_mfma_f32_16x16x32_bf16 v[20:23], v[164:167], v[210:213], v[20:23]
	v_mfma_f32_16x16x32_bf16 v[8:11], v[172:175], v[210:213], v[8:11]
	v_mfma_f32_16x16x32_bf16 v[4:7], v[164:167], v[222:225], v[4:7]
	v_mfma_f32_16x16x32_bf16 v[0:3], v[172:175], v[222:225], v[0:3]
	s_setprio 0
	s_barrier
	s_add_i32 s49, s49, 2
	s_add_u32 s54, s54, 0x100
	s_addc_u32 s55, s55, 0
	s_add_u32 s30, s30, 0x100
	s_addc_u32 s45, s45, 0
	s_cmp_gt_u32 s49, 13
	s_cbranch_scc0 .LBB0_884
	s_and_b64 vcc, exec, s[36:37]
	s_cbranch_vccz .LBB0_887
	s_barrier

; #define PG8_STAGE(bufoff, gbase, voff) do { _Pragma("unroll") for (int _i = 0; _i < 2; ++_i) \
;         __builtin_amdgcn_global_load_lds((const unsigned*)((const char*)(gbase) + (voff)[_i]), (LAS unsigned*)(lds + (bufoff) + ldsw + _i * 8192), 16, 0, 0); } while (0)
; #define PG8_LDA(dst, b, h) do { _Pragma("unroll") for (int m = 0; m < 4; ++m) _Pragma("unroll") for (int k = 0; k < 2; ++k) dst[m][k] = *(const LAS bf16x8*)(lds + PG8_SA(b, h) + aoff + m * 2048 + k * 1024); } while (0)
; #define PG8_LDB(dst, b, h) do { _Pragma("unroll") for (int n = 0; n < 2; ++n) _Pragma("unroll") for (int k = 0; k < 2; ++k) dst[n][k] = *(const LAS bf16x8*)(lds + PG8_SB(b, h) + boff + n * 2048 + k * 1024); } while (0)
; #define PG8_WAIT_V(n) asm volatile("s_waitcnt vmcnt(" #n ")" ::: "memory")
; template <class Epi, class Sched, bool ALIGN_EPI = true, bool SP2 = true>
; __device__ __forceinline__ void gemm_phase(LAS unsigned char* lds, const Gemm g, const Sched& S, const Epi& E) {
;     ...
;         for (int t = 0; t < nt; t += 2) {
;             const bool last = (t == nt - 2);
;             const char* a1 = cA + (size_t)(t + 1) * kstep;
;             const char* a2 = last ? nA : cA + (size_t)(t + 2) * kstep; const char* b2 = last ? nB : cB + (size_t)(t + 2) * kstep;
;             const char* a3 = a2 + kstep; const char* b3 = b2 + kstep;
;             PG8_LDB(B0, 0, 0); PG8_LDB(B1, 0, 1); PG8_SCHED; PG8_LDA(At, 0, 0); PG8_STAGE(PG8_SA(1, 1), a1 + hstepA, voffA);
;             PG8_WAIT_V(8); PG8_WAIT_L(0); PG8_BAR; PG8_MMA(0, 0, At, B0); PG8_MMA(0, 1, At, B1); PG8_BAR; PG8_SCHED;
;             PG8_LDA(At, 0, 1); PG8_STAGE(PG8_SB(0, 0), b2, voffB); PG8_STAGE(PG8_SB(0, 1), b2 + hstepB, voffB); PG8_STAGE(PG8_SA(0, 0), a2, voffA);
;             PG8_WAIT_V(8); PG8_WAIT_L(0); PG8_BAR; PG8_MMA(1, 0, At, B0); PG8_MMA(1, 1, At, B1); PG8_BAR; PG8_SCHED;
;             PG8_LDB(B0, 1, 0); PG8_LDB(B1, 1, 1); PG8_SCHED; PG8_LDA(At, 1, 0); PG8_STAGE(PG8_SA(0, 1), a2 + hstepA, voffA);
;             PG8_WAIT_V(8); PG8_WAIT_L(0); PG8_BAR; PG8_MMA(0, 0, At, B0); PG8_MMA(0, 1, At, B1); PG8_BAR; PG8_SCHED;
;             PG8_LDA(At, 1, 1); PG8_STAGE(PG8_SB(1, 0), b3, voffB); PG8_STAGE(PG8_SB(1, 1), b3 + hstepB, voffB); PG8_STAGE(PG8_SA(1, 0), a3, voffA);
;             PG8_WAIT_V(8); PG8_WAIT_L(0); PG8_BAR; PG8_MMA(1, 0, At, B0); PG8_MMA(1, 1, At, B1); PG8_BAR; PG8_SCHED;
.LBB0_1063:
	s_add_u32 s18, vcc_lo, 0xfffc0080
	s_addc_u32 s19, vcc_hi, -1
	s_add_i32 s34, 0, 0x10000
	s_cmp_eq_u32 s58, 12
	s_cselect_b32 s23, s51, s19
	s_cselect_b32 s22, s2, s18
	s_cselect_b32 s19, s47, s55
	s_cselect_b32 s18, s30, s54
	s_add_i32 s59, 0, 0x14000
	v_add_u32_e32 v154, s34, v144
	v_add_u32_e32 v170, s59, v144
	ds_read_b128 v[140:143], v154
	ds_read_b128 v[146:149], v154 offset:1024
	ds_read_b128 v[150:153], v154 offset:2048
	ds_read_b128 v[154:157], v154 offset:3072
	ds_read_b128 v[158:161], v170
	ds_read_b128 v[162:165], v170 offset:1024
	ds_read_b128 v[166:169], v170 offset:2048
	ds_read_b128 v[170:173], v170 offset:3072
	v_lshl_add_u64 v[178:179], vcc, 0, v[136:137]
	s_add_i32 m0, s65, 0xc000
	ds_read_b128 v[174:177], v145
	ds_read_b128 v[186:189], v145 offset:1024
	ds_read_b128 v[190:193], v145 offset:2048
	ds_read_b128 v[198:201], v145 offset:3072
	ds_read_b128 v[202:205], v145 offset:4096
	ds_read_b128 v[206:209], v145 offset:5120
	ds_read_b128 v[210:213], v145 offset:6144
	ds_read_b128 v[218:221], v145 offset:7168
	global_load_lds_dwordx4 v[178:179], off
	v_lshl_add_u64 v[178:179], vcc, 0, v[138:139]
	s_add_i32 m0, s65, 0xe000
	s_nop 0
	global_load_lds_dwordx4 v[178:179], off
	s_waitcnt vmcnt(8)
	s_waitcnt lgkmcnt(0)
	s_barrier
	s_setprio 1
	s_waitcnt lgkmcnt(0)
	v_mfma_f32_16x16x32_bf16 v[128:131], v[140:143], v[174:177], v[128:131]
	v_mfma_f32_16x16x32_bf16 v[124:127], v[150:153], v[174:177], v[124:127]
	v_mfma_f32_16x16x32_bf16 v[120:123], v[140:143], v[190:193], v[120:123]
	v_mfma_f32_16x16x32_bf16 v[112:115], v[150:153], v[190:193], v[112:115]
	v_mfma_f32_16x16x32_bf16 v[104:107], v[140:143], v[202:205], v[104:107]
	v_mfma_f32_16x16x32_bf16 v[96:99], v[150:153], v[202:205], v[96:99]
	v_mfma_f32_16x16x32_bf16 v[88:91], v[140:143], v[210:213], v[88:91]
	v_mfma_f32_16x16x32_bf16 v[80:83], v[150:153], v[210:213], v[80:83]
	v_mfma_f32_16x16x32_bf16 v[128:131], v[146:149], v[186:189], v[128:131]
	v_mfma_f32_16x16x32_bf16 v[124:127], v[154:157], v[186:189], v[124:127]
	v_mfma_f32_16x16x32_bf16 v[120:123], v[146:149], v[198:201], v[120:123]
	v_mfma_f32_16x16x32_bf16 v[112:115], v[154:157], v[198:201], v[112:115]
	v_mfma_f32_16x16x32_bf16 v[104:107], v[146:149], v[206:209], v[104:107]
	v_mfma_f32_16x16x32_bf16 v[96:99], v[154:157], v[206:209], v[96:99]
	v_mfma_f32_16x16x32_bf16 v[88:91], v[146:149], v[218:221], v[88:91]
	v_mfma_f32_16x16x32_bf16 v[80:83], v[154:157], v[218:221], v[80:83]
	v_mfma_f32_16x16x32_bf16 v[116:119], v[158:161], v[174:177], v[116:119]
	v_mfma_f32_16x16x32_bf16 v[108:111], v[166:169], v[174:177], v[108:111]
	v_mfma_f32_16x16x32_bf16 v[100:103], v[158:161], v[190:193], v[100:103]
	v_mfma_f32_16x16x32_bf16 v[92:95], v[166:169], v[190:193], v[92:95]
	v_mfma_f32_16x16x32_bf16 v[84:87], v[158:161], v[202:205], v[84:87]
	v_mfma_f32_16x16x32_bf16 v[76:79], v[166:169], v[202:205], v[76:79]
	v_mfma_f32_16x16x32_bf16 v[72:75], v[158:161], v[210:213], v[72:75]
	v_mfma_f32_16x16x32_bf16 v[68:71], v[166:169], v[210:213], v[68:71]
	v_mfma_f32_16x16x32_bf16 v[116:119], v[162:165], v[186:189], v[116:119]
	v_mfma_f32_16x16x32_bf16 v[108:111], v[170:173], v[186:189], v[108:111]
	v_mfma_f32_16x16x32_bf16 v[100:103], v[162:165], v[198:201], v[100:103]
	v_mfma_f32_16x16x32_bf16 v[92:95], v[170:173], v[198:201], v[92:95]
	v_mfma_f32_16x16x32_bf16 v[84:87], v[162:165], v[206:209], v[84:87]
	v_mfma_f32_16x16x32_bf16 v[76:79], v[170:173], v[206:209], v[76:79]
	v_mfma_f32_16x16x32_bf16 v[72:75], v[162:165], v[218:221], v[72:75]
	v_mfma_f32_16x16x32_bf16 v[68:71], v[170:173], v[218:221], v[68:71]
	s_setprio 0
	s_barrier
	s_add_i32 s34, s34, s56
	v_lshl_add_u64 v[178:179], s[18:19], 0, v[18:19]
	s_mov_b32 m0, s34
	ds_read_b128 v[174:177], v145 offset:16384
	ds_read_b128 v[186:189], v145 offset:17408
	ds_read_b128 v[190:193], v145 offset:18432
	ds_read_b128 v[198:201], v145 offset:19456
	ds_read_b128 v[202:205], v145 offset:20480
	ds_read_b128 v[206:209], v145 offset:21504
	ds_read_b128 v[210:213], v145 offset:22528
	ds_read_b128 v[218:221], v145 offset:23552
	global_load_lds_dwordx4 v[178:179], off
	s_add_i32 m0, s34, 0x2000
	s_add_u32 s34, s18, 0x40000
	v_lshl_add_u64 v[182:183], s[18:19], 0, v[16:17]
	s_addc_u32 s35, s19, 0
	s_add_i32 s59, s59, s56
	global_load_lds_dwordx4 v[182:183], off
	v_lshl_add_u64 v[214:215], s[34:35], 0, v[18:19]
	s_mov_b32 m0, s59
	v_lshl_add_u64 v[222:223], s[22:23], 0, v[132:133]
	global_load_lds_dwordx4 v[214:215], off
	v_lshl_add_u64 v[214:215], s[34:35], 0, v[16:17]
	s_add_i32 m0, s59, 0x2000
	s_nop 0
	global_load_lds_dwordx4 v[214:215], off
	v_lshl_add_u64 v[214:215], s[22:23], 0, v[134:135]
	s_mov_b32 m0, s65
	s_nop 0
	global_load_lds_dwordx4 v[214:215], off
	s_mov_b32 m0, s0
	s_nop 0
	global_load_lds_dwordx4 v[222:223], off
	s_waitcnt vmcnt(8)
	s_waitcnt lgkmcnt(0)
	s_barrier
; #define PG8_STAGE(bufoff, gbase, voff) do { _Pragma("unroll") for (int _i = 0; _i < 2; ++_i) \
;         __builtin_amdgcn_global_load_lds((const unsigned*)((const char*)(gbase) + (voff)[_i]), (LAS unsigned*)(lds + (bufoff) + ldsw + _i * 8192), 16, 0, 0); } while (0)
; #define PG8_LDA(dst, b, h) do { _Pragma("unroll") for (int m = 0; m < 4; ++m) _Pragma("unroll") for (int k = 0; k < 2; ++k) dst[m][k] = *(const LAS bf16x8*)(lds + PG8_SA(b, h) + aoff + m * 2048 + k * 1024); } while (0)
; #define PG8_LDB(dst, b, h) do { _Pragma("unroll") for (int n = 0; n < 2; ++n) _Pragma("unroll") for (int k = 0; k < 2; ++k) dst[n][k] = *(const LAS bf16x8*)(lds + PG8_SB(b, h) + boff + n * 2048 + k * 1024); } while (0)
; #define PG8_MMA(ai, bj, At, Bt) do { __builtin_amdgcn_s_setprio(1); _Pragma("unroll") for (int m = 0; m < 4; ++m) _Pragma("unroll") for (int n = 0; n < 2; ++n) _Pragma("unroll") for (int k = 0; k < 2; ++k) \
;         acc[ai][bj][m][n] = __builtin_amdgcn_mfma_f32_16x16x32_bf16(Bt[n][k], At[m][k], acc[ai][bj][m][n], 0, 0, 0); __builtin_amdgcn_s_setprio(0); } while (0)
; #define PG8_WAIT_V(n) asm volatile("s_waitcnt vmcnt(" #n ")" ::: "memory")
; template <class Epi, class Sched, bool ALIGN_EPI = true, bool SP2 = true>
; __device__ __forceinline__ void gemm_phase(LAS unsigned char* lds, const Gemm g, const Sched& S, const Epi& E) {
;     ...
;             PG8_LDB(B0, 0, 0); PG8_LDB(B1, 0, 1); PG8_SCHED; PG8_LDA(At, 0, 0); PG8_STAGE(PG8_SA(1, 1), a1 + hstepA, voffA);
;             PG8_WAIT_V(8); PG8_WAIT_L(0); PG8_BAR; PG8_MMA(0, 0, At, B0); PG8_MMA(0, 1, At, B1); PG8_BAR; PG8_SCHED;
;             PG8_LDA(At, 0, 1); PG8_STAGE(PG8_SB(0, 0), b2, voffB); PG8_STAGE(PG8_SB(0, 1), b2 + hstepB, voffB); PG8_STAGE(PG8_SA(0, 0), a2, voffA);
;             PG8_WAIT_V(8); PG8_WAIT_L(0); PG8_BAR; PG8_MMA(1, 0, At, B0); PG8_MMA(1, 1, At, B1); PG8_BAR; PG8_SCHED;
;             PG8_LDB(B0, 1, 0); PG8_LDB(B1, 1, 1); PG8_SCHED; PG8_LDA(At, 1, 0); PG8_STAGE(PG8_SA(0, 1), a2 + hstepA, voffA);
;             PG8_WAIT_V(8); PG8_WAIT_L(0); PG8_BAR; PG8_MMA(0, 0, At, B0); PG8_MMA(0, 1, At, B1); PG8_BAR; PG8_SCHED;
;             PG8_LDA(At, 1, 1); PG8_STAGE(PG8_SB(1, 0), b3, voffB); PG8_STAGE(PG8_SB(1, 1), b3 + hstepB, voffB); PG8_STAGE(PG8_SA(1, 0), a3, voffA);
;             PG8_WAIT_V(8); PG8_WAIT_L(0); PG8_BAR; PG8_MMA(1, 0, At, B0); PG8_MMA(1, 1, At, B1); PG8_BAR; PG8_SCHED;
	s_setprio 1
	s_waitcnt lgkmcnt(0)
	v_mfma_f32_16x16x32_bf16 v[64:67], v[140:143], v[174:177], v[64:67]
	v_mfma_f32_16x16x32_bf16 v[60:63], v[150:153], v[174:177], v[60:63]
	v_mfma_f32_16x16x32_bf16 v[56:59], v[140:143], v[190:193], v[56:59]
	v_mfma_f32_16x16x32_bf16 v[48:51], v[150:153], v[190:193], v[48:51]
	v_mfma_f32_16x16x32_bf16 v[40:43], v[140:143], v[202:205], v[40:43]
	v_mfma_f32_16x16x32_bf16 v[32:35], v[150:153], v[202:205], v[32:35]
	v_mfma_f32_16x16x32_bf16 v[24:27], v[140:143], v[210:213], v[24:27]
	v_mfma_f32_16x16x32_bf16 v[12:15], v[150:153], v[210:213], v[12:15]
	v_mfma_f32_16x16x32_bf16 v[64:67], v[146:149], v[186:189], v[64:67]
	v_mfma_f32_16x16x32_bf16 v[60:63], v[154:157], v[186:189], v[60:63]
	v_mfma_f32_16x16x32_bf16 v[56:59], v[146:149], v[198:201], v[56:59]
	v_mfma_f32_16x16x32_bf16 v[48:51], v[154:157], v[198:201], v[48:51]
	v_mfma_f32_16x16x32_bf16 v[40:43], v[146:149], v[206:209], v[40:43]
	v_mfma_f32_16x16x32_bf16 v[32:35], v[154:157], v[206:209], v[32:35]
	v_mfma_f32_16x16x32_bf16 v[24:27], v[146:149], v[218:221], v[24:27]
	v_mfma_f32_16x16x32_bf16 v[12:15], v[154:157], v[218:221], v[12:15]
	v_mfma_f32_16x16x32_bf16 v[52:55], v[158:161], v[174:177], v[52:55]
	v_mfma_f32_16x16x32_bf16 v[44:47], v[166:169], v[174:177], v[44:47]
	v_mfma_f32_16x16x32_bf16 v[36:39], v[158:161], v[190:193], v[36:39]
	v_mfma_f32_16x16x32_bf16 v[28:31], v[166:169], v[190:193], v[28:31]
	v_mfma_f32_16x16x32_bf16 v[20:23], v[158:161], v[202:205], v[20:23]
	v_mfma_f32_16x16x32_bf16 v[8:11], v[166:169], v[202:205], v[8:11]
	v_mfma_f32_16x16x32_bf16 v[4:7], v[158:161], v[210:213], v[4:7]
	v_mfma_f32_16x16x32_bf16 v[0:3], v[166:169], v[210:213], v[0:3]
	v_mfma_f32_16x16x32_bf16 v[52:55], v[162:165], v[186:189], v[52:55]
	v_mfma_f32_16x16x32_bf16 v[44:47], v[170:173], v[186:189], v[44:47]
	v_mfma_f32_16x16x32_bf16 v[36:39], v[162:165], v[198:201], v[36:39]
	v_mfma_f32_16x16x32_bf16 v[28:31], v[170:173], v[198:201], v[28:31]
	v_mfma_f32_16x16x32_bf16 v[20:23], v[162:165], v[206:209], v[20:23]
	v_mfma_f32_16x16x32_bf16 v[8:11], v[170:173], v[206:209], v[8:11]
	v_mfma_f32_16x16x32_bf16 v[4:7], v[162:165], v[218:221], v[4:7]
	v_mfma_f32_16x16x32_bf16 v[0:3], v[170:173], v[218:221], v[0:3]
	s_setprio 0
	s_barrier
	s_add_i32 s34, 0, 0x18000
	s_add_i32 s35, 0, 0x1c000
	v_add_u32_e32 v154, s34, v144
	v_add_u32_e32 v170, s35, v144
	ds_read_b128 v[140:143], v154
	ds_read_b128 v[146:149], v154 offset:1024
	ds_read_b128 v[150:153], v154 offset:2048
	ds_read_b128 v[154:157], v154 offset:3072
	ds_read_b128 v[158:161], v170
	ds_read_b128 v[162:165], v170 offset:1024
	ds_read_b128 v[166:169], v170 offset:2048
	ds_read_b128 v[170:173], v170 offset:3072
	s_add_u32 s22, s22, 0x40000
	s_addc_u32 s23, s23, 0
	s_mov_b32 m0, s1
	v_lshl_add_u64 v[224:225], s[22:23], 0, v[134:135]
	ds_read_b128 v[174:177], v145 offset:32768
	ds_read_b128 v[186:189], v145 offset:33792
	ds_read_b128 v[190:193], v145 offset:34816
	ds_read_b128 v[198:201], v145 offset:35840
	ds_read_b128 v[202:205], v145 offset:36864
	ds_read_b128 v[206:209], v145 offset:37888
	ds_read_b128 v[210:213], v145 offset:38912
	ds_read_b128 v[218:221], v145 offset:39936
	global_load_lds_dwordx4 v[224:225], off
	v_lshl_add_u64 v[224:225], s[22:23], 0, v[132:133]
	s_mov_b32 m0, s8
	s_nop 0
	global_load_lds_dwordx4 v[224:225], off
	s_waitcnt vmcnt(8)
	s_waitcnt lgkmcnt(0)
	s_barrier
	s_setprio 1
	s_waitcnt lgkmcnt(0)
	v_mfma_f32_16x16x32_bf16 v[128:131], v[140:143], v[174:177], v[128:131]
	v_mfma_f32_16x16x32_bf16 v[124:127], v[150:153], v[174:177], v[124:127]
	v_mfma_f32_16x16x32_bf16 v[120:123], v[140:143], v[190:193], v[120:123]
	v_mfma_f32_16x16x32_bf16 v[112:115], v[150:153], v[190:193], v[112:115]
	v_mfma_f32_16x16x32_bf16 v[104:107], v[140:143], v[202:205], v[104:107]
	v_mfma_f32_16x16x32_bf16 v[96:99], v[150:153], v[202:205], v[96:99]
	v_mfma_f32_16x16x32_bf16 v[88:91], v[140:143], v[210:213], v[88:91]
	v_mfma_f32_16x16x32_bf16 v[80:83], v[150:153], v[210:213], v[80:83]
	v_mfma_f32_16x16x32_bf16 v[128:131], v[146:149], v[186:189], v[128:131]
	v_mfma_f32_16x16x32_bf16 v[124:127], v[154:157], v[186:189], v[124:127]
	v_mfma_f32_16x16x32_bf16 v[120:123], v[146:149], v[198:201], v[120:123]
	v_mfma_f32_16x16x32_bf16 v[112:115], v[154:157], v[198:201], v[112:115]
	v_mfma_f32_16x16x32_bf16 v[104:107], v[146:149], v[206:209], v[104:107]
	v_mfma_f32_16x16x32_bf16 v[96:99], v[154:157], v[206:209], v[96:99]
	v_mfma_f32_16x16x32_bf16 v[88:91], v[146:149], v[218:221], v[88:91]
	v_mfma_f32_16x16x32_bf16 v[80:83], v[154:157], v[218:221], v[80:83]
	v_mfma_f32_16x16x32_bf16 v[116:119], v[158:161], v[174:177], v[116:119]
	v_mfma_f32_16x16x32_bf16 v[108:111], v[166:169], v[174:177], v[108:111]
	v_mfma_f32_16x16x32_bf16 v[100:103], v[158:161], v[190:193], v[100:103]
	v_mfma_f32_16x16x32_bf16 v[92:95], v[166:169], v[190:193], v[92:95]
	v_mfma_f32_16x16x32_bf16 v[84:87], v[158:161], v[202:205], v[84:87]
	v_mfma_f32_16x16x32_bf16 v[76:79], v[166:169], v[202:205], v[76:79]
	v_mfma_f32_16x16x32_bf16 v[72:75], v[158:161], v[210:213], v[72:75]
	v_mfma_f32_16x16x32_bf16 v[68:71], v[166:169], v[210:213], v[68:71]
	v_mfma_f32_16x16x32_bf16 v[116:119], v[162:165], v[186:189], v[116:119]
	v_mfma_f32_16x16x32_bf16 v[108:111], v[170:173], v[186:189], v[108:111]
	v_mfma_f32_16x16x32_bf16 v[100:103], v[162:165], v[198:201], v[100:103]
	v_mfma_f32_16x16x32_bf16 v[92:95], v[170:173], v[198:201], v[92:95]
	v_mfma_f32_16x16x32_bf16 v[84:87], v[162:165], v[206:209], v[84:87]
	v_mfma_f32_16x16x32_bf16 v[76:79], v[170:173], v[206:209], v[76:79]
	v_mfma_f32_16x16x32_bf16 v[72:75], v[162:165], v[218:221], v[72:75]
	v_mfma_f32_16x16x32_bf16 v[68:71], v[170:173], v[218:221], v[68:71]
	s_setprio 0
	s_barrier
; #define PG8_STAGE(bufoff, gbase, voff) do { _Pragma("unroll") for (int _i = 0; _i < 2; ++_i) \
;         __builtin_amdgcn_global_load_lds((const unsigned*)((const char*)(gbase) + (voff)[_i]), (LAS unsigned*)(lds + (bufoff) + ldsw + _i * 8192), 16, 0, 0); } while (0)
; #define PG8_LDA(dst, b, h) do { _Pragma("unroll") for (int m = 0; m < 4; ++m) _Pragma("unroll") for (int k = 0; k < 2; ++k) dst[m][k] = *(const LAS bf16x8*)(lds + PG8_SA(b, h) + aoff + m * 2048 + k * 1024); } while (0)
; #define PG8_LDB(dst, b, h) do { _Pragma("unroll") for (int n = 0; n < 2; ++n) _Pragma("unroll") for (int k = 0; k < 2; ++k) dst[n][k] = *(const LAS bf16x8*)(lds + PG8_SB(b, h) + boff + n * 2048 + k * 1024); } while (0)
; #define PG8_MMA(ai, bj, At, Bt) do { __builtin_amdgcn_s_setprio(1); _Pragma("unroll") for (int m = 0; m < 4; ++m) _Pragma("unroll") for (int n = 0; n < 2; ++n) _Pragma("unroll") for (int k = 0; k < 2; ++k) \
;         acc[ai][bj][m][n] = __builtin_amdgcn_mfma_f32_16x16x32_bf16(Bt[n][k], At[m][k], acc[ai][bj][m][n], 0, 0, 0); __builtin_amdgcn_s_setprio(0); } while (0)
; template <class Epi, class Sched, bool ALIGN_EPI = true, bool SP2 = true>
; __device__ __forceinline__ void gemm_phase(LAS unsigned char* lds, const Gemm g, const Sched& S, const Epi& E) {
;     ...
;             PG8_LDB(B0, 0, 0); PG8_LDB(B1, 0, 1); PG8_SCHED; PG8_LDA(At, 0, 0); PG8_STAGE(PG8_SA(1, 1), a1 + hstepA, voffA);
;             PG8_WAIT_V(8); PG8_WAIT_L(0); PG8_BAR; PG8_MMA(0, 0, At, B0); PG8_MMA(0, 1, At, B1); PG8_BAR; PG8_SCHED;
;             PG8_LDA(At, 0, 1); PG8_STAGE(PG8_SB(0, 0), b2, voffB); PG8_STAGE(PG8_SB(0, 1), b2 + hstepB, voffB); PG8_STAGE(PG8_SA(0, 0), a2, voffA);
;             PG8_WAIT_V(8); PG8_WAIT_L(0); PG8_BAR; PG8_MMA(1, 0, At, B0); PG8_MMA(1, 1, At, B1); PG8_BAR; PG8_SCHED;
;             PG8_LDB(B0, 1, 0); PG8_LDB(B1, 1, 1); PG8_SCHED; PG8_LDA(At, 1, 0); PG8_STAGE(PG8_SA(0, 1), a2 + hstepA, voffA);
;             PG8_WAIT_V(8); PG8_WAIT_L(0); PG8_BAR; PG8_MMA(0, 0, At, B0); PG8_MMA(0, 1, At, B1); PG8_BAR; PG8_SCHED;
;             PG8_LDA(At, 1, 1); PG8_STAGE(PG8_SB(1, 0), b3, voffB); PG8_STAGE(PG8_SB(1, 1), b3 + hstepB, voffB); PG8_STAGE(PG8_SA(1, 0), a3, voffA);
;             PG8_WAIT_V(8); PG8_WAIT_L(0); PG8_BAR; PG8_MMA(1, 0, At, B0); PG8_MMA(1, 1, At, B1); PG8_BAR; PG8_SCHED;
;         }
;         if constexpr (ALIGN_EPI) { if (wr == 0) PG8_BAR; }
	s_add_i32 s22, s34, s56
	v_lshl_add_u64 v[178:179], v[178:179], 0, s[14:15]
	s_mov_b32 m0, s22
	ds_read_b128 v[174:177], v145 offset:49152
	ds_read_b128 v[186:189], v145 offset:50176
	ds_read_b128 v[190:193], v145 offset:51200
	ds_read_b128 v[198:201], v145 offset:52224
	ds_read_b128 v[202:205], v145 offset:53248
	ds_read_b128 v[206:209], v145 offset:54272
	ds_read_b128 v[210:213], v145 offset:55296
	ds_read_b128 v[218:221], v145 offset:56320
	global_load_lds_dwordx4 v[178:179], off
	s_add_i32 m0, s22, 0x2000
	s_add_u32 s18, s18, 0x40080
	v_lshl_add_u64 v[178:179], v[182:183], 0, s[14:15]
	s_addc_u32 s19, s19, 0
	s_add_i32 s22, s35, s56
	global_load_lds_dwordx4 v[178:179], off
	v_lshl_add_u64 v[178:179], s[18:19], 0, v[18:19]
	s_mov_b32 m0, s22
	s_nop 0
	global_load_lds_dwordx4 v[178:179], off
	v_lshl_add_u64 v[178:179], s[18:19], 0, v[16:17]
	s_add_i32 m0, s22, 0x2000
	s_nop 0
	global_load_lds_dwordx4 v[178:179], off
	v_lshl_add_u64 v[178:179], v[214:215], 0, s[14:15]
	s_mov_b32 m0, s49
	s_nop 0
	global_load_lds_dwordx4 v[178:179], off
	v_lshl_add_u64 v[178:179], v[222:223], 0, s[14:15]
	s_mov_b32 m0, s66
	s_nop 0
	global_load_lds_dwordx4 v[178:179], off
	s_waitcnt vmcnt(8)
	s_waitcnt lgkmcnt(0)
	s_barrier
	s_setprio 1
	s_waitcnt lgkmcnt(0)
	v_mfma_f32_16x16x32_bf16 v[64:67], v[140:143], v[174:177], v[64:67]
	v_mfma_f32_16x16x32_bf16 v[60:63], v[150:153], v[174:177], v[60:63]
	v_mfma_f32_16x16x32_bf16 v[56:59], v[140:143], v[190:193], v[56:59]
	v_mfma_f32_16x16x32_bf16 v[48:51], v[150:153], v[190:193], v[48:51]
	v_mfma_f32_16x16x32_bf16 v[40:43], v[140:143], v[202:205], v[40:43]
	v_mfma_f32_16x16x32_bf16 v[32:35], v[150:153], v[202:205], v[32:35]
	v_mfma_f32_16x16x32_bf16 v[24:27], v[140:143], v[210:213], v[24:27]
	v_mfma_f32_16x16x32_bf16 v[12:15], v[150:153], v[210:213], v[12:15]
	v_mfma_f32_16x16x32_bf16 v[64:67], v[146:149], v[186:189], v[64:67]
	v_mfma_f32_16x16x32_bf16 v[60:63], v[154:157], v[186:189], v[60:63]
	v_mfma_f32_16x16x32_bf16 v[56:59], v[146:149], v[198:201], v[56:59]
	v_mfma_f32_16x16x32_bf16 v[48:51], v[154:157], v[198:201], v[48:51]
	v_mfma_f32_16x16x32_bf16 v[40:43], v[146:149], v[206:209], v[40:43]
	v_mfma_f32_16x16x32_bf16 v[32:35], v[154:157], v[206:209], v[32:35]
	v_mfma_f32_16x16x32_bf16 v[24:27], v[146:149], v[218:221], v[24:27]
	v_mfma_f32_16x16x32_bf16 v[12:15], v[154:157], v[218:221], v[12:15]
	v_mfma_f32_16x16x32_bf16 v[52:55], v[158:161], v[174:177], v[52:55]
	v_mfma_f32_16x16x32_bf16 v[44:47], v[166:169], v[174:177], v[44:47]
	v_mfma_f32_16x16x32_bf16 v[36:39], v[158:161], v[190:193], v[36:39]
	v_mfma_f32_16x16x32_bf16 v[28:31], v[166:169], v[190:193], v[28:31]
	v_mfma_f32_16x16x32_bf16 v[20:23], v[158:161], v[202:205], v[20:23]
	v_mfma_f32_16x16x32_bf16 v[8:11], v[166:169], v[202:205], v[8:11]
	v_mfma_f32_16x16x32_bf16 v[4:7], v[158:161], v[210:213], v[4:7]
	v_mfma_f32_16x16x32_bf16 v[0:3], v[166:169], v[210:213], v[0:3]
	v_mfma_f32_16x16x32_bf16 v[52:55], v[162:165], v[186:189], v[52:55]
	v_mfma_f32_16x16x32_bf16 v[44:47], v[170:173], v[186:189], v[44:47]
	v_mfma_f32_16x16x32_bf16 v[36:39], v[162:165], v[198:201], v[36:39]
	v_mfma_f32_16x16x32_bf16 v[28:31], v[170:173], v[198:201], v[28:31]
	v_mfma_f32_16x16x32_bf16 v[20:23], v[162:165], v[206:209], v[20:23]
	v_mfma_f32_16x16x32_bf16 v[8:11], v[170:173], v[206:209], v[8:11]
	v_mfma_f32_16x16x32_bf16 v[4:7], v[162:165], v[218:221], v[4:7]
	v_mfma_f32_16x16x32_bf16 v[0:3], v[170:173], v[218:221], v[0:3]
	s_setprio 0
	s_barrier
	s_add_i32 s58, s58, 2
	s_add_u32 vcc_lo, vcc_lo, 0x100
	s_addc_u32 vcc_hi, vcc_hi, 0
	s_add_u32 s54, s54, 0x100
	s_addc_u32 s55, s55, 0
	s_cmp_gt_u32 s58, 13
	s_cbranch_scc0 .LBB0_1063
	s_and_b64 vcc, exec, s[44:45]
	s_cbranch_vccz .LBB0_1066
	s_barrier

; #define PG8_STAGE(bufoff, gbase, voff) do { _Pragma("unroll") for (int _i = 0; _i < 2; ++_i) \
;         __builtin_amdgcn_global_load_lds((const unsigned*)((const char*)(gbase) + (voff)[_i]), (LAS unsigned*)(lds + (bufoff) + ldsw + _i * 8192), 16, 0, 0); } while (0)
; #define PG8_LDA(dst, b, h) do { _Pragma("unroll") for (int m = 0; m < 4; ++m) _Pragma("unroll") for (int k = 0; k < 2; ++k) dst[m][k] = *(const LAS bf16x8*)(lds + PG8_SA(b, h) + aoff + m * 2048 + k * 1024); } while (0)
; #define PG8_LDB(dst, b, h) do { _Pragma("unroll") for (int n = 0; n < 2; ++n) _Pragma("unroll") for (int k = 0; k < 2; ++k) dst[n][k] = *(const LAS bf16x8*)(lds + PG8_SB(b, h) + boff + n * 2048 + k * 1024); } while (0)
; #define PG8_WAIT_V(n) asm volatile("s_waitcnt vmcnt(" #n ")" ::: "memory")
; template <class Epi, class Sched, bool ALIGN_EPI = true, bool SP2 = true>
; __device__ __forceinline__ void gemm_phase(LAS unsigned char* lds, const Gemm g, const Sched& S, const Epi& E) {
;     ...
;         for (int t = 0; t < nt; t += 2) {
;             const bool last = (t == nt - 2);
;             const char* a1 = cA + (size_t)(t + 1) * kstep;
;             const char* a2 = last ? nA : cA + (size_t)(t + 2) * kstep; const char* b2 = last ? nB : cB + (size_t)(t + 2) * kstep;
;             const char* a3 = a2 + kstep; const char* b3 = b2 + kstep;
;             PG8_LDB(B0, 0, 0); PG8_LDB(B1, 0, 1); PG8_SCHED; PG8_LDA(At, 0, 0); PG8_STAGE(PG8_SA(1, 1), a1 + hstepA, voffA);
;             PG8_WAIT_V(8); PG8_WAIT_L(0); PG8_BAR; PG8_MMA(0, 0, At, B0); PG8_MMA(0, 1, At, B1); PG8_BAR; PG8_SCHED;
;             PG8_LDA(At, 0, 1); PG8_STAGE(PG8_SB(0, 0), b2, voffB); PG8_STAGE(PG8_SB(0, 1), b2 + hstepB, voffB); PG8_STAGE(PG8_SA(0, 0), a2, voffA);
;             PG8_WAIT_V(8); PG8_WAIT_L(0); PG8_BAR; PG8_MMA(1, 0, At, B0); PG8_MMA(1, 1, At, B1); PG8_BAR; PG8_SCHED;
;             PG8_LDB(B0, 1, 0); PG8_LDB(B1, 1, 1); PG8_SCHED; PG8_LDA(At, 1, 0); PG8_STAGE(PG8_SA(0, 1), a2 + hstepA, voffA);
;             PG8_WAIT_V(8); PG8_WAIT_L(0); PG8_BAR; PG8_MMA(0, 0, At, B0); PG8_MMA(0, 1, At, B1); PG8_BAR; PG8_SCHED;
;             PG8_LDA(At, 1, 1); PG8_STAGE(PG8_SB(1, 0), b3, voffB); PG8_STAGE(PG8_SB(1, 1), b3 + hstepB, voffB); PG8_STAGE(PG8_SA(1, 0), a3, voffA);
;             PG8_WAIT_V(8); PG8_WAIT_L(0); PG8_BAR; PG8_MMA(1, 0, At, B0); PG8_MMA(1, 1, At, B1); PG8_BAR; PG8_SCHED;
.LBB0_1229:
	s_add_u32 s18, s16, 0x100
	s_addc_u32 s19, s17, 0
	s_add_i32 s57, 0, 0x10000
	s_cmp_eq_u32 s56, 40
	s_cselect_b32 s23, s43, s19
	s_cselect_b32 s22, s42, s18
	v_add_u32_e32 v140, s57, v142
	s_cselect_b32 s21, s45, s30
	s_cselect_b32 s20, s44, s2
	s_add_i32 s58, 0, 0x14000
	ds_read_b128 v[144:147], v140
	ds_read_b128 v[148:151], v140 offset:1024
	ds_read_b128 v[152:155], v140 offset:2048
	ds_read_b128 v[156:159], v140 offset:3072
	v_add_u32_e32 v140, s58, v142
	ds_read_b128 v[160:163], v140
	ds_read_b128 v[164:167], v140 offset:1024
	ds_read_b128 v[168:171], v140 offset:2048
	ds_read_b128 v[172:175], v140 offset:3072
	v_lshl_add_u64 v[140:141], s[16:17], 0, v[136:137]
	s_add_i32 m0, s46, 0xc000
	ds_read_b128 v[186:189], v143
	ds_read_b128 v[190:193], v143 offset:1024
	ds_read_b128 v[198:201], v143 offset:2048
	ds_read_b128 v[202:205], v143 offset:3072
	ds_read_b128 v[206:209], v143 offset:4096
	ds_read_b128 v[210:213], v143 offset:5120
	ds_read_b128 v[218:221], v143 offset:6144
	ds_read_b128 v[222:225], v143 offset:7168
	global_load_lds_dwordx4 v[140:141], off
	v_lshl_add_u64 v[140:141], s[16:17], 0, v[138:139]
	s_add_i32 m0, s46, 0xe000
	s_nop 0
	global_load_lds_dwordx4 v[140:141], off
	s_waitcnt vmcnt(8)
	s_waitcnt lgkmcnt(0)
	s_barrier
	s_setprio 1
	s_waitcnt lgkmcnt(0)
	v_mfma_f32_16x16x32_bf16 v[128:131], v[144:147], v[186:189], v[128:131]
	v_mfma_f32_16x16x32_bf16 v[124:127], v[152:155], v[186:189], v[124:127]
	v_mfma_f32_16x16x32_bf16 v[120:123], v[144:147], v[198:201], v[120:123]
	v_mfma_f32_16x16x32_bf16 v[112:115], v[152:155], v[198:201], v[112:115]
	v_mfma_f32_16x16x32_bf16 v[104:107], v[144:147], v[206:209], v[104:107]
	v_mfma_f32_16x16x32_bf16 v[96:99], v[152:155], v[206:209], v[96:99]
	v_mfma_f32_16x16x32_bf16 v[88:91], v[144:147], v[218:221], v[88:91]
	v_mfma_f32_16x16x32_bf16 v[80:83], v[152:155], v[218:221], v[80:83]
	v_mfma_f32_16x16x32_bf16 v[128:131], v[148:151], v[190:193], v[128:131]
	v_mfma_f32_16x16x32_bf16 v[124:127], v[156:159], v[190:193], v[124:127]
	v_mfma_f32_16x16x32_bf16 v[120:123], v[148:151], v[202:205], v[120:123]
	v_mfma_f32_16x16x32_bf16 v[112:115], v[156:159], v[202:205], v[112:115]
	v_mfma_f32_16x16x32_bf16 v[104:107], v[148:151], v[210:213], v[104:107]
	v_mfma_f32_16x16x32_bf16 v[96:99], v[156:159], v[210:213], v[96:99]
	v_mfma_f32_16x16x32_bf16 v[88:91], v[148:151], v[222:225], v[88:91]
	v_mfma_f32_16x16x32_bf16 v[80:83], v[156:159], v[222:225], v[80:83]
	v_mfma_f32_16x16x32_bf16 v[116:119], v[160:163], v[186:189], v[116:119]
	v_mfma_f32_16x16x32_bf16 v[108:111], v[168:171], v[186:189], v[108:111]
	v_mfma_f32_16x16x32_bf16 v[100:103], v[160:163], v[198:201], v[100:103]
	v_mfma_f32_16x16x32_bf16 v[92:95], v[168:171], v[198:201], v[92:95]
	v_mfma_f32_16x16x32_bf16 v[84:87], v[160:163], v[206:209], v[84:87]
	v_mfma_f32_16x16x32_bf16 v[76:79], v[168:171], v[206:209], v[76:79]
	v_mfma_f32_16x16x32_bf16 v[72:75], v[160:163], v[218:221], v[72:75]
	v_mfma_f32_16x16x32_bf16 v[68:71], v[168:171], v[218:221], v[68:71]
	v_mfma_f32_16x16x32_bf16 v[116:119], v[164:167], v[190:193], v[116:119]
	v_mfma_f32_16x16x32_bf16 v[108:111], v[172:175], v[190:193], v[108:111]
	v_mfma_f32_16x16x32_bf16 v[100:103], v[164:167], v[202:205], v[100:103]
	v_mfma_f32_16x16x32_bf16 v[92:95], v[172:175], v[202:205], v[92:95]
	v_mfma_f32_16x16x32_bf16 v[84:87], v[164:167], v[210:213], v[84:87]
	v_mfma_f32_16x16x32_bf16 v[76:79], v[172:175], v[210:213], v[76:79]
	v_mfma_f32_16x16x32_bf16 v[72:75], v[164:167], v[222:225], v[72:75]
	v_mfma_f32_16x16x32_bf16 v[68:71], v[172:175], v[222:225], v[68:71]
	s_setprio 0
	s_barrier
	s_add_i32 s16, s57, s38
	v_lshl_add_u64 v[140:141], s[20:21], 0, v[18:19]
	s_mov_b32 m0, s16
	ds_read_b128 v[186:189], v143 offset:16384
	ds_read_b128 v[190:193], v143 offset:17408
	ds_read_b128 v[198:201], v143 offset:18432
	ds_read_b128 v[202:205], v143 offset:19456
	ds_read_b128 v[206:209], v143 offset:20480
	ds_read_b128 v[210:213], v143 offset:21504
	ds_read_b128 v[218:221], v143 offset:22528
	ds_read_b128 v[222:225], v143 offset:23552
	global_load_lds_dwordx4 v[140:141], off
	s_add_i32 m0, s16, 0x2000
	s_add_u32 s16, s20, 0xb0000
	v_lshl_add_u64 v[176:177], s[20:21], 0, v[16:17]
	s_addc_u32 s17, s21, 0
	s_add_i32 s57, s58, s38
	global_load_lds_dwordx4 v[176:177], off
	v_lshl_add_u64 v[178:179], s[16:17], 0, v[18:19]
	s_mov_b32 m0, s57
	v_lshl_add_u64 v[182:183], s[22:23], 0, v[132:133]
	global_load_lds_dwordx4 v[178:179], off
	v_lshl_add_u64 v[178:179], s[16:17], 0, v[16:17]
	s_add_i32 m0, s57, 0x2000
	s_nop 0
	global_load_lds_dwordx4 v[178:179], off
	v_lshl_add_u64 v[178:179], s[22:23], 0, v[134:135]
	s_mov_b32 m0, s46
	s_nop 0
	global_load_lds_dwordx4 v[178:179], off
	s_mov_b32 m0, s47
	s_nop 0
	global_load_lds_dwordx4 v[182:183], off
	s_waitcnt vmcnt(8)
	s_waitcnt lgkmcnt(0)
	s_barrier
; #define PG8_STAGE(bufoff, gbase, voff) do { _Pragma("unroll") for (int _i = 0; _i < 2; ++_i) \
;         __builtin_amdgcn_global_load_lds((const unsigned*)((const char*)(gbase) + (voff)[_i]), (LAS unsigned*)(lds + (bufoff) + ldsw + _i * 8192), 16, 0, 0); } while (0)
; #define PG8_LDA(dst, b, h) do { _Pragma("unroll") for (int m = 0; m < 4; ++m) _Pragma("unroll") for (int k = 0; k < 2; ++k) dst[m][k] = *(const LAS bf16x8*)(lds + PG8_SA(b, h) + aoff + m * 2048 + k * 1024); } while (0)
; #define PG8_LDB(dst, b, h) do { _Pragma("unroll") for (int n = 0; n < 2; ++n) _Pragma("unroll") for (int k = 0; k < 2; ++k) dst[n][k] = *(const LAS bf16x8*)(lds + PG8_SB(b, h) + boff + n * 2048 + k * 1024); } while (0)
; #define PG8_MMA(ai, bj, At, Bt) do { __builtin_amdgcn_s_setprio(1); _Pragma("unroll") for (int m = 0; m < 4; ++m) _Pragma("unroll") for (int n = 0; n < 2; ++n) _Pragma("unroll") for (int k = 0; k < 2; ++k) \
;         acc[ai][bj][m][n] = __builtin_amdgcn_mfma_f32_16x16x32_bf16(Bt[n][k], At[m][k], acc[ai][bj][m][n], 0, 0, 0); __builtin_amdgcn_s_setprio(0); } while (0)
; #define PG8_WAIT_V(n) asm volatile("s_waitcnt vmcnt(" #n ")" ::: "memory")
; template <class Epi, class Sched, bool ALIGN_EPI = true, bool SP2 = true>
; __device__ __forceinline__ void gemm_phase(LAS unsigned char* lds, const Gemm g, const Sched& S, const Epi& E) {
;     ...
;             PG8_LDB(B0, 0, 0); PG8_LDB(B1, 0, 1); PG8_SCHED; PG8_LDA(At, 0, 0); PG8_STAGE(PG8_SA(1, 1), a1 + hstepA, voffA);
;             PG8_WAIT_V(8); PG8_WAIT_L(0); PG8_BAR; PG8_MMA(0, 0, At, B0); PG8_MMA(0, 1, At, B1); PG8_BAR; PG8_SCHED;
;             PG8_LDA(At, 0, 1); PG8_STAGE(PG8_SB(0, 0), b2, voffB); PG8_STAGE(PG8_SB(0, 1), b2 + hstepB, voffB); PG8_STAGE(PG8_SA(0, 0), a2, voffA);
;             PG8_WAIT_V(8); PG8_WAIT_L(0); PG8_BAR; PG8_MMA(1, 0, At, B0); PG8_MMA(1, 1, At, B1); PG8_BAR; PG8_SCHED;
;             PG8_LDB(B0, 1, 0); PG8_LDB(B1, 1, 1); PG8_SCHED; PG8_LDA(At, 1, 0); PG8_STAGE(PG8_SA(0, 1), a2 + hstepA, voffA);
;             PG8_WAIT_V(8); PG8_WAIT_L(0); PG8_BAR; PG8_MMA(0, 0, At, B0); PG8_MMA(0, 1, At, B1); PG8_BAR; PG8_SCHED;
;             PG8_LDA(At, 1, 1); PG8_STAGE(PG8_SB(1, 0), b3, voffB); PG8_STAGE(PG8_SB(1, 1), b3 + hstepB, voffB); PG8_STAGE(PG8_SA(1, 0), a3, voffA);
;             PG8_WAIT_V(8); PG8_WAIT_L(0); PG8_BAR; PG8_MMA(1, 0, At, B0); PG8_MMA(1, 1, At, B1); PG8_BAR; PG8_SCHED;
	s_setprio 1
	s_waitcnt lgkmcnt(0)
	v_mfma_f32_16x16x32_bf16 v[64:67], v[144:147], v[186:189], v[64:67]
	v_mfma_f32_16x16x32_bf16 v[60:63], v[152:155], v[186:189], v[60:63]
	v_mfma_f32_16x16x32_bf16 v[56:59], v[144:147], v[198:201], v[56:59]
	v_mfma_f32_16x16x32_bf16 v[48:51], v[152:155], v[198:201], v[48:51]
	v_mfma_f32_16x16x32_bf16 v[40:43], v[144:147], v[206:209], v[40:43]
	v_mfma_f32_16x16x32_bf16 v[32:35], v[152:155], v[206:209], v[32:35]
	v_mfma_f32_16x16x32_bf16 v[24:27], v[144:147], v[218:221], v[24:27]
	v_mfma_f32_16x16x32_bf16 v[12:15], v[152:155], v[218:221], v[12:15]
	v_mfma_f32_16x16x32_bf16 v[64:67], v[148:151], v[190:193], v[64:67]
	v_mfma_f32_16x16x32_bf16 v[60:63], v[156:159], v[190:193], v[60:63]
	v_mfma_f32_16x16x32_bf16 v[56:59], v[148:151], v[202:205], v[56:59]
	v_mfma_f32_16x16x32_bf16 v[48:51], v[156:159], v[202:205], v[48:51]
	v_mfma_f32_16x16x32_bf16 v[40:43], v[148:151], v[210:213], v[40:43]
	v_mfma_f32_16x16x32_bf16 v[32:35], v[156:159], v[210:213], v[32:35]
	v_mfma_f32_16x16x32_bf16 v[24:27], v[148:151], v[222:225], v[24:27]
	v_mfma_f32_16x16x32_bf16 v[12:15], v[156:159], v[222:225], v[12:15]
	v_mfma_f32_16x16x32_bf16 v[52:55], v[160:163], v[186:189], v[52:55]
	v_mfma_f32_16x16x32_bf16 v[44:47], v[168:171], v[186:189], v[44:47]
	v_mfma_f32_16x16x32_bf16 v[36:39], v[160:163], v[198:201], v[36:39]
	v_mfma_f32_16x16x32_bf16 v[28:31], v[168:171], v[198:201], v[28:31]
	v_mfma_f32_16x16x32_bf16 v[20:23], v[160:163], v[206:209], v[20:23]
	v_mfma_f32_16x16x32_bf16 v[8:11], v[168:171], v[206:209], v[8:11]
	v_mfma_f32_16x16x32_bf16 v[4:7], v[160:163], v[218:221], v[4:7]
	v_mfma_f32_16x16x32_bf16 v[0:3], v[168:171], v[218:221], v[0:3]
	v_mfma_f32_16x16x32_bf16 v[52:55], v[164:167], v[190:193], v[52:55]
	v_mfma_f32_16x16x32_bf16 v[44:47], v[172:175], v[190:193], v[44:47]
	v_mfma_f32_16x16x32_bf16 v[36:39], v[164:167], v[202:205], v[36:39]
	v_mfma_f32_16x16x32_bf16 v[28:31], v[172:175], v[202:205], v[28:31]
	v_mfma_f32_16x16x32_bf16 v[20:23], v[164:167], v[210:213], v[20:23]
	v_mfma_f32_16x16x32_bf16 v[8:11], v[172:175], v[210:213], v[8:11]
	v_mfma_f32_16x16x32_bf16 v[4:7], v[164:167], v[222:225], v[4:7]
	v_mfma_f32_16x16x32_bf16 v[0:3], v[172:175], v[222:225], v[0:3]
	s_setprio 0
	s_barrier
	s_add_i32 s57, 0, 0x18000
	s_add_i32 s58, 0, 0x1c000
	v_add_u32_e32 v156, s57, v142
	v_add_u32_e32 v172, s58, v142
	ds_read_b128 v[144:147], v156
	ds_read_b128 v[148:151], v156 offset:1024
	ds_read_b128 v[152:155], v156 offset:2048
	ds_read_b128 v[156:159], v156 offset:3072
	ds_read_b128 v[160:163], v172
	ds_read_b128 v[164:167], v172 offset:1024
	ds_read_b128 v[168:171], v172 offset:2048
	ds_read_b128 v[172:175], v172 offset:3072
	s_add_u32 s16, s22, 0xb0000
	s_addc_u32 s17, s23, 0
	s_mov_b32 m0, s50
	v_lshl_add_u64 v[214:215], s[16:17], 0, v[134:135]
	ds_read_b128 v[186:189], v143 offset:32768
	ds_read_b128 v[190:193], v143 offset:33792
	ds_read_b128 v[198:201], v143 offset:34816
	ds_read_b128 v[202:205], v143 offset:35840
	ds_read_b128 v[206:209], v143 offset:36864
	ds_read_b128 v[210:213], v143 offset:37888
	ds_read_b128 v[218:221], v143 offset:38912
	ds_read_b128 v[222:225], v143 offset:39936
	global_load_lds_dwordx4 v[214:215], off
	v_lshl_add_u64 v[214:215], s[16:17], 0, v[132:133]
	s_mov_b32 m0, s51
	s_nop 0
	global_load_lds_dwordx4 v[214:215], off
	s_waitcnt vmcnt(8)
	s_waitcnt lgkmcnt(0)
	s_barrier
	s_setprio 1
	s_waitcnt lgkmcnt(0)
	v_mfma_f32_16x16x32_bf16 v[128:131], v[144:147], v[186:189], v[128:131]
	v_mfma_f32_16x16x32_bf16 v[124:127], v[152:155], v[186:189], v[124:127]
	v_mfma_f32_16x16x32_bf16 v[120:123], v[144:147], v[198:201], v[120:123]
	v_mfma_f32_16x16x32_bf16 v[112:115], v[152:155], v[198:201], v[112:115]
	v_mfma_f32_16x16x32_bf16 v[104:107], v[144:147], v[206:209], v[104:107]
	v_mfma_f32_16x16x32_bf16 v[96:99], v[152:155], v[206:209], v[96:99]
	v_mfma_f32_16x16x32_bf16 v[88:91], v[144:147], v[218:221], v[88:91]
	v_mfma_f32_16x16x32_bf16 v[80:83], v[152:155], v[218:221], v[80:83]
	v_mfma_f32_16x16x32_bf16 v[128:131], v[148:151], v[190:193], v[128:131]
	v_mfma_f32_16x16x32_bf16 v[124:127], v[156:159], v[190:193], v[124:127]
	v_mfma_f32_16x16x32_bf16 v[120:123], v[148:151], v[202:205], v[120:123]
	v_mfma_f32_16x16x32_bf16 v[112:115], v[156:159], v[202:205], v[112:115]
	v_mfma_f32_16x16x32_bf16 v[104:107], v[148:151], v[210:213], v[104:107]
	v_mfma_f32_16x16x32_bf16 v[96:99], v[156:159], v[210:213], v[96:99]
	v_mfma_f32_16x16x32_bf16 v[88:91], v[148:151], v[222:225], v[88:91]
	v_mfma_f32_16x16x32_bf16 v[80:83], v[156:159], v[222:225], v[80:83]
	v_mfma_f32_16x16x32_bf16 v[116:119], v[160:163], v[186:189], v[116:119]
	v_mfma_f32_16x16x32_bf16 v[108:111], v[168:171], v[186:189], v[108:111]
	v_mfma_f32_16x16x32_bf16 v[100:103], v[160:163], v[198:201], v[100:103]
	v_mfma_f32_16x16x32_bf16 v[92:95], v[168:171], v[198:201], v[92:95]
	v_mfma_f32_16x16x32_bf16 v[84:87], v[160:163], v[206:209], v[84:87]
	v_mfma_f32_16x16x32_bf16 v[76:79], v[168:171], v[206:209], v[76:79]
	v_mfma_f32_16x16x32_bf16 v[72:75], v[160:163], v[218:221], v[72:75]
	v_mfma_f32_16x16x32_bf16 v[68:71], v[168:171], v[218:221], v[68:71]
	v_mfma_f32_16x16x32_bf16 v[116:119], v[164:167], v[190:193], v[116:119]
	v_mfma_f32_16x16x32_bf16 v[108:111], v[172:175], v[190:193], v[108:111]
	v_mfma_f32_16x16x32_bf16 v[100:103], v[164:167], v[202:205], v[100:103]
	v_mfma_f32_16x16x32_bf16 v[92:95], v[172:175], v[202:205], v[92:95]
	v_mfma_f32_16x16x32_bf16 v[84:87], v[164:167], v[210:213], v[84:87]
	v_mfma_f32_16x16x32_bf16 v[76:79], v[172:175], v[210:213], v[76:79]
	v_mfma_f32_16x16x32_bf16 v[72:75], v[164:167], v[222:225], v[72:75]
	v_mfma_f32_16x16x32_bf16 v[68:71], v[172:175], v[222:225], v[68:71]
	s_setprio 0
	s_barrier
; #define PG8_STAGE(bufoff, gbase, voff) do { _Pragma("unroll") for (int _i = 0; _i < 2; ++_i) \
;         __builtin_amdgcn_global_load_lds((const unsigned*)((const char*)(gbase) + (voff)[_i]), (LAS unsigned*)(lds + (bufoff) + ldsw + _i * 8192), 16, 0, 0); } while (0)
; #define PG8_LDA(dst, b, h) do { _Pragma("unroll") for (int m = 0; m < 4; ++m) _Pragma("unroll") for (int k = 0; k < 2; ++k) dst[m][k] = *(const LAS bf16x8*)(lds + PG8_SA(b, h) + aoff + m * 2048 + k * 1024); } while (0)
; #define PG8_LDB(dst, b, h) do { _Pragma("unroll") for (int n = 0; n < 2; ++n) _Pragma("unroll") for (int k = 0; k < 2; ++k) dst[n][k] = *(const LAS bf16x8*)(lds + PG8_SB(b, h) + boff + n * 2048 + k * 1024); } while (0)
; #define PG8_MMA(ai, bj, At, Bt) do { __builtin_amdgcn_s_setprio(1); _Pragma("unroll") for (int m = 0; m < 4; ++m) _Pragma("unroll") for (int n = 0; n < 2; ++n) _Pragma("unroll") for (int k = 0; k < 2; ++k) \
;         acc[ai][bj][m][n] = __builtin_amdgcn_mfma_f32_16x16x32_bf16(Bt[n][k], At[m][k], acc[ai][bj][m][n], 0, 0, 0); __builtin_amdgcn_s_setprio(0); } while (0)
; template <class Epi, class Sched, bool ALIGN_EPI = true, bool SP2 = true>
; __device__ __forceinline__ void gemm_phase(LAS unsigned char* lds, const Gemm g, const Sched& S, const Epi& E) {
;     ...
;             PG8_LDB(B0, 0, 0); PG8_LDB(B1, 0, 1); PG8_SCHED; PG8_LDA(At, 0, 0); PG8_STAGE(PG8_SA(1, 1), a1 + hstepA, voffA);
;             PG8_WAIT_V(8); PG8_WAIT_L(0); PG8_BAR; PG8_MMA(0, 0, At, B0); PG8_MMA(0, 1, At, B1); PG8_BAR; PG8_SCHED;
;             PG8_LDA(At, 0, 1); PG8_STAGE(PG8_SB(0, 0), b2, voffB); PG8_STAGE(PG8_SB(0, 1), b2 + hstepB, voffB); PG8_STAGE(PG8_SA(0, 0), a2, voffA);
;             PG8_WAIT_V(8); PG8_WAIT_L(0); PG8_BAR; PG8_MMA(1, 0, At, B0); PG8_MMA(1, 1, At, B1); PG8_BAR; PG8_SCHED;
;             PG8_LDB(B0, 1, 0); PG8_LDB(B1, 1, 1); PG8_SCHED; PG8_LDA(At, 1, 0); PG8_STAGE(PG8_SA(0, 1), a2 + hstepA, voffA);
;             PG8_WAIT_V(8); PG8_WAIT_L(0); PG8_BAR; PG8_MMA(0, 0, At, B0); PG8_MMA(0, 1, At, B1); PG8_BAR; PG8_SCHED;
;             PG8_LDA(At, 1, 1); PG8_STAGE(PG8_SB(1, 0), b3, voffB); PG8_STAGE(PG8_SB(1, 1), b3 + hstepB, voffB); PG8_STAGE(PG8_SA(1, 0), a3, voffA);
;             PG8_WAIT_V(8); PG8_WAIT_L(0); PG8_BAR; PG8_MMA(1, 0, At, B0); PG8_MMA(1, 1, At, B1); PG8_BAR; PG8_SCHED;
;         }
;         if constexpr (ALIGN_EPI) { if (wr == 0) PG8_BAR; }
	s_add_i32 s16, s57, s38
	v_lshl_add_u64 v[140:141], v[140:141], 0, s[14:15]
	s_mov_b32 m0, s16
	ds_read_b128 v[186:189], v143 offset:49152
	ds_read_b128 v[190:193], v143 offset:50176
	ds_read_b128 v[198:201], v143 offset:51200
	ds_read_b128 v[202:205], v143 offset:52224
	ds_read_b128 v[206:209], v143 offset:53248
	ds_read_b128 v[210:213], v143 offset:54272
	ds_read_b128 v[218:221], v143 offset:55296
	ds_read_b128 v[222:225], v143 offset:56320
	global_load_lds_dwordx4 v[140:141], off
	s_add_i32 m0, s16, 0x2000
	s_add_u32 s16, s20, 0xb0080
	v_lshl_add_u64 v[140:141], v[176:177], 0, s[14:15]
	s_addc_u32 s17, s21, 0
	s_add_i32 s20, s58, s38
	global_load_lds_dwordx4 v[140:141], off
	v_lshl_add_u64 v[140:141], s[16:17], 0, v[18:19]
	s_mov_b32 m0, s20
	s_nop 0
	global_load_lds_dwordx4 v[140:141], off
	v_lshl_add_u64 v[140:141], s[16:17], 0, v[16:17]
	s_add_i32 m0, s20, 0x2000
	s_nop 0
	global_load_lds_dwordx4 v[140:141], off
	v_lshl_add_u64 v[140:141], v[178:179], 0, s[14:15]
	s_mov_b32 m0, s8
	s_nop 0
	global_load_lds_dwordx4 v[140:141], off
	v_lshl_add_u64 v[140:141], v[182:183], 0, s[14:15]
	s_mov_b32 m0, s9
	s_nop 0
	global_load_lds_dwordx4 v[140:141], off
	s_waitcnt vmcnt(8)
	s_waitcnt lgkmcnt(0)
	s_barrier
	s_setprio 1
	s_waitcnt lgkmcnt(0)
	v_mfma_f32_16x16x32_bf16 v[64:67], v[144:147], v[186:189], v[64:67]
	v_mfma_f32_16x16x32_bf16 v[60:63], v[152:155], v[186:189], v[60:63]
	v_mfma_f32_16x16x32_bf16 v[56:59], v[144:147], v[198:201], v[56:59]
	v_mfma_f32_16x16x32_bf16 v[48:51], v[152:155], v[198:201], v[48:51]
	v_mfma_f32_16x16x32_bf16 v[40:43], v[144:147], v[206:209], v[40:43]
	v_mfma_f32_16x16x32_bf16 v[32:35], v[152:155], v[206:209], v[32:35]
	v_mfma_f32_16x16x32_bf16 v[24:27], v[144:147], v[218:221], v[24:27]
	v_mfma_f32_16x16x32_bf16 v[12:15], v[152:155], v[218:221], v[12:15]
	v_mfma_f32_16x16x32_bf16 v[64:67], v[148:151], v[190:193], v[64:67]
	v_mfma_f32_16x16x32_bf16 v[60:63], v[156:159], v[190:193], v[60:63]
	v_mfma_f32_16x16x32_bf16 v[56:59], v[148:151], v[202:205], v[56:59]
	v_mfma_f32_16x16x32_bf16 v[48:51], v[156:159], v[202:205], v[48:51]
	v_mfma_f32_16x16x32_bf16 v[40:43], v[148:151], v[210:213], v[40:43]
	v_mfma_f32_16x16x32_bf16 v[32:35], v[156:159], v[210:213], v[32:35]
	v_mfma_f32_16x16x32_bf16 v[24:27], v[148:151], v[222:225], v[24:27]
	v_mfma_f32_16x16x32_bf16 v[12:15], v[156:159], v[222:225], v[12:15]
	v_mfma_f32_16x16x32_bf16 v[52:55], v[160:163], v[186:189], v[52:55]
	v_mfma_f32_16x16x32_bf16 v[44:47], v[168:171], v[186:189], v[44:47]
	v_mfma_f32_16x16x32_bf16 v[36:39], v[160:163], v[198:201], v[36:39]
	v_mfma_f32_16x16x32_bf16 v[28:31], v[168:171], v[198:201], v[28:31]
	v_mfma_f32_16x16x32_bf16 v[20:23], v[160:163], v[206:209], v[20:23]
	v_mfma_f32_16x16x32_bf16 v[8:11], v[168:171], v[206:209], v[8:11]
	v_mfma_f32_16x16x32_bf16 v[4:7], v[160:163], v[218:221], v[4:7]
	v_mfma_f32_16x16x32_bf16 v[0:3], v[168:171], v[218:221], v[0:3]
	v_mfma_f32_16x16x32_bf16 v[52:55], v[164:167], v[190:193], v[52:55]
	v_mfma_f32_16x16x32_bf16 v[44:47], v[172:175], v[190:193], v[44:47]
	v_mfma_f32_16x16x32_bf16 v[36:39], v[164:167], v[202:205], v[36:39]
	v_mfma_f32_16x16x32_bf16 v[28:31], v[172:175], v[202:205], v[28:31]
	v_mfma_f32_16x16x32_bf16 v[20:23], v[164:167], v[210:213], v[20:23]
	v_mfma_f32_16x16x32_bf16 v[8:11], v[172:175], v[210:213], v[8:11]
	v_mfma_f32_16x16x32_bf16 v[4:7], v[164:167], v[222:225], v[4:7]
	v_mfma_f32_16x16x32_bf16 v[0:3], v[172:175], v[222:225], v[0:3]
	s_setprio 0
	s_barrier
	s_add_i32 s56, s56, 2
	s_add_u32 s2, s2, 0x100
	s_addc_u32 s30, s30, 0
	s_cmp_gt_u32 s56, 41
	s_mov_b64 s[16:17], s[18:19]
	s_cbranch_scc0 .LBB0_1229
	s_and_b64 vcc, exec, s[36:37]
	s_cbranch_vccz .LBB0_1232
	s_barrier
